# GEMM K-loops: closing barrier of each MFMA segment moved up over its last 6 MFMAs, priority raise delayed behind first 12 MFMAs (timing-only edit)
# speedup vs baseline: 1.0022x; 1.0022x over previous
; #define PG8_STAGE(bufoff, gbase, voff) do { _Pragma("unroll") for (int _i = 0; _i < 2; ++_i) \
;         __builtin_amdgcn_global_load_lds((const unsigned*)((const char*)(gbase) + (voff)[_i]), (PG8_LAS unsigned*)(lds + (bufoff) + ldsw + _i * 8192), 16, 0, 0); } while (0)
; #define PG8_LDA(dst, b, h) do { _Pragma("unroll") for (int m = 0; m < 4; ++m) _Pragma("unroll") for (int k = 0; k < 2; ++k) dst[m][k] = *(const PG8_LAS bf16x8*)(lds + PG8_SA(b, h) + aoff + m * 2048 + k * 1024); } while (0)
; #define PG8_LDB(dst, b, h) do { _Pragma("unroll") for (int n = 0; n < 2; ++n) _Pragma("unroll") for (int k = 0; k < 2; ++k) dst[n][k] = *(const PG8_LAS bf16x8*)(lds + PG8_SB(b, h) + boff + n * 2048 + k * 1024); } while (0)
; #define PG8_MMA(ai, bj, At, Bt) do { __builtin_amdgcn_s_setprio(1); _Pragma("unroll") for (int m = 0; m < 4; ++m) _Pragma("unroll") for (int n = 0; n < 2; ++n) _Pragma("unroll") for (int k = 0; k < 2; ++k) \
;         acc[ai][bj][m][n] = __builtin_amdgcn_mfma_f32_16x16x32_bf16(Bt[n][k], At[m][k], acc[ai][bj][m][n], 0, 0, 0); __builtin_amdgcn_s_setprio(0); } while (0)
; #define PG8_WAIT_V(n) asm volatile("s_waitcnt vmcnt(" #n ")" ::: "memory")
; #define PG8_BAR __builtin_amdgcn_s_barrier()
; template <class Epi, class Sched, bool ALIGN_EPI = false, bool SP2 = false>
; __device__ __forceinline__ void gemm_phase(PG8_LAS unsigned char* lds, const Gemm g, const Sched& S, const Epi& E, const int wave_id) {
;     ...
;         for (int t = 0; t < nt; t += 2) {
;             const bool last = (t == nt - 2);
;             const char* a1 = cA + (size_t)(t + 1) * kstep;
;             const char* a2 = last ? nA : cA + (size_t)(t + 2) * kstep; const char* b2 = last ? nB : cB + (size_t)(t + 2) * kstep;
;             const char* a3 = a2 + kstep; const char* b3 = b2 + kstep;
;             if (last && has_next) S.a_ready(nxt);
;             if constexpr (SP2) {
;             PG8_LDB(B0, 0, 0); PG8_LDB(B1, 0, 1); PG8_SCHED; PG8_LDA(At, 0, 0); PG8_STAGE(PG8_SA(1, 1), a1 + hstep, voffA);
;             PG8_WAIT_V(8); PG8_WAIT_L(0); PG8_BAR; PG8_MMA(0, 0, At, B0); PG8_MMA(0, 1, At, B1); PG8_BAR; PG8_SCHED;
;             PG8_LDA(At, 0, 1); PG8_STAGE(PG8_SB(0, 0), b2, voffB); PG8_STAGE(PG8_SB(0, 1), b2 + hstep, voffB); PG8_STAGE(PG8_SA(0, 0), a2, voffA);
;             PG8_WAIT_V(8); PG8_WAIT_L(0); PG8_BAR; PG8_MMA(1, 0, At, B0); PG8_MMA(1, 1, At, B1); PG8_BAR; PG8_SCHED;
.LBB0_172:
	ds_read_b128 v[148:151], v159
	ds_read_b128 v[152:155], v159 offset:1024
	ds_read_b128 v[162:165], v159 offset:2048
	ds_read_b128 v[166:169], v159 offset:3072
	ds_read_b128 v[170:173], v160
	ds_read_b128 v[174:177], v160 offset:1024
	ds_read_b128 v[178:181], v160 offset:2048
	ds_read_b128 v[182:185], v160 offset:3072
	s_add_u32 s48, s46, 0xfff80080
	s_addc_u32 s49, s47, -1
	s_cmp_eq_u32 s79, 28
	s_cselect_b32 s51, s5, s49
	s_cselect_b32 s50, s7, s48
	s_cselect_b32 s49, s37, s78
	s_cselect_b32 s48, s41, s67
	v_lshl_add_u64 v[218:219], s[46:47], 0, v[138:139]
	s_add_i32 m0, s68, 0xc000
	ds_read_b128 v[186:189], v161
	ds_read_b128 v[190:193], v161 offset:1024
	ds_read_b128 v[194:197], v161 offset:2048
	ds_read_b128 v[198:201], v161 offset:3072
	ds_read_b128 v[202:205], v161 offset:4096
	ds_read_b128 v[206:209], v161 offset:5120
	ds_read_b128 v[210:213], v161 offset:6144
	ds_read_b128 v[214:217], v161 offset:7168
	global_load_lds_dwordx4 v[218:219], off
	v_lshl_add_u64 v[218:219], s[46:47], 0, v[140:141]
	s_add_i32 m0, s68, 0xe000
	s_nop 0
	global_load_lds_dwordx4 v[218:219], off
	s_waitcnt vmcnt(8)
	s_waitcnt lgkmcnt(0)
	s_barrier
	s_waitcnt lgkmcnt(0)
	v_mfma_f32_16x16x32_bf16 v[124:127], v[148:151], v[186:189], v[124:127]
	v_mfma_f32_16x16x32_bf16 v[120:123], v[162:165], v[186:189], v[120:123]
	v_mfma_f32_16x16x32_bf16 v[108:111], v[148:151], v[194:197], v[108:111]
	v_mfma_f32_16x16x32_bf16 v[104:107], v[162:165], v[194:197], v[104:107]
	v_mfma_f32_16x16x32_bf16 v[92:95], v[148:151], v[202:205], v[92:95]
	v_mfma_f32_16x16x32_bf16 v[88:91], v[162:165], v[202:205], v[88:91]
	v_mfma_f32_16x16x32_bf16 v[76:79], v[148:151], v[210:213], v[76:79]
	v_mfma_f32_16x16x32_bf16 v[72:75], v[162:165], v[210:213], v[72:75]
	v_mfma_f32_16x16x32_bf16 v[124:127], v[152:155], v[190:193], v[124:127]
	v_mfma_f32_16x16x32_bf16 v[120:123], v[166:169], v[190:193], v[120:123]
	v_mfma_f32_16x16x32_bf16 v[108:111], v[152:155], v[198:201], v[108:111]
	v_mfma_f32_16x16x32_bf16 v[104:107], v[166:169], v[198:201], v[104:107]
	s_setprio 1
	v_mfma_f32_16x16x32_bf16 v[92:95], v[152:155], v[206:209], v[92:95]
	v_mfma_f32_16x16x32_bf16 v[88:91], v[166:169], v[206:209], v[88:91]
	v_mfma_f32_16x16x32_bf16 v[76:79], v[152:155], v[214:217], v[76:79]
	v_mfma_f32_16x16x32_bf16 v[72:75], v[166:169], v[214:217], v[72:75]
	s_setprio 0
	s_setprio 1
	v_mfma_f32_16x16x32_bf16 v[116:119], v[170:173], v[186:189], v[116:119]
	v_mfma_f32_16x16x32_bf16 v[112:115], v[178:181], v[186:189], v[112:115]
	v_mfma_f32_16x16x32_bf16 v[100:103], v[170:173], v[194:197], v[100:103]
	v_mfma_f32_16x16x32_bf16 v[96:99], v[178:181], v[194:197], v[96:99]
	v_mfma_f32_16x16x32_bf16 v[84:87], v[170:173], v[202:205], v[84:87]
	v_mfma_f32_16x16x32_bf16 v[80:83], v[178:181], v[202:205], v[80:83]
	v_mfma_f32_16x16x32_bf16 v[68:71], v[170:173], v[210:213], v[68:71]
	v_mfma_f32_16x16x32_bf16 v[64:67], v[178:181], v[210:213], v[64:67]
	v_mfma_f32_16x16x32_bf16 v[116:119], v[174:177], v[190:193], v[116:119]
	v_mfma_f32_16x16x32_bf16 v[112:115], v[182:185], v[190:193], v[112:115]
	s_barrier
	v_mfma_f32_16x16x32_bf16 v[100:103], v[174:177], v[198:201], v[100:103]
	v_mfma_f32_16x16x32_bf16 v[96:99], v[182:185], v[198:201], v[96:99]
	v_mfma_f32_16x16x32_bf16 v[84:87], v[174:177], v[206:209], v[84:87]
	v_mfma_f32_16x16x32_bf16 v[80:83], v[182:185], v[206:209], v[80:83]
	v_mfma_f32_16x16x32_bf16 v[68:71], v[174:177], v[214:217], v[68:71]
	v_mfma_f32_16x16x32_bf16 v[64:67], v[182:185], v[214:217], v[64:67]
	s_setprio 0
	s_add_i32 s80, s76, s56
	v_lshl_add_u64 v[218:219], s[48:49], 0, v[130:131]
	s_mov_b32 m0, s80
	ds_read_b128 v[186:189], v161 offset:16384
	ds_read_b128 v[190:193], v161 offset:17408
	ds_read_b128 v[194:197], v161 offset:18432
	ds_read_b128 v[198:201], v161 offset:19456
	ds_read_b128 v[202:205], v161 offset:20480
	ds_read_b128 v[206:209], v161 offset:21504
	ds_read_b128 v[210:213], v161 offset:22528
	ds_read_b128 v[214:217], v161 offset:23552
	global_load_lds_dwordx4 v[218:219], off
	s_add_i32 m0, s80, 0x2000
	s_add_u32 s80, s48, 0x80000
	v_lshl_add_u64 v[220:221], s[48:49], 0, v[134:135]
	s_addc_u32 s81, s49, 0
	s_add_i32 s82, s77, s56
	global_load_lds_dwordx4 v[220:221], off
	v_lshl_add_u64 v[222:223], s[80:81], 0, v[130:131]
	s_mov_b32 m0, s82
	v_lshl_add_u64 v[224:225], s[50:51], 0, v[132:133]
	global_load_lds_dwordx4 v[222:223], off
	v_lshl_add_u64 v[222:223], s[80:81], 0, v[134:135]
	s_add_i32 m0, s82, 0x2000
	s_nop 0
	global_load_lds_dwordx4 v[222:223], off
	v_lshl_add_u64 v[222:223], s[50:51], 0, v[128:129]
	s_mov_b32 m0, s68
	s_nop 0
	global_load_lds_dwordx4 v[222:223], off
	s_mov_b32 m0, s70
	s_nop 0
	global_load_lds_dwordx4 v[224:225], off
	s_waitcnt vmcnt(8)
	s_waitcnt lgkmcnt(0)
	s_barrier
; #define PG8_STAGE(bufoff, gbase, voff) do { _Pragma("unroll") for (int _i = 0; _i < 2; ++_i) \
;         __builtin_amdgcn_global_load_lds((const unsigned*)((const char*)(gbase) + (voff)[_i]), (PG8_LAS unsigned*)(lds + (bufoff) + ldsw + _i * 8192), 16, 0, 0); } while (0)
; #define PG8_LDA(dst, b, h) do { _Pragma("unroll") for (int m = 0; m < 4; ++m) _Pragma("unroll") for (int k = 0; k < 2; ++k) dst[m][k] = *(const PG8_LAS bf16x8*)(lds + PG8_SA(b, h) + aoff + m * 2048 + k * 1024); } while (0)
; #define PG8_LDB(dst, b, h) do { _Pragma("unroll") for (int n = 0; n < 2; ++n) _Pragma("unroll") for (int k = 0; k < 2; ++k) dst[n][k] = *(const PG8_LAS bf16x8*)(lds + PG8_SB(b, h) + boff + n * 2048 + k * 1024); } while (0)
; #define PG8_MMA(ai, bj, At, Bt) do { __builtin_amdgcn_s_setprio(1); _Pragma("unroll") for (int m = 0; m < 4; ++m) _Pragma("unroll") for (int n = 0; n < 2; ++n) _Pragma("unroll") for (int k = 0; k < 2; ++k) \
;         acc[ai][bj][m][n] = __builtin_amdgcn_mfma_f32_16x16x32_bf16(Bt[n][k], At[m][k], acc[ai][bj][m][n], 0, 0, 0); __builtin_amdgcn_s_setprio(0); } while (0)
; #define PG8_WAIT_V(n) asm volatile("s_waitcnt vmcnt(" #n ")" ::: "memory")
; #define PG8_WAIT_L(n) asm volatile("s_waitcnt lgkmcnt(" #n ")" ::: "memory")
; #define PG8_BAR __builtin_amdgcn_s_barrier()
; #define PG8_SCHED __builtin_amdgcn_sched_barrier(0)
; template <class Epi, class Sched, bool ALIGN_EPI = false, bool SP2 = false>
; __device__ __forceinline__ void gemm_phase(PG8_LAS unsigned char* lds, const Gemm g, const Sched& S, const Epi& E, const int wave_id) {
;     ...
;             PG8_WAIT_V(8); PG8_WAIT_L(0); PG8_BAR; PG8_MMA(1, 0, At, B0); PG8_MMA(1, 1, At, B1); PG8_BAR; PG8_SCHED;
;             PG8_LDB(B0, 1, 0); PG8_LDB(B1, 1, 1); PG8_SCHED; PG8_LDA(At, 1, 0); PG8_STAGE(PG8_SA(0, 1), a2 + hstep, voffA);
;             PG8_WAIT_V(8); PG8_WAIT_L(0); PG8_BAR; PG8_MMA(0, 0, At, B0); PG8_MMA(0, 1, At, B1); PG8_BAR; PG8_SCHED;
	s_waitcnt lgkmcnt(0)
	v_mfma_f32_16x16x32_bf16 v[60:63], v[148:151], v[186:189], v[60:63]
	v_mfma_f32_16x16x32_bf16 v[56:59], v[162:165], v[186:189], v[56:59]
	v_mfma_f32_16x16x32_bf16 v[44:47], v[148:151], v[194:197], v[44:47]
	v_mfma_f32_16x16x32_bf16 v[40:43], v[162:165], v[194:197], v[40:43]
	v_mfma_f32_16x16x32_bf16 v[28:31], v[148:151], v[202:205], v[28:31]
	v_mfma_f32_16x16x32_bf16 v[24:27], v[162:165], v[202:205], v[24:27]
	v_mfma_f32_16x16x32_bf16 v[12:15], v[148:151], v[210:213], v[12:15]
	v_mfma_f32_16x16x32_bf16 v[8:11], v[162:165], v[210:213], v[8:11]
	v_mfma_f32_16x16x32_bf16 v[60:63], v[152:155], v[190:193], v[60:63]
	v_mfma_f32_16x16x32_bf16 v[56:59], v[166:169], v[190:193], v[56:59]
	v_mfma_f32_16x16x32_bf16 v[44:47], v[152:155], v[198:201], v[44:47]
	v_mfma_f32_16x16x32_bf16 v[40:43], v[166:169], v[198:201], v[40:43]
	s_setprio 1
	v_mfma_f32_16x16x32_bf16 v[28:31], v[152:155], v[206:209], v[28:31]
	v_mfma_f32_16x16x32_bf16 v[24:27], v[166:169], v[206:209], v[24:27]
	v_mfma_f32_16x16x32_bf16 v[12:15], v[152:155], v[214:217], v[12:15]
	v_mfma_f32_16x16x32_bf16 v[8:11], v[166:169], v[214:217], v[8:11]
	s_setprio 0
	s_setprio 1
	v_mfma_f32_16x16x32_bf16 v[52:55], v[170:173], v[186:189], v[52:55]
	v_mfma_f32_16x16x32_bf16 v[48:51], v[178:181], v[186:189], v[48:51]
	v_mfma_f32_16x16x32_bf16 v[36:39], v[170:173], v[194:197], v[36:39]
	v_mfma_f32_16x16x32_bf16 v[32:35], v[178:181], v[194:197], v[32:35]
	v_mfma_f32_16x16x32_bf16 v[20:23], v[170:173], v[202:205], v[20:23]
	v_mfma_f32_16x16x32_bf16 v[16:19], v[178:181], v[202:205], v[16:19]
	v_mfma_f32_16x16x32_bf16 v[4:7], v[170:173], v[210:213], v[4:7]
	v_mfma_f32_16x16x32_bf16 v[0:3], v[178:181], v[210:213], v[0:3]
	v_mfma_f32_16x16x32_bf16 v[52:55], v[174:177], v[190:193], v[52:55]
	v_mfma_f32_16x16x32_bf16 v[48:51], v[182:185], v[190:193], v[48:51]
	s_barrier
	v_mfma_f32_16x16x32_bf16 v[36:39], v[174:177], v[198:201], v[36:39]
	v_mfma_f32_16x16x32_bf16 v[32:35], v[182:185], v[198:201], v[32:35]
	v_mfma_f32_16x16x32_bf16 v[20:23], v[174:177], v[206:209], v[20:23]
	v_mfma_f32_16x16x32_bf16 v[16:19], v[182:185], v[206:209], v[16:19]
	v_mfma_f32_16x16x32_bf16 v[4:7], v[174:177], v[214:217], v[4:7]
	v_mfma_f32_16x16x32_bf16 v[0:3], v[182:185], v[214:217], v[0:3]
	s_setprio 0
	s_add_i32 s80, 0, 0x18000
	v_add_u32_e32 v136, s80, v157
	s_add_i32 s81, 0, 0x1c000
	ds_read_b128 v[148:151], v136
	ds_read_b128 v[152:155], v136 offset:1024
	ds_read_b128 v[162:165], v136 offset:2048
	ds_read_b128 v[166:169], v136 offset:3072
	v_add_u32_e32 v136, s81, v157
	ds_read_b128 v[170:173], v136
	ds_read_b128 v[174:177], v136 offset:1024
	ds_read_b128 v[178:181], v136 offset:2048
	ds_read_b128 v[182:185], v136 offset:3072
	s_add_u32 s50, s50, 0x80000
	s_addc_u32 s51, s51, 0
	s_mov_b32 m0, s71
	v_lshl_add_u64 v[226:227], s[50:51], 0, v[128:129]
	ds_read_b128 v[186:189], v161 offset:32768
	ds_read_b128 v[190:193], v161 offset:33792
	ds_read_b128 v[194:197], v161 offset:34816
	ds_read_b128 v[198:201], v161 offset:35840
	ds_read_b128 v[202:205], v161 offset:36864
	ds_read_b128 v[206:209], v161 offset:37888
	ds_read_b128 v[210:213], v161 offset:38912
	ds_read_b128 v[214:217], v161 offset:39936
	global_load_lds_dwordx4 v[226:227], off
	v_lshl_add_u64 v[226:227], s[50:51], 0, v[132:133]
	s_mov_b32 m0, s72
	s_nop 0
	global_load_lds_dwordx4 v[226:227], off
	s_waitcnt vmcnt(8)
	s_waitcnt lgkmcnt(0)
	s_barrier
	s_waitcnt lgkmcnt(0)
	v_mfma_f32_16x16x32_bf16 v[124:127], v[148:151], v[186:189], v[124:127]
	v_mfma_f32_16x16x32_bf16 v[120:123], v[162:165], v[186:189], v[120:123]
	v_mfma_f32_16x16x32_bf16 v[108:111], v[148:151], v[194:197], v[108:111]
	v_mfma_f32_16x16x32_bf16 v[104:107], v[162:165], v[194:197], v[104:107]
	v_mfma_f32_16x16x32_bf16 v[92:95], v[148:151], v[202:205], v[92:95]
	v_mfma_f32_16x16x32_bf16 v[88:91], v[162:165], v[202:205], v[88:91]
	v_mfma_f32_16x16x32_bf16 v[76:79], v[148:151], v[210:213], v[76:79]
	v_mfma_f32_16x16x32_bf16 v[72:75], v[162:165], v[210:213], v[72:75]
	v_mfma_f32_16x16x32_bf16 v[124:127], v[152:155], v[190:193], v[124:127]
	v_mfma_f32_16x16x32_bf16 v[120:123], v[166:169], v[190:193], v[120:123]
	v_mfma_f32_16x16x32_bf16 v[108:111], v[152:155], v[198:201], v[108:111]
	v_mfma_f32_16x16x32_bf16 v[104:107], v[166:169], v[198:201], v[104:107]
	s_setprio 1
	v_mfma_f32_16x16x32_bf16 v[92:95], v[152:155], v[206:209], v[92:95]
	v_mfma_f32_16x16x32_bf16 v[88:91], v[166:169], v[206:209], v[88:91]
	v_mfma_f32_16x16x32_bf16 v[76:79], v[152:155], v[214:217], v[76:79]
	v_mfma_f32_16x16x32_bf16 v[72:75], v[166:169], v[214:217], v[72:75]
	s_setprio 0
	s_setprio 1
	v_mfma_f32_16x16x32_bf16 v[116:119], v[170:173], v[186:189], v[116:119]
	v_mfma_f32_16x16x32_bf16 v[112:115], v[178:181], v[186:189], v[112:115]
	v_mfma_f32_16x16x32_bf16 v[100:103], v[170:173], v[194:197], v[100:103]
	v_mfma_f32_16x16x32_bf16 v[96:99], v[178:181], v[194:197], v[96:99]
	v_mfma_f32_16x16x32_bf16 v[84:87], v[170:173], v[202:205], v[84:87]
	v_mfma_f32_16x16x32_bf16 v[80:83], v[178:181], v[202:205], v[80:83]
	v_mfma_f32_16x16x32_bf16 v[68:71], v[170:173], v[210:213], v[68:71]
	v_mfma_f32_16x16x32_bf16 v[64:67], v[178:181], v[210:213], v[64:67]
	v_mfma_f32_16x16x32_bf16 v[116:119], v[174:177], v[190:193], v[116:119]
	v_mfma_f32_16x16x32_bf16 v[112:115], v[182:185], v[190:193], v[112:115]
	s_barrier
; #define PG8_STAGE(bufoff, gbase, voff) do { _Pragma("unroll") for (int _i = 0; _i < 2; ++_i) \
;         __builtin_amdgcn_global_load_lds((const unsigned*)((const char*)(gbase) + (voff)[_i]), (PG8_LAS unsigned*)(lds + (bufoff) + ldsw + _i * 8192), 16, 0, 0); } while (0)
; #define PG8_LDA(dst, b, h) do { _Pragma("unroll") for (int m = 0; m < 4; ++m) _Pragma("unroll") for (int k = 0; k < 2; ++k) dst[m][k] = *(const PG8_LAS bf16x8*)(lds + PG8_SA(b, h) + aoff + m * 2048 + k * 1024); } while (0)
; #define PG8_MMA(ai, bj, At, Bt) do { __builtin_amdgcn_s_setprio(1); _Pragma("unroll") for (int m = 0; m < 4; ++m) _Pragma("unroll") for (int n = 0; n < 2; ++n) _Pragma("unroll") for (int k = 0; k < 2; ++k) \
;         acc[ai][bj][m][n] = __builtin_amdgcn_mfma_f32_16x16x32_bf16(Bt[n][k], At[m][k], acc[ai][bj][m][n], 0, 0, 0); __builtin_amdgcn_s_setprio(0); } while (0)
; #define PG8_WAIT_V(n) asm volatile("s_waitcnt vmcnt(" #n ")" ::: "memory")
; #define PG8_WAIT_L(n) asm volatile("s_waitcnt lgkmcnt(" #n ")" ::: "memory")
; #define PG8_BAR __builtin_amdgcn_s_barrier()
; #define PG8_SCHED __builtin_amdgcn_sched_barrier(0)
; template <class Epi, class Sched, bool ALIGN_EPI = false, bool SP2 = false>
; __device__ __forceinline__ void gemm_phase(PG8_LAS unsigned char* lds, const Gemm g, const Sched& S, const Epi& E, const int wave_id) {
;     ...
;             PG8_WAIT_V(8); PG8_WAIT_L(0); PG8_BAR; PG8_MMA(0, 0, At, B0); PG8_MMA(0, 1, At, B1); PG8_BAR; PG8_SCHED;
;             PG8_LDA(At, 1, 1); PG8_STAGE(PG8_SB(1, 0), b3, voffB); PG8_STAGE(PG8_SB(1, 1), b3 + hstep, voffB); PG8_STAGE(PG8_SA(1, 0), a3, voffA);
;             PG8_WAIT_V(8); PG8_WAIT_L(0); PG8_BAR; PG8_MMA(1, 0, At, B0); PG8_MMA(1, 1, At, B1); PG8_BAR; PG8_SCHED;
;     ...
;         }
;         if constexpr (ALIGN_EPI) { if (wr == 0) PG8_BAR; }
	v_mfma_f32_16x16x32_bf16 v[100:103], v[174:177], v[198:201], v[100:103]
	v_mfma_f32_16x16x32_bf16 v[96:99], v[182:185], v[198:201], v[96:99]
	v_mfma_f32_16x16x32_bf16 v[84:87], v[174:177], v[206:209], v[84:87]
	v_mfma_f32_16x16x32_bf16 v[80:83], v[182:185], v[206:209], v[80:83]
	v_mfma_f32_16x16x32_bf16 v[68:71], v[174:177], v[214:217], v[68:71]
	v_mfma_f32_16x16x32_bf16 v[64:67], v[182:185], v[214:217], v[64:67]
	s_setprio 0
	s_add_i32 s50, s80, s56
	v_lshl_add_u64 v[218:219], v[218:219], 0, s[16:17]
	s_mov_b32 m0, s50
	ds_read_b128 v[186:189], v161 offset:49152
	ds_read_b128 v[190:193], v161 offset:50176
	ds_read_b128 v[194:197], v161 offset:51200
	ds_read_b128 v[198:201], v161 offset:52224
	ds_read_b128 v[202:205], v161 offset:53248
	ds_read_b128 v[206:209], v161 offset:54272
	ds_read_b128 v[210:213], v161 offset:55296
	ds_read_b128 v[214:217], v161 offset:56320
	global_load_lds_dwordx4 v[218:219], off
	s_add_i32 m0, s50, 0x2000
	s_add_u32 s48, s48, 0x80080
	v_lshl_add_u64 v[218:219], v[220:221], 0, s[16:17]
	s_addc_u32 s49, s49, 0
	s_add_i32 s50, s81, s56
	global_load_lds_dwordx4 v[218:219], off
	v_lshl_add_u64 v[218:219], s[48:49], 0, v[130:131]
	s_mov_b32 m0, s50
	s_nop 0
	global_load_lds_dwordx4 v[218:219], off
	v_lshl_add_u64 v[218:219], s[48:49], 0, v[134:135]
	s_add_i32 m0, s50, 0x2000
	s_nop 0
	global_load_lds_dwordx4 v[218:219], off
	v_lshl_add_u64 v[218:219], v[222:223], 0, s[16:17]
	s_mov_b32 m0, s73
	s_nop 0
	global_load_lds_dwordx4 v[218:219], off
	v_lshl_add_u64 v[218:219], v[224:225], 0, s[16:17]
	s_mov_b32 m0, s74
	s_nop 0
	global_load_lds_dwordx4 v[218:219], off
	s_waitcnt vmcnt(8)
	s_waitcnt lgkmcnt(0)
	s_barrier
	s_waitcnt lgkmcnt(0)
	v_mfma_f32_16x16x32_bf16 v[60:63], v[148:151], v[186:189], v[60:63]
	v_mfma_f32_16x16x32_bf16 v[56:59], v[162:165], v[186:189], v[56:59]
	v_mfma_f32_16x16x32_bf16 v[44:47], v[148:151], v[194:197], v[44:47]
	v_mfma_f32_16x16x32_bf16 v[40:43], v[162:165], v[194:197], v[40:43]
	v_mfma_f32_16x16x32_bf16 v[28:31], v[148:151], v[202:205], v[28:31]
	v_mfma_f32_16x16x32_bf16 v[24:27], v[162:165], v[202:205], v[24:27]
	v_mfma_f32_16x16x32_bf16 v[12:15], v[148:151], v[210:213], v[12:15]
	v_mfma_f32_16x16x32_bf16 v[8:11], v[162:165], v[210:213], v[8:11]
	v_mfma_f32_16x16x32_bf16 v[60:63], v[152:155], v[190:193], v[60:63]
	v_mfma_f32_16x16x32_bf16 v[56:59], v[166:169], v[190:193], v[56:59]
	v_mfma_f32_16x16x32_bf16 v[44:47], v[152:155], v[198:201], v[44:47]
	v_mfma_f32_16x16x32_bf16 v[40:43], v[166:169], v[198:201], v[40:43]
	s_setprio 1
	v_mfma_f32_16x16x32_bf16 v[28:31], v[152:155], v[206:209], v[28:31]
	v_mfma_f32_16x16x32_bf16 v[24:27], v[166:169], v[206:209], v[24:27]
	v_mfma_f32_16x16x32_bf16 v[12:15], v[152:155], v[214:217], v[12:15]
	v_mfma_f32_16x16x32_bf16 v[8:11], v[166:169], v[214:217], v[8:11]
	s_setprio 0
	s_setprio 1
	v_mfma_f32_16x16x32_bf16 v[52:55], v[170:173], v[186:189], v[52:55]
	v_mfma_f32_16x16x32_bf16 v[48:51], v[178:181], v[186:189], v[48:51]
	v_mfma_f32_16x16x32_bf16 v[36:39], v[170:173], v[194:197], v[36:39]
	v_mfma_f32_16x16x32_bf16 v[32:35], v[178:181], v[194:197], v[32:35]
	v_mfma_f32_16x16x32_bf16 v[20:23], v[170:173], v[202:205], v[20:23]
	v_mfma_f32_16x16x32_bf16 v[16:19], v[178:181], v[202:205], v[16:19]
	v_mfma_f32_16x16x32_bf16 v[4:7], v[170:173], v[210:213], v[4:7]
	v_mfma_f32_16x16x32_bf16 v[0:3], v[178:181], v[210:213], v[0:3]
	v_mfma_f32_16x16x32_bf16 v[52:55], v[174:177], v[190:193], v[52:55]
	v_mfma_f32_16x16x32_bf16 v[48:51], v[182:185], v[190:193], v[48:51]
	s_barrier
	v_mfma_f32_16x16x32_bf16 v[36:39], v[174:177], v[198:201], v[36:39]
	v_mfma_f32_16x16x32_bf16 v[32:35], v[182:185], v[198:201], v[32:35]
	v_mfma_f32_16x16x32_bf16 v[20:23], v[174:177], v[206:209], v[20:23]
	v_mfma_f32_16x16x32_bf16 v[16:19], v[182:185], v[206:209], v[16:19]
	v_mfma_f32_16x16x32_bf16 v[4:7], v[174:177], v[214:217], v[4:7]
	v_mfma_f32_16x16x32_bf16 v[0:3], v[182:185], v[214:217], v[0:3]
	s_setprio 0
	s_add_i32 s79, s79, 2
	s_add_u32 s46, s46, 0x100
	s_addc_u32 s47, s47, 0
	s_add_u32 s67, s67, 0x100
	s_addc_u32 s78, s78, 0
	s_cmp_gt_u32 s79, 29
	s_cbranch_scc0 .LBB0_172
	s_and_b64 vcc, exec, s[24:25]
	s_cbranch_vccz .LBB0_175
	s_barrier

; #define PG8_STAGE(bufoff, gbase, voff) do { _Pragma("unroll") for (int _i = 0; _i < 2; ++_i) \
;         __builtin_amdgcn_global_load_lds((const unsigned*)((const char*)(gbase) + (voff)[_i]), (PG8_LAS unsigned*)(lds + (bufoff) + ldsw + _i * 8192), 16, 0, 0); } while (0)
; #define PG8_LDA(dst, b, h) do { _Pragma("unroll") for (int m = 0; m < 4; ++m) _Pragma("unroll") for (int k = 0; k < 2; ++k) dst[m][k] = *(const PG8_LAS bf16x8*)(lds + PG8_SA(b, h) + aoff + m * 2048 + k * 1024); } while (0)
; #define PG8_LDB(dst, b, h) do { _Pragma("unroll") for (int n = 0; n < 2; ++n) _Pragma("unroll") for (int k = 0; k < 2; ++k) dst[n][k] = *(const PG8_LAS bf16x8*)(lds + PG8_SB(b, h) + boff + n * 2048 + k * 1024); } while (0)
; #define PG8_MMA(ai, bj, At, Bt) do { __builtin_amdgcn_s_setprio(1); _Pragma("unroll") for (int m = 0; m < 4; ++m) _Pragma("unroll") for (int n = 0; n < 2; ++n) _Pragma("unroll") for (int k = 0; k < 2; ++k) \
;         acc[ai][bj][m][n] = __builtin_amdgcn_mfma_f32_16x16x32_bf16(Bt[n][k], At[m][k], acc[ai][bj][m][n], 0, 0, 0); __builtin_amdgcn_s_setprio(0); } while (0)
; #define PG8_WAIT_V(n) asm volatile("s_waitcnt vmcnt(" #n ")" ::: "memory")
; #define PG8_BAR __builtin_amdgcn_s_barrier()
; template <class Epi, class Sched, bool ALIGN_EPI = false, bool SP2 = false>
; __device__ __forceinline__ void gemm_phase(PG8_LAS unsigned char* lds, const Gemm g, const Sched& S, const Epi& E, const int wave_id) {
;     ...
;         for (int t = 0; t < nt; t += 2) {
;             const bool last = (t == nt - 2);
;             const char* a1 = cA + (size_t)(t + 1) * kstep;
;             const char* a2 = last ? nA : cA + (size_t)(t + 2) * kstep; const char* b2 = last ? nB : cB + (size_t)(t + 2) * kstep;
;             const char* a3 = a2 + kstep; const char* b3 = b2 + kstep;
;             if (last && has_next) S.a_ready(nxt);
;             if constexpr (SP2) {
;             PG8_LDB(B0, 0, 0); PG8_LDB(B1, 0, 1); PG8_SCHED; PG8_LDA(At, 0, 0); PG8_STAGE(PG8_SA(1, 1), a1 + hstep, voffA);
;             PG8_WAIT_V(8); PG8_WAIT_L(0); PG8_BAR; PG8_MMA(0, 0, At, B0); PG8_MMA(0, 1, At, B1); PG8_BAR; PG8_SCHED;
;             PG8_LDA(At, 0, 1); PG8_STAGE(PG8_SB(0, 0), b2, voffB); PG8_STAGE(PG8_SB(0, 1), b2 + hstep, voffB); PG8_STAGE(PG8_SA(0, 0), a2, voffA);
;             PG8_WAIT_V(8); PG8_WAIT_L(0); PG8_BAR; PG8_MMA(1, 0, At, B0); PG8_MMA(1, 1, At, B1); PG8_BAR; PG8_SCHED;
.LBB0_450:
	ds_read_b128 v[132:135], v193
	ds_read_b128 v[136:139], v193 offset:1024
	ds_read_b128 v[140:143], v193 offset:2048
	ds_read_b128 v[144:147], v193 offset:3072
	ds_read_b128 v[148:151], v194
	ds_read_b128 v[152:155], v194 offset:1024
	ds_read_b128 v[156:159], v194 offset:2048
	ds_read_b128 v[176:179], v194 offset:3072
	s_add_u32 s26, s22, s24
	s_addc_u32 s27, s23, s25
	s_add_u32 s26, s26, 0x100
	s_addc_u32 s27, s27, 0
	s_add_u32 s45, s40, s24
	s_addc_u32 s47, s41, s25
	s_cmpk_eq_i32 s24, 0x700
	s_cselect_b32 s37, s1, s27
	s_cselect_b32 s36, s43, s26
	s_cselect_b32 s27, s5, s47
	s_cselect_b32 s26, s4, s45
	s_mov_b32 m0, s79
	v_lshl_add_u64 v[218:219], v[112:113], 0, s[24:25]
	ds_read_b128 v[180:183], v195
	ds_read_b128 v[184:187], v195 offset:1024
	ds_read_b128 v[188:191], v195 offset:2048
	ds_read_b128 v[198:201], v195 offset:3072
	ds_read_b128 v[202:205], v195 offset:4096
	ds_read_b128 v[206:209], v195 offset:5120
	ds_read_b128 v[210:213], v195 offset:6144
	ds_read_b128 v[214:217], v195 offset:7168
	global_load_lds_dwordx4 v[218:219], off
	v_lshl_add_u64 v[218:219], v[114:115], 0, s[24:25]
	s_mov_b32 m0, s80
	s_nop 0
	global_load_lds_dwordx4 v[218:219], off
	s_waitcnt vmcnt(8)
	s_waitcnt lgkmcnt(0)
	s_barrier
	s_waitcnt lgkmcnt(0)
	v_mfma_f32_16x16x32_bf16 v[128:131], v[132:135], v[180:183], v[128:131]
	v_mfma_f32_16x16x32_bf16 v[120:123], v[140:143], v[180:183], v[120:123]
	v_mfma_f32_16x16x32_bf16 v[108:111], v[132:135], v[188:191], v[108:111]
	v_mfma_f32_16x16x32_bf16 v[100:103], v[140:143], v[188:191], v[100:103]
	v_mfma_f32_16x16x32_bf16 v[92:95], v[132:135], v[202:205], v[92:95]
	v_mfma_f32_16x16x32_bf16 v[84:87], v[140:143], v[202:205], v[84:87]
	v_mfma_f32_16x16x32_bf16 v[76:79], v[132:135], v[210:213], v[76:79]
	v_mfma_f32_16x16x32_bf16 v[68:71], v[140:143], v[210:213], v[68:71]
	v_mfma_f32_16x16x32_bf16 v[128:131], v[136:139], v[184:187], v[128:131]
	v_mfma_f32_16x16x32_bf16 v[120:123], v[144:147], v[184:187], v[120:123]
	v_mfma_f32_16x16x32_bf16 v[108:111], v[136:139], v[198:201], v[108:111]
	v_mfma_f32_16x16x32_bf16 v[100:103], v[144:147], v[198:201], v[100:103]
	s_setprio 1
	v_mfma_f32_16x16x32_bf16 v[92:95], v[136:139], v[206:209], v[92:95]
	v_mfma_f32_16x16x32_bf16 v[84:87], v[144:147], v[206:209], v[84:87]
	v_mfma_f32_16x16x32_bf16 v[76:79], v[136:139], v[214:217], v[76:79]
	v_mfma_f32_16x16x32_bf16 v[68:71], v[144:147], v[214:217], v[68:71]
	s_setprio 0
	s_setprio 1
	v_mfma_f32_16x16x32_bf16 v[124:127], v[148:151], v[180:183], v[124:127]
	v_mfma_f32_16x16x32_bf16 v[116:119], v[156:159], v[180:183], v[116:119]
	v_mfma_f32_16x16x32_bf16 v[104:107], v[148:151], v[188:191], v[104:107]
	v_mfma_f32_16x16x32_bf16 v[96:99], v[156:159], v[188:191], v[96:99]
	v_mfma_f32_16x16x32_bf16 v[88:91], v[148:151], v[202:205], v[88:91]
	v_mfma_f32_16x16x32_bf16 v[80:83], v[156:159], v[202:205], v[80:83]
	v_mfma_f32_16x16x32_bf16 v[72:75], v[148:151], v[210:213], v[72:75]
	v_mfma_f32_16x16x32_bf16 v[64:67], v[156:159], v[210:213], v[64:67]
	v_mfma_f32_16x16x32_bf16 v[124:127], v[152:155], v[184:187], v[124:127]
	v_mfma_f32_16x16x32_bf16 v[116:119], v[176:179], v[184:187], v[116:119]
	s_barrier
	v_mfma_f32_16x16x32_bf16 v[104:107], v[152:155], v[198:201], v[104:107]
	v_mfma_f32_16x16x32_bf16 v[96:99], v[176:179], v[198:201], v[96:99]
	v_mfma_f32_16x16x32_bf16 v[88:91], v[152:155], v[206:209], v[88:91]
	v_mfma_f32_16x16x32_bf16 v[80:83], v[176:179], v[206:209], v[80:83]
	v_mfma_f32_16x16x32_bf16 v[72:75], v[152:155], v[214:217], v[72:75]
	v_mfma_f32_16x16x32_bf16 v[64:67], v[176:179], v[214:217], v[64:67]
	s_setprio 0
	s_mov_b32 m0, s81
	v_lshl_add_u64 v[218:219], s[26:27], 0, v[162:163]
	s_add_u32 s50, s26, 0x40000
	ds_read_b128 v[180:183], v195 offset:16384
	ds_read_b128 v[184:187], v195 offset:17408
	ds_read_b128 v[188:191], v195 offset:18432
	ds_read_b128 v[198:201], v195 offset:19456
	ds_read_b128 v[202:205], v195 offset:20480
	ds_read_b128 v[206:209], v195 offset:21504
	ds_read_b128 v[210:213], v195 offset:22528
	ds_read_b128 v[214:217], v195 offset:23552
	global_load_lds_dwordx4 v[218:219], off
	v_lshl_add_u64 v[220:221], s[26:27], 0, v[166:167]
	s_mov_b32 m0, s82
	s_addc_u32 s51, s27, 0
	global_load_lds_dwordx4 v[220:221], off
	v_lshl_add_u64 v[222:223], s[50:51], 0, v[162:163]
	s_mov_b32 m0, s83
	v_lshl_add_u64 v[224:225], s[36:37], 0, v[164:165]
	global_load_lds_dwordx4 v[222:223], off
	v_lshl_add_u64 v[222:223], s[50:51], 0, v[166:167]
	s_mov_b32 m0, s84
	s_nop 0
	global_load_lds_dwordx4 v[222:223], off
	v_lshl_add_u64 v[222:223], s[36:37], 0, v[160:161]
	s_mov_b32 m0, s33
	s_nop 0
	global_load_lds_dwordx4 v[222:223], off
	s_mov_b32 m0, s63
	s_nop 0
	global_load_lds_dwordx4 v[224:225], off
	s_waitcnt vmcnt(8)
	s_waitcnt lgkmcnt(0)
	s_barrier
; #define PG8_STAGE(bufoff, gbase, voff) do { _Pragma("unroll") for (int _i = 0; _i < 2; ++_i) \
;         __builtin_amdgcn_global_load_lds((const unsigned*)((const char*)(gbase) + (voff)[_i]), (PG8_LAS unsigned*)(lds + (bufoff) + ldsw + _i * 8192), 16, 0, 0); } while (0)
; #define PG8_LDA(dst, b, h) do { _Pragma("unroll") for (int m = 0; m < 4; ++m) _Pragma("unroll") for (int k = 0; k < 2; ++k) dst[m][k] = *(const PG8_LAS bf16x8*)(lds + PG8_SA(b, h) + aoff + m * 2048 + k * 1024); } while (0)
; #define PG8_LDB(dst, b, h) do { _Pragma("unroll") for (int n = 0; n < 2; ++n) _Pragma("unroll") for (int k = 0; k < 2; ++k) dst[n][k] = *(const PG8_LAS bf16x8*)(lds + PG8_SB(b, h) + boff + n * 2048 + k * 1024); } while (0)
; #define PG8_MMA(ai, bj, At, Bt) do { __builtin_amdgcn_s_setprio(1); _Pragma("unroll") for (int m = 0; m < 4; ++m) _Pragma("unroll") for (int n = 0; n < 2; ++n) _Pragma("unroll") for (int k = 0; k < 2; ++k) \
;         acc[ai][bj][m][n] = __builtin_amdgcn_mfma_f32_16x16x32_bf16(Bt[n][k], At[m][k], acc[ai][bj][m][n], 0, 0, 0); __builtin_amdgcn_s_setprio(0); } while (0)
; #define PG8_WAIT_V(n) asm volatile("s_waitcnt vmcnt(" #n ")" ::: "memory")
; #define PG8_WAIT_L(n) asm volatile("s_waitcnt lgkmcnt(" #n ")" ::: "memory")
; #define PG8_BAR __builtin_amdgcn_s_barrier()
; #define PG8_SCHED __builtin_amdgcn_sched_barrier(0)
; template <class Epi, class Sched, bool ALIGN_EPI = false, bool SP2 = false>
; __device__ __forceinline__ void gemm_phase(PG8_LAS unsigned char* lds, const Gemm g, const Sched& S, const Epi& E, const int wave_id) {
;     ...
;             PG8_WAIT_V(8); PG8_WAIT_L(0); PG8_BAR; PG8_MMA(1, 0, At, B0); PG8_MMA(1, 1, At, B1); PG8_BAR; PG8_SCHED;
;             PG8_LDB(B0, 1, 0); PG8_LDB(B1, 1, 1); PG8_SCHED; PG8_LDA(At, 1, 0); PG8_STAGE(PG8_SA(0, 1), a2 + hstep, voffA);
;             PG8_WAIT_V(8); PG8_WAIT_L(0); PG8_BAR; PG8_MMA(0, 0, At, B0); PG8_MMA(0, 1, At, B1); PG8_BAR; PG8_SCHED;
	s_waitcnt lgkmcnt(0)
	v_mfma_f32_16x16x32_bf16 v[60:63], v[132:135], v[180:183], v[60:63]
	v_mfma_f32_16x16x32_bf16 v[52:55], v[140:143], v[180:183], v[52:55]
	v_mfma_f32_16x16x32_bf16 v[44:47], v[132:135], v[188:191], v[44:47]
	v_mfma_f32_16x16x32_bf16 v[36:39], v[140:143], v[188:191], v[36:39]
	v_mfma_f32_16x16x32_bf16 v[28:31], v[132:135], v[202:205], v[28:31]
	v_mfma_f32_16x16x32_bf16 v[20:23], v[140:143], v[202:205], v[20:23]
	v_mfma_f32_16x16x32_bf16 v[12:15], v[132:135], v[210:213], v[12:15]
	v_mfma_f32_16x16x32_bf16 v[4:7], v[140:143], v[210:213], v[4:7]
	v_mfma_f32_16x16x32_bf16 v[60:63], v[136:139], v[184:187], v[60:63]
	v_mfma_f32_16x16x32_bf16 v[52:55], v[144:147], v[184:187], v[52:55]
	v_mfma_f32_16x16x32_bf16 v[44:47], v[136:139], v[198:201], v[44:47]
	v_mfma_f32_16x16x32_bf16 v[36:39], v[144:147], v[198:201], v[36:39]
	s_setprio 1
	v_mfma_f32_16x16x32_bf16 v[28:31], v[136:139], v[206:209], v[28:31]
	v_mfma_f32_16x16x32_bf16 v[20:23], v[144:147], v[206:209], v[20:23]
	v_mfma_f32_16x16x32_bf16 v[12:15], v[136:139], v[214:217], v[12:15]
	v_mfma_f32_16x16x32_bf16 v[4:7], v[144:147], v[214:217], v[4:7]
	s_setprio 0
	s_setprio 1
	v_mfma_f32_16x16x32_bf16 v[56:59], v[148:151], v[180:183], v[56:59]
	v_mfma_f32_16x16x32_bf16 v[48:51], v[156:159], v[180:183], v[48:51]
	v_mfma_f32_16x16x32_bf16 v[40:43], v[148:151], v[188:191], v[40:43]
	v_mfma_f32_16x16x32_bf16 v[32:35], v[156:159], v[188:191], v[32:35]
	v_mfma_f32_16x16x32_bf16 v[24:27], v[148:151], v[202:205], v[24:27]
	v_mfma_f32_16x16x32_bf16 v[16:19], v[156:159], v[202:205], v[16:19]
	v_mfma_f32_16x16x32_bf16 v[8:11], v[148:151], v[210:213], v[8:11]
	v_mfma_f32_16x16x32_bf16 v[0:3], v[156:159], v[210:213], v[0:3]
	v_mfma_f32_16x16x32_bf16 v[56:59], v[152:155], v[184:187], v[56:59]
	v_mfma_f32_16x16x32_bf16 v[48:51], v[176:179], v[184:187], v[48:51]
	s_barrier
	v_mfma_f32_16x16x32_bf16 v[40:43], v[152:155], v[198:201], v[40:43]
	v_mfma_f32_16x16x32_bf16 v[32:35], v[176:179], v[198:201], v[32:35]
	v_mfma_f32_16x16x32_bf16 v[24:27], v[152:155], v[206:209], v[24:27]
	v_mfma_f32_16x16x32_bf16 v[16:19], v[176:179], v[206:209], v[16:19]
	v_mfma_f32_16x16x32_bf16 v[8:11], v[152:155], v[214:217], v[8:11]
	v_mfma_f32_16x16x32_bf16 v[0:3], v[176:179], v[214:217], v[0:3]
	s_setprio 0
	ds_read_b128 v[132:135], v196
	ds_read_b128 v[136:139], v196 offset:1024
	ds_read_b128 v[140:143], v196 offset:2048
	ds_read_b128 v[144:147], v196 offset:3072
	ds_read_b128 v[148:151], v197
	ds_read_b128 v[152:155], v197 offset:1024
	ds_read_b128 v[156:159], v197 offset:2048
	ds_read_b128 v[176:179], v197 offset:3072
	s_add_u32 s36, s36, 0x40000
	s_addc_u32 s37, s37, 0
	s_mov_b32 m0, s69
	v_lshl_add_u64 v[226:227], s[36:37], 0, v[160:161]
	ds_read_b128 v[180:183], v195 offset:32768
	ds_read_b128 v[184:187], v195 offset:33792
	ds_read_b128 v[188:191], v195 offset:34816
	ds_read_b128 v[198:201], v195 offset:35840
	ds_read_b128 v[202:205], v195 offset:36864
	ds_read_b128 v[206:209], v195 offset:37888
	ds_read_b128 v[210:213], v195 offset:38912
	ds_read_b128 v[214:217], v195 offset:39936
	global_load_lds_dwordx4 v[226:227], off
	v_lshl_add_u64 v[226:227], s[36:37], 0, v[164:165]
	s_mov_b32 m0, s70
	s_nop 0
	global_load_lds_dwordx4 v[226:227], off
	s_waitcnt vmcnt(8)
	s_waitcnt lgkmcnt(0)
	s_barrier
	s_waitcnt lgkmcnt(0)
	v_mfma_f32_16x16x32_bf16 v[128:131], v[132:135], v[180:183], v[128:131]
	v_mfma_f32_16x16x32_bf16 v[120:123], v[140:143], v[180:183], v[120:123]
	v_mfma_f32_16x16x32_bf16 v[108:111], v[132:135], v[188:191], v[108:111]
	v_mfma_f32_16x16x32_bf16 v[100:103], v[140:143], v[188:191], v[100:103]
	v_mfma_f32_16x16x32_bf16 v[92:95], v[132:135], v[202:205], v[92:95]
	v_mfma_f32_16x16x32_bf16 v[84:87], v[140:143], v[202:205], v[84:87]
	v_mfma_f32_16x16x32_bf16 v[76:79], v[132:135], v[210:213], v[76:79]
	v_mfma_f32_16x16x32_bf16 v[68:71], v[140:143], v[210:213], v[68:71]
	v_mfma_f32_16x16x32_bf16 v[128:131], v[136:139], v[184:187], v[128:131]
	v_mfma_f32_16x16x32_bf16 v[120:123], v[144:147], v[184:187], v[120:123]
	v_mfma_f32_16x16x32_bf16 v[108:111], v[136:139], v[198:201], v[108:111]
	v_mfma_f32_16x16x32_bf16 v[100:103], v[144:147], v[198:201], v[100:103]
	s_setprio 1
	v_mfma_f32_16x16x32_bf16 v[92:95], v[136:139], v[206:209], v[92:95]
	v_mfma_f32_16x16x32_bf16 v[84:87], v[144:147], v[206:209], v[84:87]
	v_mfma_f32_16x16x32_bf16 v[76:79], v[136:139], v[214:217], v[76:79]
	v_mfma_f32_16x16x32_bf16 v[68:71], v[144:147], v[214:217], v[68:71]
	s_setprio 0
	s_setprio 1
	v_mfma_f32_16x16x32_bf16 v[124:127], v[148:151], v[180:183], v[124:127]
	v_mfma_f32_16x16x32_bf16 v[116:119], v[156:159], v[180:183], v[116:119]
	v_mfma_f32_16x16x32_bf16 v[104:107], v[148:151], v[188:191], v[104:107]
	v_mfma_f32_16x16x32_bf16 v[96:99], v[156:159], v[188:191], v[96:99]
	v_mfma_f32_16x16x32_bf16 v[88:91], v[148:151], v[202:205], v[88:91]
	v_mfma_f32_16x16x32_bf16 v[80:83], v[156:159], v[202:205], v[80:83]
	v_mfma_f32_16x16x32_bf16 v[72:75], v[148:151], v[210:213], v[72:75]
	v_mfma_f32_16x16x32_bf16 v[64:67], v[156:159], v[210:213], v[64:67]
	v_mfma_f32_16x16x32_bf16 v[124:127], v[152:155], v[184:187], v[124:127]
	v_mfma_f32_16x16x32_bf16 v[116:119], v[176:179], v[184:187], v[116:119]
	s_barrier
; #define PG8_STAGE(bufoff, gbase, voff) do { _Pragma("unroll") for (int _i = 0; _i < 2; ++_i) \
;         __builtin_amdgcn_global_load_lds((const unsigned*)((const char*)(gbase) + (voff)[_i]), (PG8_LAS unsigned*)(lds + (bufoff) + ldsw + _i * 8192), 16, 0, 0); } while (0)
; #define PG8_LDA(dst, b, h) do { _Pragma("unroll") for (int m = 0; m < 4; ++m) _Pragma("unroll") for (int k = 0; k < 2; ++k) dst[m][k] = *(const PG8_LAS bf16x8*)(lds + PG8_SA(b, h) + aoff + m * 2048 + k * 1024); } while (0)
; #define PG8_MMA(ai, bj, At, Bt) do { __builtin_amdgcn_s_setprio(1); _Pragma("unroll") for (int m = 0; m < 4; ++m) _Pragma("unroll") for (int n = 0; n < 2; ++n) _Pragma("unroll") for (int k = 0; k < 2; ++k) \
;         acc[ai][bj][m][n] = __builtin_amdgcn_mfma_f32_16x16x32_bf16(Bt[n][k], At[m][k], acc[ai][bj][m][n], 0, 0, 0); __builtin_amdgcn_s_setprio(0); } while (0)
; #define PG8_WAIT_V(n) asm volatile("s_waitcnt vmcnt(" #n ")" ::: "memory")
; #define PG8_WAIT_L(n) asm volatile("s_waitcnt lgkmcnt(" #n ")" ::: "memory")
; #define PG8_BAR __builtin_amdgcn_s_barrier()
; #define PG8_SCHED __builtin_amdgcn_sched_barrier(0)
; template <class Epi, class Sched, bool ALIGN_EPI = false, bool SP2 = false>
; __device__ __forceinline__ void gemm_phase(PG8_LAS unsigned char* lds, const Gemm g, const Sched& S, const Epi& E, const int wave_id) {
;     ...
;             PG8_WAIT_V(8); PG8_WAIT_L(0); PG8_BAR; PG8_MMA(0, 0, At, B0); PG8_MMA(0, 1, At, B1); PG8_BAR; PG8_SCHED;
;             PG8_LDA(At, 1, 1); PG8_STAGE(PG8_SB(1, 0), b3, voffB); PG8_STAGE(PG8_SB(1, 1), b3 + hstep, voffB); PG8_STAGE(PG8_SA(1, 0), a3, voffA);
;             PG8_WAIT_V(8); PG8_WAIT_L(0); PG8_BAR; PG8_MMA(1, 0, At, B0); PG8_MMA(1, 1, At, B1); PG8_BAR; PG8_SCHED;
;     ...
;         }
;         if constexpr (ALIGN_EPI) { if (wr == 0) PG8_BAR; }
	v_mfma_f32_16x16x32_bf16 v[104:107], v[152:155], v[198:201], v[104:107]
	v_mfma_f32_16x16x32_bf16 v[96:99], v[176:179], v[198:201], v[96:99]
	v_mfma_f32_16x16x32_bf16 v[88:91], v[152:155], v[206:209], v[88:91]
	v_mfma_f32_16x16x32_bf16 v[80:83], v[176:179], v[206:209], v[80:83]
	v_mfma_f32_16x16x32_bf16 v[72:75], v[152:155], v[214:217], v[72:75]
	v_mfma_f32_16x16x32_bf16 v[64:67], v[176:179], v[214:217], v[64:67]
	s_setprio 0
	s_mov_b32 m0, s87
	v_lshl_add_u64 v[218:219], v[218:219], 0, s[18:19]
	s_add_u32 s26, s26, 0x40080
	ds_read_b128 v[180:183], v195 offset:49152
	ds_read_b128 v[184:187], v195 offset:50176
	ds_read_b128 v[188:191], v195 offset:51200
	ds_read_b128 v[198:201], v195 offset:52224
	ds_read_b128 v[202:205], v195 offset:53248
	ds_read_b128 v[206:209], v195 offset:54272
	ds_read_b128 v[210:213], v195 offset:55296
	ds_read_b128 v[214:217], v195 offset:56320
	global_load_lds_dwordx4 v[218:219], off
	v_lshl_add_u64 v[218:219], v[220:221], 0, s[18:19]
	s_mov_b32 m0, s88
	s_addc_u32 s27, s27, 0
	global_load_lds_dwordx4 v[218:219], off
	v_lshl_add_u64 v[218:219], s[26:27], 0, v[162:163]
	s_mov_b32 m0, s89
	s_nop 0
	global_load_lds_dwordx4 v[218:219], off
	v_lshl_add_u64 v[218:219], s[26:27], 0, v[166:167]
	s_mov_b32 m0, s90
	s_nop 0
	global_load_lds_dwordx4 v[218:219], off
	v_lshl_add_u64 v[218:219], v[222:223], 0, s[18:19]
	s_mov_b32 m0, s73
	s_nop 0
	global_load_lds_dwordx4 v[218:219], off
	v_lshl_add_u64 v[218:219], v[224:225], 0, s[18:19]
	s_mov_b32 m0, s74
	s_nop 0
	global_load_lds_dwordx4 v[218:219], off
	s_waitcnt vmcnt(8)
	s_waitcnt lgkmcnt(0)
	s_barrier
	s_waitcnt lgkmcnt(0)
	v_mfma_f32_16x16x32_bf16 v[60:63], v[132:135], v[180:183], v[60:63]
	v_mfma_f32_16x16x32_bf16 v[52:55], v[140:143], v[180:183], v[52:55]
	v_mfma_f32_16x16x32_bf16 v[44:47], v[132:135], v[188:191], v[44:47]
	v_mfma_f32_16x16x32_bf16 v[36:39], v[140:143], v[188:191], v[36:39]
	v_mfma_f32_16x16x32_bf16 v[28:31], v[132:135], v[202:205], v[28:31]
	v_mfma_f32_16x16x32_bf16 v[20:23], v[140:143], v[202:205], v[20:23]
	v_mfma_f32_16x16x32_bf16 v[12:15], v[132:135], v[210:213], v[12:15]
	v_mfma_f32_16x16x32_bf16 v[4:7], v[140:143], v[210:213], v[4:7]
	v_mfma_f32_16x16x32_bf16 v[60:63], v[136:139], v[184:187], v[60:63]
	v_mfma_f32_16x16x32_bf16 v[52:55], v[144:147], v[184:187], v[52:55]
	v_mfma_f32_16x16x32_bf16 v[44:47], v[136:139], v[198:201], v[44:47]
	v_mfma_f32_16x16x32_bf16 v[36:39], v[144:147], v[198:201], v[36:39]
	s_setprio 1
	v_mfma_f32_16x16x32_bf16 v[28:31], v[136:139], v[206:209], v[28:31]
	v_mfma_f32_16x16x32_bf16 v[20:23], v[144:147], v[206:209], v[20:23]
	v_mfma_f32_16x16x32_bf16 v[12:15], v[136:139], v[214:217], v[12:15]
	v_mfma_f32_16x16x32_bf16 v[4:7], v[144:147], v[214:217], v[4:7]
	s_setprio 0
	s_setprio 1
	v_mfma_f32_16x16x32_bf16 v[56:59], v[148:151], v[180:183], v[56:59]
	v_mfma_f32_16x16x32_bf16 v[48:51], v[156:159], v[180:183], v[48:51]
	v_mfma_f32_16x16x32_bf16 v[40:43], v[148:151], v[188:191], v[40:43]
	v_mfma_f32_16x16x32_bf16 v[32:35], v[156:159], v[188:191], v[32:35]
	v_mfma_f32_16x16x32_bf16 v[24:27], v[148:151], v[202:205], v[24:27]
	v_mfma_f32_16x16x32_bf16 v[16:19], v[156:159], v[202:205], v[16:19]
	v_mfma_f32_16x16x32_bf16 v[8:11], v[148:151], v[210:213], v[8:11]
	v_mfma_f32_16x16x32_bf16 v[0:3], v[156:159], v[210:213], v[0:3]
	v_mfma_f32_16x16x32_bf16 v[56:59], v[152:155], v[184:187], v[56:59]
	v_mfma_f32_16x16x32_bf16 v[48:51], v[176:179], v[184:187], v[48:51]
	s_barrier
	v_mfma_f32_16x16x32_bf16 v[40:43], v[152:155], v[198:201], v[40:43]
	v_mfma_f32_16x16x32_bf16 v[32:35], v[176:179], v[198:201], v[32:35]
	v_mfma_f32_16x16x32_bf16 v[24:27], v[152:155], v[206:209], v[24:27]
	v_mfma_f32_16x16x32_bf16 v[16:19], v[176:179], v[206:209], v[16:19]
	v_mfma_f32_16x16x32_bf16 v[8:11], v[152:155], v[214:217], v[8:11]
	v_mfma_f32_16x16x32_bf16 v[0:3], v[176:179], v[214:217], v[0:3]
	s_setprio 0
	s_add_i32 s44, s44, 2
	s_add_u32 s24, s24, 0x100
	s_addc_u32 s25, s25, 0
	s_cmp_gt_u32 s44, 13
	s_cbranch_scc0 .LBB0_450
	s_and_b64 vcc, exec, s[16:17]
	s_cbranch_vccz .LBB0_453
	s_barrier

; #define PG8_STAGE(bufoff, gbase, voff) do { _Pragma("unroll") for (int _i = 0; _i < 2; ++_i) \
;         __builtin_amdgcn_global_load_lds((const unsigned*)((const char*)(gbase) + (voff)[_i]), (PG8_LAS unsigned*)(lds + (bufoff) + ldsw + _i * 8192), 16, 0, 0); } while (0)
; #define PG8_LDA(dst, b, h) do { _Pragma("unroll") for (int m = 0; m < 4; ++m) _Pragma("unroll") for (int k = 0; k < 2; ++k) dst[m][k] = *(const PG8_LAS bf16x8*)(lds + PG8_SA(b, h) + aoff + m * 2048 + k * 1024); } while (0)
; #define PG8_LDB(dst, b, h) do { _Pragma("unroll") for (int n = 0; n < 2; ++n) _Pragma("unroll") for (int k = 0; k < 2; ++k) dst[n][k] = *(const PG8_LAS bf16x8*)(lds + PG8_SB(b, h) + boff + n * 2048 + k * 1024); } while (0)
; #define PG8_MMA(ai, bj, At, Bt) do { __builtin_amdgcn_s_setprio(1); _Pragma("unroll") for (int m = 0; m < 4; ++m) _Pragma("unroll") for (int n = 0; n < 2; ++n) _Pragma("unroll") for (int k = 0; k < 2; ++k) \
;         acc[ai][bj][m][n] = __builtin_amdgcn_mfma_f32_16x16x32_bf16(Bt[n][k], At[m][k], acc[ai][bj][m][n], 0, 0, 0); __builtin_amdgcn_s_setprio(0); } while (0)
; #define PG8_WAIT_V(n) asm volatile("s_waitcnt vmcnt(" #n ")" ::: "memory")
; #define PG8_WAIT_L(n) asm volatile("s_waitcnt lgkmcnt(" #n ")" ::: "memory")
; #define PG8_BAR __builtin_amdgcn_s_barrier()
; #define PG8_SCHED __builtin_amdgcn_sched_barrier(0)
; template <class Epi, class Sched, bool ALIGN_EPI = false, bool SP2 = false>
; __device__ __forceinline__ void gemm_phase(PG8_LAS unsigned char* lds, const Gemm g, const Sched& S, const Epi& E, const int wave_id) {
;     ...
;     const int aoff = lds_byte(wr * 64 + fr, fq * 8), boff = lds_byte(wc * 32 + fr, fq * 8);
;     ...
;         PG8_WAIT_V(2); PG8_BAR;
;         PG8_STAGE(PG8_SB(1, 0), cB + kstep, voffB); PG8_STAGE(PG8_SA(1, 0), cA + kstep, voffA); PG8_STAGE(PG8_SB(1, 1), cB + hstep + kstep, voffB);
;         PG8_WAIT_V(6); PG8_BAR;
;     ...
;             PG8_LDB(B0, 0, 0); PG8_LDB(B1, 0, 1); PG8_SCHED; PG8_LDA(At, 0, 0); PG8_STAGE(PG8_SA(1, 1), a1 + hstep, voffA);
;             PG8_WAIT_V(8); PG8_WAIT_L(0); PG8_BAR; PG8_MMA(0, 0, At, B0); PG8_MMA(0, 1, At, B1); PG8_BAR; PG8_SCHED;
.LBB0_484:
	s_mov_b64 s[0:1], 0x80
	s_mov_b32 m0, s87
	v_lshl_add_u64 v[4:5], v[28:29], 0, s[0:1]
	s_waitcnt vmcnt(2)
	s_barrier
	global_load_lds_dwordx4 v[4:5], off
	v_lshl_add_u64 v[6:7], v[30:31], 0, s[0:1]
	s_mov_b32 m0, s88
	v_lshl_add_u64 v[0:1], v[22:23], 0, s[0:1]
	global_load_lds_dwordx4 v[6:7], off
	s_mov_b32 m0, s73
	s_add_u32 s22, s18, 0x10080
	global_load_lds_dwordx4 v[0:1], off
	v_lshl_add_u64 v[2:3], v[24:25], 0, s[0:1]
	s_mov_b32 m0, s74
	s_addc_u32 s23, s19, 0
	global_load_lds_dwordx4 v[2:3], off
	v_lshl_add_u64 v[8:9], s[22:23], 0, v[32:33]
	s_mov_b32 m0, s89
	v_lshl_add_u64 v[10:11], s[22:23], 0, v[34:35]
	global_load_lds_dwordx4 v[8:9], off
	s_mov_b32 m0, s90
	v_lshrrev_b32_e32 v38, 1, v36
	global_load_lds_dwordx4 v[10:11], off
	v_and_b32_e32 v128, 24, v38
	v_and_b32_e32 v37, 15, v36
	v_lshlrev_b32_e32 v39, 1, v128
	v_lshlrev_b32_e32 v36, 2, v36
	v_or_b32_e32 v129, s57, v37
	v_lshl_or_b32 v37, v37, 6, v39
	v_and_b32_e32 v36, 32, v36
	v_lshlrev_b32_e32 v38, 6, v129
	s_movk_i32 s0, 0x3c0
	v_bitop3_b32 v70, v37, s93, v36 bitop3:0xde
	v_and_or_b32 v68, v38, s0, v39
	v_lshlrev_b32_e32 v38, 2, v129
	v_add_u32_e32 v233, s78, v70
	v_and_b32_e32 v69, 32, v38
	s_waitcnt vmcnt(6)
	s_barrier
	v_add_u32_e32 v232, s77, v70
	ds_read_b128 v[36:39], v233 offset:3072
	ds_read_b128 v[40:43], v233 offset:2048
	ds_read_b128 v[44:47], v233 offset:1024
	ds_read_b128 v[48:51], v233
	ds_read_b128 v[52:55], v232 offset:3072
	ds_read_b128 v[56:59], v232 offset:2048
	ds_read_b128 v[60:63], v232 offset:1024
	ds_read_b128 v[64:67], v232
	v_bitop3_b32 v68, v68, s64, v69 bitop3:0xde
	v_writelane_b32 v254, s93, 9
	v_add_u32_e32 v242, 0, v68
	v_add_u32_e32 v234, s85, v70
	v_add_u32_e32 v235, s86, v70
	s_add_u32 s0, s4, 0x10080
	s_addc_u32 s1, s5, 0
	s_mov_b32 m0, s79
	v_lshl_add_u64 v[100:101], s[0:1], 0, v[16:17]
	ds_read_b128 v[68:71], v242
	ds_read_b128 v[72:75], v242 offset:1024
	ds_read_b128 v[76:79], v242 offset:2048
	ds_read_b128 v[80:83], v242 offset:3072
	ds_read_b128 v[84:87], v242 offset:4096
	ds_read_b128 v[88:91], v242 offset:5120
	ds_read_b128 v[92:95], v242 offset:6144
	ds_read_b128 v[96:99], v242 offset:7168
	global_load_lds_dwordx4 v[100:101], off
	v_lshl_add_u64 v[100:101], s[0:1], 0, v[18:19]
	s_mov_b32 m0, s80
	s_nop 0
	global_load_lds_dwordx4 v[100:101], off
	s_waitcnt vmcnt(8)
	s_waitcnt lgkmcnt(0)
	s_barrier
	s_waitcnt lgkmcnt(0)
	v_mfma_f32_16x16x32_bf16 v[100:103], v[64:67], v[68:71], 0
	v_mfma_f32_16x16x32_bf16 v[104:107], v[56:59], v[68:71], 0
	v_mfma_f32_16x16x32_bf16 v[108:111], v[64:67], v[76:79], 0
	v_mfma_f32_16x16x32_bf16 v[112:115], v[56:59], v[76:79], 0
	v_mfma_f32_16x16x32_bf16 v[116:119], v[64:67], v[84:87], 0
	v_mfma_f32_16x16x32_bf16 v[120:123], v[56:59], v[84:87], 0
	v_mfma_f32_16x16x32_bf16 v[124:127], v[64:67], v[92:95], 0
	v_mfma_f32_16x16x32_bf16 v[100:103], v[60:63], v[72:75], v[100:103]
	v_mfma_f32_16x16x32_bf16 v[104:107], v[52:55], v[72:75], v[104:107]
	v_mfma_f32_16x16x32_bf16 v[108:111], v[60:63], v[80:83], v[108:111]
	v_mfma_f32_16x16x32_bf16 v[112:115], v[52:55], v[80:83], v[112:115]
	v_mfma_f32_16x16x32_bf16 v[116:119], v[60:63], v[88:91], v[116:119]
	s_setprio 1
	v_mfma_f32_16x16x32_bf16 v[120:123], v[52:55], v[88:91], v[120:123]
	v_mfma_f32_16x16x32_bf16 v[124:127], v[60:63], v[96:99], v[124:127]
	v_mfma_f32_16x16x32_bf16 v[130:133], v[56:59], v[92:95], 0
	v_mfma_f32_16x16x32_bf16 v[130:133], v[52:55], v[96:99], v[130:133]
	s_setprio 0
	s_setprio 1
	v_mfma_f32_16x16x32_bf16 v[134:137], v[48:51], v[68:71], 0
	v_mfma_f32_16x16x32_bf16 v[68:71], v[40:43], v[68:71], 0
	v_mfma_f32_16x16x32_bf16 v[134:137], v[44:47], v[72:75], v[134:137]
	v_mfma_f32_16x16x32_bf16 v[68:71], v[36:39], v[72:75], v[68:71]
	v_mfma_f32_16x16x32_bf16 v[72:75], v[48:51], v[76:79], 0
	v_mfma_f32_16x16x32_bf16 v[76:79], v[40:43], v[76:79], 0
	v_mfma_f32_16x16x32_bf16 v[72:75], v[44:47], v[80:83], v[72:75]
	v_mfma_f32_16x16x32_bf16 v[76:79], v[36:39], v[80:83], v[76:79]
	v_mfma_f32_16x16x32_bf16 v[80:83], v[48:51], v[84:87], 0
	v_mfma_f32_16x16x32_bf16 v[84:87], v[40:43], v[84:87], 0
	s_barrier
	v_mfma_f32_16x16x32_bf16 v[80:83], v[44:47], v[88:91], v[80:83]
	v_mfma_f32_16x16x32_bf16 v[84:87], v[36:39], v[88:91], v[84:87]
	v_mfma_f32_16x16x32_bf16 v[88:91], v[48:51], v[92:95], 0
	v_mfma_f32_16x16x32_bf16 v[92:95], v[40:43], v[92:95], 0
	v_mfma_f32_16x16x32_bf16 v[88:91], v[44:47], v[96:99], v[88:91]
	v_mfma_f32_16x16x32_bf16 v[92:95], v[36:39], v[96:99], v[92:95]
	s_setprio 0
	s_mov_b64 s[0:1], 0x100
	s_mov_b32 m0, s81
	v_lshl_add_u64 v[166:167], v[28:29], 0, s[0:1]
	s_add_u32 s24, s18, 0x10100
	ds_read_b128 v[96:99], v242 offset:16384
	ds_read_b128 v[138:141], v242 offset:17408
	ds_read_b128 v[142:145], v242 offset:18432
	ds_read_b128 v[146:149], v242 offset:19456
	ds_read_b128 v[150:153], v242 offset:20480
	ds_read_b128 v[154:157], v242 offset:21504
	ds_read_b128 v[158:161], v242 offset:22528
	ds_read_b128 v[162:165], v242 offset:23552
	global_load_lds_dwordx4 v[166:167], off
	v_lshl_add_u64 v[166:167], v[30:31], 0, s[0:1]
	s_mov_b32 m0, s82
	s_addc_u32 s25, s19, 0
	global_load_lds_dwordx4 v[166:167], off
	v_lshl_add_u64 v[166:167], s[24:25], 0, v[32:33]
	s_mov_b32 m0, s83
	s_nop 0
	global_load_lds_dwordx4 v[166:167], off
	v_lshl_add_u64 v[166:167], s[24:25], 0, v[34:35]
	s_mov_b32 m0, s84
	s_nop 0
	global_load_lds_dwordx4 v[166:167], off
	v_lshl_add_u64 v[166:167], v[22:23], 0, s[0:1]
	s_mov_b32 m0, s33
	s_nop 0
	global_load_lds_dwordx4 v[166:167], off
	v_lshl_add_u64 v[166:167], v[24:25], 0, s[0:1]
	s_mov_b32 m0, s63
	s_nop 0
	global_load_lds_dwordx4 v[166:167], off
	s_waitcnt vmcnt(8)
	s_waitcnt lgkmcnt(0)
	s_barrier
; #define PG8_STAGE(bufoff, gbase, voff) do { _Pragma("unroll") for (int _i = 0; _i < 2; ++_i) \
;         __builtin_amdgcn_global_load_lds((const unsigned*)((const char*)(gbase) + (voff)[_i]), (PG8_LAS unsigned*)(lds + (bufoff) + ldsw + _i * 8192), 16, 0, 0); } while (0)
; #define PG8_LDA(dst, b, h) do { _Pragma("unroll") for (int m = 0; m < 4; ++m) _Pragma("unroll") for (int k = 0; k < 2; ++k) dst[m][k] = *(const PG8_LAS bf16x8*)(lds + PG8_SA(b, h) + aoff + m * 2048 + k * 1024); } while (0)
; #define PG8_LDB(dst, b, h) do { _Pragma("unroll") for (int n = 0; n < 2; ++n) _Pragma("unroll") for (int k = 0; k < 2; ++k) dst[n][k] = *(const PG8_LAS bf16x8*)(lds + PG8_SB(b, h) + boff + n * 2048 + k * 1024); } while (0)
; #define PG8_MMA(ai, bj, At, Bt) do { __builtin_amdgcn_s_setprio(1); _Pragma("unroll") for (int m = 0; m < 4; ++m) _Pragma("unroll") for (int n = 0; n < 2; ++n) _Pragma("unroll") for (int k = 0; k < 2; ++k) \
;         acc[ai][bj][m][n] = __builtin_amdgcn_mfma_f32_16x16x32_bf16(Bt[n][k], At[m][k], acc[ai][bj][m][n], 0, 0, 0); __builtin_amdgcn_s_setprio(0); } while (0)
; #define PG8_WAIT_V(n) asm volatile("s_waitcnt vmcnt(" #n ")" ::: "memory")
; #define PG8_WAIT_L(n) asm volatile("s_waitcnt lgkmcnt(" #n ")" ::: "memory")
; #define PG8_BAR __builtin_amdgcn_s_barrier()
; #define PG8_SCHED __builtin_amdgcn_sched_barrier(0)
; template <class Epi, class Sched, bool ALIGN_EPI = false, bool SP2 = false>
; __device__ __forceinline__ void gemm_phase(PG8_LAS unsigned char* lds, const Gemm g, const Sched& S, const Epi& E, const int wave_id) {
;     ...
;             PG8_WAIT_V(8); PG8_WAIT_L(0); PG8_BAR; PG8_MMA(1, 0, At, B0); PG8_MMA(1, 1, At, B1); PG8_BAR; PG8_SCHED;
;             PG8_LDB(B0, 1, 0); PG8_LDB(B1, 1, 1); PG8_SCHED; PG8_LDA(At, 1, 0); PG8_STAGE(PG8_SA(0, 1), a2 + hstep, voffA);
;             PG8_WAIT_V(8); PG8_WAIT_L(0); PG8_BAR; PG8_MMA(0, 0, At, B0); PG8_MMA(0, 1, At, B1); PG8_BAR; PG8_SCHED;
	s_waitcnt lgkmcnt(0)
	v_mfma_f32_16x16x32_bf16 v[166:169], v[64:67], v[96:99], 0
	v_mfma_f32_16x16x32_bf16 v[170:173], v[56:59], v[96:99], 0
	v_mfma_f32_16x16x32_bf16 v[174:177], v[64:67], v[142:145], 0
	v_mfma_f32_16x16x32_bf16 v[178:181], v[56:59], v[142:145], 0
	v_mfma_f32_16x16x32_bf16 v[182:185], v[64:67], v[150:153], 0
	v_mfma_f32_16x16x32_bf16 v[186:189], v[56:59], v[150:153], 0
	v_mfma_f32_16x16x32_bf16 v[64:67], v[64:67], v[158:161], 0
	v_mfma_f32_16x16x32_bf16 v[56:59], v[56:59], v[158:161], 0
	v_mfma_f32_16x16x32_bf16 v[166:169], v[60:63], v[138:141], v[166:169]
	v_mfma_f32_16x16x32_bf16 v[170:173], v[52:55], v[138:141], v[170:173]
	v_mfma_f32_16x16x32_bf16 v[174:177], v[60:63], v[146:149], v[174:177]
	v_mfma_f32_16x16x32_bf16 v[178:181], v[52:55], v[146:149], v[178:181]
	s_setprio 1
	v_mfma_f32_16x16x32_bf16 v[182:185], v[60:63], v[154:157], v[182:185]
	v_mfma_f32_16x16x32_bf16 v[186:189], v[52:55], v[154:157], v[186:189]
	v_mfma_f32_16x16x32_bf16 v[60:63], v[60:63], v[162:165], v[64:67]
	v_mfma_f32_16x16x32_bf16 v[52:55], v[52:55], v[162:165], v[56:59]
	s_setprio 0
	s_setprio 1
	v_mfma_f32_16x16x32_bf16 v[56:59], v[48:51], v[96:99], 0
	v_mfma_f32_16x16x32_bf16 v[64:67], v[40:43], v[96:99], 0
	v_mfma_f32_16x16x32_bf16 v[56:59], v[44:47], v[138:141], v[56:59]
	v_mfma_f32_16x16x32_bf16 v[64:67], v[36:39], v[138:141], v[64:67]
	v_mfma_f32_16x16x32_bf16 v[96:99], v[48:51], v[142:145], 0
	v_mfma_f32_16x16x32_bf16 v[138:141], v[40:43], v[142:145], 0
	v_mfma_f32_16x16x32_bf16 v[96:99], v[44:47], v[146:149], v[96:99]
	v_mfma_f32_16x16x32_bf16 v[138:141], v[36:39], v[146:149], v[138:141]
	v_mfma_f32_16x16x32_bf16 v[142:145], v[48:51], v[150:153], 0
	v_mfma_f32_16x16x32_bf16 v[146:149], v[40:43], v[150:153], 0
	s_barrier
	v_mfma_f32_16x16x32_bf16 v[48:51], v[48:51], v[158:161], 0
	v_mfma_f32_16x16x32_bf16 v[40:43], v[40:43], v[158:161], 0
	v_mfma_f32_16x16x32_bf16 v[142:145], v[44:47], v[154:157], v[142:145]
	v_mfma_f32_16x16x32_bf16 v[146:149], v[36:39], v[154:157], v[146:149]
	v_mfma_f32_16x16x32_bf16 v[44:47], v[44:47], v[162:165], v[48:51]
	v_mfma_f32_16x16x32_bf16 v[36:39], v[36:39], v[162:165], v[40:43]
	s_setprio 0
	s_nop 1
	ds_read_b128 v[40:43], v234
	ds_read_b128 v[48:51], v234 offset:1024
	ds_read_b128 v[150:153], v234 offset:2048
	ds_read_b128 v[154:157], v234 offset:3072
	ds_read_b128 v[158:161], v235
	ds_read_b128 v[162:165], v235 offset:1024
	ds_read_b128 v[190:193], v235 offset:2048
	ds_read_b128 v[194:197], v235 offset:3072
	s_add_u32 s0, s4, 0x10100
	s_addc_u32 s1, s5, 0
	s_mov_b32 m0, s69
	v_lshl_add_u64 v[230:231], s[0:1], 0, v[16:17]
	ds_read_b128 v[198:201], v242 offset:32768
	ds_read_b128 v[202:205], v242 offset:33792
	ds_read_b128 v[206:209], v242 offset:34816
	ds_read_b128 v[210:213], v242 offset:35840
	ds_read_b128 v[214:217], v242 offset:36864
	ds_read_b128 v[218:221], v242 offset:37888
	ds_read_b128 v[222:225], v242 offset:38912
	ds_read_b128 v[226:229], v242 offset:39936
	global_load_lds_dwordx4 v[230:231], off
	v_lshl_add_u64 v[230:231], s[0:1], 0, v[18:19]
	s_mov_b32 m0, s70
	s_nop 0
	global_load_lds_dwordx4 v[230:231], off
	s_waitcnt vmcnt(8)
	s_waitcnt lgkmcnt(0)
	s_barrier
	s_waitcnt lgkmcnt(0)
	v_mfma_f32_16x16x32_bf16 v[100:103], v[40:43], v[198:201], v[100:103]
	v_mfma_f32_16x16x32_bf16 v[104:107], v[150:153], v[198:201], v[104:107]
	v_mfma_f32_16x16x32_bf16 v[108:111], v[40:43], v[206:209], v[108:111]
	v_mfma_f32_16x16x32_bf16 v[112:115], v[150:153], v[206:209], v[112:115]
	v_mfma_f32_16x16x32_bf16 v[116:119], v[40:43], v[214:217], v[116:119]
	v_mfma_f32_16x16x32_bf16 v[120:123], v[150:153], v[214:217], v[120:123]
	v_mfma_f32_16x16x32_bf16 v[124:127], v[40:43], v[222:225], v[124:127]
	v_mfma_f32_16x16x32_bf16 v[100:103], v[48:51], v[202:205], v[100:103]
	v_mfma_f32_16x16x32_bf16 v[104:107], v[154:157], v[202:205], v[104:107]
	v_mfma_f32_16x16x32_bf16 v[108:111], v[48:51], v[210:213], v[108:111]
	v_mfma_f32_16x16x32_bf16 v[112:115], v[154:157], v[210:213], v[112:115]
	v_mfma_f32_16x16x32_bf16 v[116:119], v[48:51], v[218:221], v[116:119]
	s_setprio 1
	v_mfma_f32_16x16x32_bf16 v[120:123], v[154:157], v[218:221], v[120:123]
	v_mfma_f32_16x16x32_bf16 v[124:127], v[48:51], v[226:229], v[124:127]
	v_mfma_f32_16x16x32_bf16 v[130:133], v[150:153], v[222:225], v[130:133]
	v_mfma_f32_16x16x32_bf16 v[130:133], v[154:157], v[226:229], v[130:133]
	s_setprio 0
	s_setprio 1
	v_mfma_f32_16x16x32_bf16 v[68:71], v[190:193], v[198:201], v[68:71]
	v_mfma_f32_16x16x32_bf16 v[72:75], v[158:161], v[206:209], v[72:75]
	v_mfma_f32_16x16x32_bf16 v[76:79], v[190:193], v[206:209], v[76:79]
	v_mfma_f32_16x16x32_bf16 v[80:83], v[158:161], v[214:217], v[80:83]
	v_mfma_f32_16x16x32_bf16 v[84:87], v[190:193], v[214:217], v[84:87]
	v_mfma_f32_16x16x32_bf16 v[88:91], v[158:161], v[222:225], v[88:91]
	v_mfma_f32_16x16x32_bf16 v[92:95], v[190:193], v[222:225], v[92:95]
	v_mfma_f32_16x16x32_bf16 v[134:137], v[158:161], v[198:201], v[134:137]
	v_mfma_f32_16x16x32_bf16 v[68:71], v[194:197], v[202:205], v[68:71]
	v_mfma_f32_16x16x32_bf16 v[72:75], v[162:165], v[210:213], v[72:75]
	s_barrier
; #define PG8_STAGE(bufoff, gbase, voff) do { _Pragma("unroll") for (int _i = 0; _i < 2; ++_i) \
;         __builtin_amdgcn_global_load_lds((const unsigned*)((const char*)(gbase) + (voff)[_i]), (PG8_LAS unsigned*)(lds + (bufoff) + ldsw + _i * 8192), 16, 0, 0); } while (0)
; #define PG8_LDA(dst, b, h) do { _Pragma("unroll") for (int m = 0; m < 4; ++m) _Pragma("unroll") for (int k = 0; k < 2; ++k) dst[m][k] = *(const PG8_LAS bf16x8*)(lds + PG8_SA(b, h) + aoff + m * 2048 + k * 1024); } while (0)
; #define PG8_LDB(dst, b, h) do { _Pragma("unroll") for (int n = 0; n < 2; ++n) _Pragma("unroll") for (int k = 0; k < 2; ++k) dst[n][k] = *(const PG8_LAS bf16x8*)(lds + PG8_SB(b, h) + boff + n * 2048 + k * 1024); } while (0)
; #define PG8_MMA(ai, bj, At, Bt) do { __builtin_amdgcn_s_setprio(1); _Pragma("unroll") for (int m = 0; m < 4; ++m) _Pragma("unroll") for (int n = 0; n < 2; ++n) _Pragma("unroll") for (int k = 0; k < 2; ++k) \
;         acc[ai][bj][m][n] = __builtin_amdgcn_mfma_f32_16x16x32_bf16(Bt[n][k], At[m][k], acc[ai][bj][m][n], 0, 0, 0); __builtin_amdgcn_s_setprio(0); } while (0)
; #define PG8_WAIT_V(n) asm volatile("s_waitcnt vmcnt(" #n ")" ::: "memory")
; #define PG8_WAIT_L(n) asm volatile("s_waitcnt lgkmcnt(" #n ")" ::: "memory")
; #define PG8_BAR __builtin_amdgcn_s_barrier()
; #define PG8_SCHED __builtin_amdgcn_sched_barrier(0)
; template <class Epi, class Sched, bool ALIGN_EPI = false, bool SP2 = false>
; __device__ __forceinline__ void gemm_phase(PG8_LAS unsigned char* lds, const Gemm g, const Sched& S, const Epi& E, const int wave_id) {
;     ...
;             PG8_LDB(B0, 0, 0); PG8_LDB(B1, 0, 1); PG8_SCHED; PG8_LDA(At, 0, 0); PG8_STAGE(PG8_SA(1, 1), a1 + hstep, voffA);
;     ...
;             PG8_WAIT_V(8); PG8_WAIT_L(0); PG8_BAR; PG8_MMA(0, 0, At, B0); PG8_MMA(0, 1, At, B1); PG8_BAR; PG8_SCHED;
;             PG8_LDA(At, 1, 1); PG8_STAGE(PG8_SB(1, 0), b3, voffB); PG8_STAGE(PG8_SB(1, 1), b3 + hstep, voffB); PG8_STAGE(PG8_SA(1, 0), a3, voffA);
;             PG8_WAIT_V(8); PG8_WAIT_L(0); PG8_BAR; PG8_MMA(1, 0, At, B0); PG8_MMA(1, 1, At, B1); PG8_BAR; PG8_SCHED;
	v_mfma_f32_16x16x32_bf16 v[76:79], v[194:197], v[210:213], v[76:79]
	v_mfma_f32_16x16x32_bf16 v[80:83], v[162:165], v[218:221], v[80:83]
	v_mfma_f32_16x16x32_bf16 v[84:87], v[194:197], v[218:221], v[84:87]
	v_mfma_f32_16x16x32_bf16 v[88:91], v[162:165], v[226:229], v[88:91]
	v_mfma_f32_16x16x32_bf16 v[92:95], v[194:197], v[226:229], v[92:95]
	v_mfma_f32_16x16x32_bf16 v[134:137], v[162:165], v[202:205], v[134:137]
	s_setprio 0
	s_mov_b64 s[0:1], 0x180
	s_mov_b32 m0, s87
	v_lshl_add_u64 v[230:231], v[28:29], 0, s[0:1]
	s_add_u32 s26, s18, 0x10180
	ds_read_b128 v[198:201], v242 offset:49152
	ds_read_b128 v[202:205], v242 offset:50176
	ds_read_b128 v[206:209], v242 offset:51200
	ds_read_b128 v[210:213], v242 offset:52224
	ds_read_b128 v[214:217], v242 offset:53248
	ds_read_b128 v[218:221], v242 offset:54272
	ds_read_b128 v[222:225], v242 offset:55296
	ds_read_b128 v[226:229], v242 offset:56320
	global_load_lds_dwordx4 v[230:231], off
	v_lshl_add_u64 v[230:231], v[30:31], 0, s[0:1]
	s_mov_b32 m0, s88
	s_addc_u32 s27, s19, 0
	global_load_lds_dwordx4 v[230:231], off
	v_lshl_add_u64 v[32:33], s[26:27], 0, v[32:33]
	s_mov_b32 m0, s89
	s_nop 0
	global_load_lds_dwordx4 v[32:33], off
	v_lshl_add_u64 v[32:33], s[26:27], 0, v[34:35]
	s_mov_b32 m0, s90
	s_nop 0
	global_load_lds_dwordx4 v[32:33], off
	v_lshl_add_u64 v[32:33], v[22:23], 0, s[0:1]
	s_mov_b32 m0, s73
	s_nop 0
	global_load_lds_dwordx4 v[32:33], off
	v_lshl_add_u64 v[32:33], v[24:25], 0, s[0:1]
	s_mov_b32 m0, s74
	s_nop 0
	global_load_lds_dwordx4 v[32:33], off
	s_waitcnt vmcnt(8)
	s_waitcnt lgkmcnt(0)
	s_barrier
	s_waitcnt lgkmcnt(0)
	v_mfma_f32_16x16x32_bf16 v[32:35], v[40:43], v[198:201], v[166:169]
	v_mfma_f32_16x16x32_bf16 v[166:169], v[150:153], v[198:201], v[170:173]
	v_mfma_f32_16x16x32_bf16 v[170:173], v[40:43], v[206:209], v[174:177]
	v_mfma_f32_16x16x32_bf16 v[174:177], v[150:153], v[206:209], v[178:181]
	v_mfma_f32_16x16x32_bf16 v[178:181], v[40:43], v[214:217], v[182:185]
	v_mfma_f32_16x16x32_bf16 v[40:43], v[40:43], v[222:225], v[60:63]
	v_mfma_f32_16x16x32_bf16 v[32:35], v[48:51], v[202:205], v[32:35]
	v_mfma_f32_16x16x32_bf16 v[170:173], v[48:51], v[210:213], v[170:173]
	v_mfma_f32_16x16x32_bf16 v[178:181], v[48:51], v[218:221], v[178:181]
	v_mfma_f32_16x16x32_bf16 v[40:43], v[48:51], v[226:229], v[40:43]
	v_mfma_f32_16x16x32_bf16 v[48:51], v[150:153], v[222:225], v[52:55]
	v_mfma_f32_16x16x32_bf16 v[182:185], v[150:153], v[214:217], v[186:189]
	s_setprio 1
	v_mfma_f32_16x16x32_bf16 v[48:51], v[154:157], v[226:229], v[48:51]
	v_mfma_f32_16x16x32_bf16 v[166:169], v[154:157], v[202:205], v[166:169]
	v_mfma_f32_16x16x32_bf16 v[174:177], v[154:157], v[210:213], v[174:177]
	v_mfma_f32_16x16x32_bf16 v[182:185], v[154:157], v[218:221], v[182:185]
	s_setprio 0
	s_setprio 1
	v_mfma_f32_16x16x32_bf16 v[52:55], v[158:161], v[198:201], v[56:59]
	v_mfma_f32_16x16x32_bf16 v[56:59], v[190:193], v[198:201], v[64:67]
	v_mfma_f32_16x16x32_bf16 v[60:63], v[158:161], v[206:209], v[96:99]
	v_mfma_f32_16x16x32_bf16 v[64:67], v[190:193], v[206:209], v[138:141]
	v_mfma_f32_16x16x32_bf16 v[96:99], v[158:161], v[214:217], v[142:145]
	v_mfma_f32_16x16x32_bf16 v[44:47], v[158:161], v[222:225], v[44:47]
	v_mfma_f32_16x16x32_bf16 v[36:39], v[190:193], v[222:225], v[36:39]
	v_mfma_f32_16x16x32_bf16 v[52:55], v[162:165], v[202:205], v[52:55]
	v_mfma_f32_16x16x32_bf16 v[56:59], v[194:197], v[202:205], v[56:59]
	v_mfma_f32_16x16x32_bf16 v[60:63], v[162:165], v[210:213], v[60:63]
	s_barrier
	v_mfma_f32_16x16x32_bf16 v[64:67], v[194:197], v[210:213], v[64:67]
	v_mfma_f32_16x16x32_bf16 v[96:99], v[162:165], v[218:221], v[96:99]
	v_mfma_f32_16x16x32_bf16 v[138:141], v[190:193], v[214:217], v[146:149]
	v_mfma_f32_16x16x32_bf16 v[44:47], v[162:165], v[226:229], v[44:47]
	v_mfma_f32_16x16x32_bf16 v[36:39], v[194:197], v[226:229], v[36:39]
	v_mfma_f32_16x16x32_bf16 v[138:141], v[194:197], v[218:221], v[138:141]
	s_setprio 0
	ds_read_b128 v[142:145], v232
	ds_read_b128 v[146:149], v232 offset:1024
	ds_read_b128 v[150:153], v232 offset:2048
	ds_read_b128 v[154:157], v232 offset:3072
	ds_read_b128 v[158:161], v233
	ds_read_b128 v[162:165], v233 offset:1024
	ds_read_b128 v[186:189], v233 offset:2048
	ds_read_b128 v[190:193], v233 offset:3072
	s_add_u32 s0, s4, 0x10180
	s_addc_u32 s1, s5, 0
	s_mov_b32 m0, s79
	v_lshl_add_u64 v[16:17], s[0:1], 0, v[16:17]
	ds_read_b128 v[194:197], v242
	ds_read_b128 v[198:201], v242 offset:1024
	ds_read_b128 v[202:205], v242 offset:2048
	ds_read_b128 v[206:209], v242 offset:3072
	ds_read_b128 v[210:213], v242 offset:4096
	ds_read_b128 v[214:217], v242 offset:5120
	ds_read_b128 v[218:221], v242 offset:6144
	ds_read_b128 v[222:225], v242 offset:7168
	global_load_lds_dwordx4 v[16:17], off
	v_lshl_add_u64 v[16:17], s[0:1], 0, v[18:19]
	s_mov_b32 m0, s80
	s_nop 0
	global_load_lds_dwordx4 v[16:17], off
	s_waitcnt vmcnt(8)
	s_waitcnt lgkmcnt(0)
	s_barrier
; #define PG8_STAGE(bufoff, gbase, voff) do { _Pragma("unroll") for (int _i = 0; _i < 2; ++_i) \
;         __builtin_amdgcn_global_load_lds((const unsigned*)((const char*)(gbase) + (voff)[_i]), (PG8_LAS unsigned*)(lds + (bufoff) + ldsw + _i * 8192), 16, 0, 0); } while (0)
; #define PG8_LDA(dst, b, h) do { _Pragma("unroll") for (int m = 0; m < 4; ++m) _Pragma("unroll") for (int k = 0; k < 2; ++k) dst[m][k] = *(const PG8_LAS bf16x8*)(lds + PG8_SA(b, h) + aoff + m * 2048 + k * 1024); } while (0)
; #define PG8_LDB(dst, b, h) do { _Pragma("unroll") for (int n = 0; n < 2; ++n) _Pragma("unroll") for (int k = 0; k < 2; ++k) dst[n][k] = *(const PG8_LAS bf16x8*)(lds + PG8_SB(b, h) + boff + n * 2048 + k * 1024); } while (0)
; #define PG8_MMA(ai, bj, At, Bt) do { __builtin_amdgcn_s_setprio(1); _Pragma("unroll") for (int m = 0; m < 4; ++m) _Pragma("unroll") for (int n = 0; n < 2; ++n) _Pragma("unroll") for (int k = 0; k < 2; ++k) \
;         acc[ai][bj][m][n] = __builtin_amdgcn_mfma_f32_16x16x32_bf16(Bt[n][k], At[m][k], acc[ai][bj][m][n], 0, 0, 0); __builtin_amdgcn_s_setprio(0); } while (0)
; #define PG8_WAIT_V(n) asm volatile("s_waitcnt vmcnt(" #n ")" ::: "memory")
; #define PG8_WAIT_L(n) asm volatile("s_waitcnt lgkmcnt(" #n ")" ::: "memory")
; #define PG8_BAR __builtin_amdgcn_s_barrier()
; #define PG8_SCHED __builtin_amdgcn_sched_barrier(0)
; template <class Epi, class Sched, bool ALIGN_EPI = false, bool SP2 = false>
; __device__ __forceinline__ void gemm_phase(PG8_LAS unsigned char* lds, const Gemm g, const Sched& S, const Epi& E, const int wave_id) {
;     ...
;             PG8_LDB(B0, 0, 0); PG8_LDB(B1, 0, 1); PG8_SCHED; PG8_LDA(At, 0, 0); PG8_STAGE(PG8_SA(1, 1), a1 + hstep, voffA);
;             PG8_WAIT_V(8); PG8_WAIT_L(0); PG8_BAR; PG8_MMA(0, 0, At, B0); PG8_MMA(0, 1, At, B1); PG8_BAR; PG8_SCHED;
;             PG8_LDA(At, 0, 1); PG8_STAGE(PG8_SB(0, 0), b2, voffB); PG8_STAGE(PG8_SB(0, 1), b2 + hstep, voffB); PG8_STAGE(PG8_SA(0, 0), a2, voffA);
;             PG8_WAIT_V(8); PG8_WAIT_L(0); PG8_BAR; PG8_MMA(1, 0, At, B0); PG8_MMA(1, 1, At, B1); PG8_BAR; PG8_SCHED;
	s_waitcnt lgkmcnt(0)
	v_mfma_f32_16x16x32_bf16 v[16:19], v[142:145], v[194:197], v[100:103]
	v_mfma_f32_16x16x32_bf16 v[100:103], v[150:153], v[194:197], v[104:107]
	v_mfma_f32_16x16x32_bf16 v[104:107], v[142:145], v[202:205], v[108:111]
	v_mfma_f32_16x16x32_bf16 v[108:111], v[150:153], v[202:205], v[112:115]
	v_mfma_f32_16x16x32_bf16 v[112:115], v[142:145], v[210:213], v[116:119]
	v_mfma_f32_16x16x32_bf16 v[116:119], v[146:149], v[214:217], v[112:115]
	v_mfma_f32_16x16x32_bf16 v[112:115], v[150:153], v[210:213], v[120:123]
	v_mfma_f32_16x16x32_bf16 v[226:229], v[154:157], v[214:217], v[112:115]
	v_mfma_f32_16x16x32_bf16 v[112:115], v[142:145], v[218:221], v[124:127]
	v_mfma_f32_16x16x32_bf16 v[16:19], v[146:149], v[198:201], v[16:19]
	v_mfma_f32_16x16x32_bf16 v[100:103], v[154:157], v[198:201], v[100:103]
	v_mfma_f32_16x16x32_bf16 v[104:107], v[146:149], v[206:209], v[104:107]
	s_setprio 1
	v_mfma_f32_16x16x32_bf16 v[108:111], v[154:157], v[206:209], v[108:111]
	v_mfma_f32_16x16x32_bf16 v[124:127], v[146:149], v[222:225], v[112:115]
	v_mfma_f32_16x16x32_bf16 v[112:115], v[150:153], v[218:221], v[130:133]
	v_mfma_f32_16x16x32_bf16 v[130:133], v[154:157], v[222:225], v[112:115]
	s_setprio 0
	s_setprio 1
	v_mfma_f32_16x16x32_bf16 v[80:83], v[158:161], v[210:213], v[80:83]
	v_mfma_f32_16x16x32_bf16 v[112:115], v[158:161], v[194:197], v[134:137]
	v_mfma_f32_16x16x32_bf16 v[68:71], v[186:189], v[194:197], v[68:71]
	v_mfma_f32_16x16x32_bf16 v[194:197], v[162:165], v[214:217], v[80:83]
	v_mfma_f32_16x16x32_bf16 v[80:83], v[186:189], v[210:213], v[84:87]
	v_mfma_f32_16x16x32_bf16 v[72:75], v[158:161], v[202:205], v[72:75]
	v_mfma_f32_16x16x32_bf16 v[76:79], v[186:189], v[202:205], v[76:79]
	v_mfma_f32_16x16x32_bf16 v[84:87], v[190:193], v[214:217], v[80:83]
	v_mfma_f32_16x16x32_bf16 v[80:83], v[158:161], v[218:221], v[88:91]
	v_mfma_f32_16x16x32_bf16 v[134:137], v[162:165], v[198:201], v[112:115]
	s_barrier
	v_mfma_f32_16x16x32_bf16 v[68:71], v[190:193], v[198:201], v[68:71]
	v_mfma_f32_16x16x32_bf16 v[72:75], v[162:165], v[206:209], v[72:75]
	v_mfma_f32_16x16x32_bf16 v[76:79], v[190:193], v[206:209], v[76:79]
	v_mfma_f32_16x16x32_bf16 v[198:201], v[162:165], v[222:225], v[80:83]
	v_mfma_f32_16x16x32_bf16 v[80:83], v[186:189], v[218:221], v[92:95]
	v_mfma_f32_16x16x32_bf16 v[202:205], v[190:193], v[222:225], v[80:83]
	s_setprio 0
	s_mov_b32 m0, s81
	s_nop 3
	ds_read_b128 v[80:83], v242 offset:16384
	ds_read_b128 v[88:91], v242 offset:17408
	ds_read_b128 v[92:95], v242 offset:18432
	ds_read_b128 v[112:115], v242 offset:19456
	ds_read_b128 v[120:123], v242 offset:20480
	ds_read_b128 v[206:209], v242 offset:21504
	ds_read_b128 v[210:213], v242 offset:22528
	ds_read_b128 v[214:217], v242 offset:23552
	global_load_lds_dwordx4 v[28:29], off
	s_mov_b32 m0, s82
	s_nop 0
	global_load_lds_dwordx4 v[30:31], off
	s_mov_b32 m0, s83
	s_nop 0
	global_load_lds_dwordx4 v[26:27], off
	s_mov_b32 m0, s84
	s_nop 0
	global_load_lds_dwordx4 v[20:21], off
	s_mov_b32 m0, s33
	s_nop 0
	global_load_lds_dwordx4 v[22:23], off
	s_mov_b32 m0, s63
	s_nop 0
	global_load_lds_dwordx4 v[24:25], off
	s_waitcnt vmcnt(8)
	s_waitcnt lgkmcnt(0)
	s_barrier
	s_waitcnt lgkmcnt(0)
	v_mfma_f32_16x16x32_bf16 v[20:23], v[142:145], v[80:83], v[32:35]
	v_mfma_f32_16x16x32_bf16 v[24:27], v[150:153], v[80:83], v[166:169]
	v_mfma_f32_16x16x32_bf16 v[28:31], v[142:145], v[92:95], v[170:173]
	v_mfma_f32_16x16x32_bf16 v[32:35], v[150:153], v[92:95], v[174:177]
	v_mfma_f32_16x16x32_bf16 v[40:43], v[142:145], v[210:213], v[40:43]
	v_mfma_f32_16x16x32_bf16 v[20:23], v[146:149], v[88:91], v[20:23]
	v_mfma_f32_16x16x32_bf16 v[24:27], v[154:157], v[88:91], v[24:27]
	v_mfma_f32_16x16x32_bf16 v[28:31], v[146:149], v[112:115], v[28:31]
	v_mfma_f32_16x16x32_bf16 v[32:35], v[154:157], v[112:115], v[32:35]
	v_mfma_f32_16x16x32_bf16 v[166:169], v[142:145], v[120:123], v[178:181]
	v_mfma_f32_16x16x32_bf16 v[170:173], v[150:153], v[120:123], v[182:185]
	v_mfma_f32_16x16x32_bf16 v[40:43], v[146:149], v[214:217], v[40:43]
	s_setprio 1
	v_mfma_f32_16x16x32_bf16 v[48:51], v[150:153], v[210:213], v[48:51]
	v_mfma_f32_16x16x32_bf16 v[166:169], v[146:149], v[206:209], v[166:169]
	v_mfma_f32_16x16x32_bf16 v[170:173], v[154:157], v[206:209], v[170:173]
	v_mfma_f32_16x16x32_bf16 v[142:145], v[154:157], v[214:217], v[48:51]
	s_setprio 0
	s_setprio 1
	v_mfma_f32_16x16x32_bf16 v[48:51], v[158:161], v[80:83], v[52:55]
	v_mfma_f32_16x16x32_bf16 v[146:149], v[162:165], v[88:91], v[48:51]
	v_mfma_f32_16x16x32_bf16 v[48:51], v[186:189], v[80:83], v[56:59]
	v_mfma_f32_16x16x32_bf16 v[150:153], v[190:193], v[88:91], v[48:51]
	v_mfma_f32_16x16x32_bf16 v[48:51], v[158:161], v[92:95], v[60:63]
	v_mfma_f32_16x16x32_bf16 v[154:157], v[162:165], v[112:115], v[48:51]
	v_mfma_f32_16x16x32_bf16 v[48:51], v[186:189], v[92:95], v[64:67]
	v_mfma_f32_16x16x32_bf16 v[174:177], v[190:193], v[112:115], v[48:51]
	v_mfma_f32_16x16x32_bf16 v[48:51], v[158:161], v[120:123], v[96:99]
	v_mfma_f32_16x16x32_bf16 v[178:181], v[162:165], v[206:209], v[48:51]
	s_barrier
; #define PG8_STAGE(bufoff, gbase, voff) do { _Pragma("unroll") for (int _i = 0; _i < 2; ++_i) \
;         __builtin_amdgcn_global_load_lds((const unsigned*)((const char*)(gbase) + (voff)[_i]), (PG8_LAS unsigned*)(lds + (bufoff) + ldsw + _i * 8192), 16, 0, 0); } while (0)
; #define PG8_LDA(dst, b, h) do { _Pragma("unroll") for (int m = 0; m < 4; ++m) _Pragma("unroll") for (int k = 0; k < 2; ++k) dst[m][k] = *(const PG8_LAS bf16x8*)(lds + PG8_SA(b, h) + aoff + m * 2048 + k * 1024); } while (0)
; #define PG8_LDB(dst, b, h) do { _Pragma("unroll") for (int n = 0; n < 2; ++n) _Pragma("unroll") for (int k = 0; k < 2; ++k) dst[n][k] = *(const PG8_LAS bf16x8*)(lds + PG8_SB(b, h) + boff + n * 2048 + k * 1024); } while (0)
; #define PG8_MMA(ai, bj, At, Bt) do { __builtin_amdgcn_s_setprio(1); _Pragma("unroll") for (int m = 0; m < 4; ++m) _Pragma("unroll") for (int n = 0; n < 2; ++n) _Pragma("unroll") for (int k = 0; k < 2; ++k) \
;         acc[ai][bj][m][n] = __builtin_amdgcn_mfma_f32_16x16x32_bf16(Bt[n][k], At[m][k], acc[ai][bj][m][n], 0, 0, 0); __builtin_amdgcn_s_setprio(0); } while (0)
; #define PG8_WAIT_V(n) asm volatile("s_waitcnt vmcnt(" #n ")" ::: "memory")
; #define PG8_WAIT_L(n) asm volatile("s_waitcnt lgkmcnt(" #n ")" ::: "memory")
; #define PG8_BAR __builtin_amdgcn_s_barrier()
; #define PG8_SCHED __builtin_amdgcn_sched_barrier(0)
; template <class Epi, class Sched, bool ALIGN_EPI = false, bool SP2 = false>
; __device__ __forceinline__ void gemm_phase(PG8_LAS unsigned char* lds, const Gemm g, const Sched& S, const Epi& E, const int wave_id) {
;     ...
;             PG8_LDB(B0, 1, 0); PG8_LDB(B1, 1, 1); PG8_SCHED; PG8_LDA(At, 1, 0); PG8_STAGE(PG8_SA(0, 1), a2 + hstep, voffA);
;             PG8_WAIT_V(8); PG8_WAIT_L(0); PG8_BAR; PG8_MMA(0, 0, At, B0); PG8_MMA(0, 1, At, B1); PG8_BAR; PG8_SCHED;
;             PG8_LDA(At, 1, 1); PG8_STAGE(PG8_SB(1, 0), b3, voffB); PG8_STAGE(PG8_SB(1, 1), b3 + hstep, voffB); PG8_STAGE(PG8_SA(1, 0), a3, voffA);
;             PG8_WAIT_V(8); PG8_WAIT_L(0); PG8_BAR; PG8_MMA(1, 0, At, B0); PG8_MMA(1, 1, At, B1); PG8_BAR; PG8_SCHED;
;     ...
;         if constexpr (ALIGN_EPI) { if (wr == 0) PG8_BAR; }
	v_mfma_f32_16x16x32_bf16 v[48:51], v[186:189], v[120:123], v[138:141]
	v_mfma_f32_16x16x32_bf16 v[44:47], v[158:161], v[210:213], v[44:47]
	v_mfma_f32_16x16x32_bf16 v[36:39], v[186:189], v[210:213], v[36:39]
	v_mfma_f32_16x16x32_bf16 v[138:141], v[190:193], v[206:209], v[48:51]
	v_mfma_f32_16x16x32_bf16 v[158:161], v[162:165], v[214:217], v[44:47]
	v_mfma_f32_16x16x32_bf16 v[162:165], v[190:193], v[214:217], v[36:39]
	s_setprio 0
	ds_read_b128 v[64:67], v234
	ds_read_b128 v[182:185], v234 offset:1024
	ds_read_b128 v[186:189], v234 offset:2048
	ds_read_b128 v[190:193], v234 offset:3072
	ds_read_b128 v[206:209], v235
	ds_read_b128 v[210:213], v235 offset:1024
	ds_read_b128 v[214:217], v235 offset:2048
	ds_read_b128 v[218:221], v235 offset:3072
	s_mov_b32 m0, s69
	ds_read_b128 v[36:39], v242 offset:32768
	ds_read_b128 v[44:47], v242 offset:33792
	ds_read_b128 v[52:55], v242 offset:34816
	ds_read_b128 v[60:63], v242 offset:35840
	ds_read_b128 v[222:225], v242 offset:36864
	ds_read_b128 v[230:233], v242 offset:37888
	ds_read_b128 v[234:237], v242 offset:38912
	ds_read_b128 v[238:241], v242 offset:39936
	global_load_lds_dwordx4 v[12:13], off
	s_mov_b32 m0, s70
	s_nop 0
	global_load_lds_dwordx4 v[14:15], off
	s_waitcnt vmcnt(8)
	s_waitcnt lgkmcnt(0)
	s_barrier
	s_waitcnt lgkmcnt(0)
	v_mfma_f32_16x16x32_bf16 v[12:15], v[64:67], v[36:39], v[16:19]
	v_mfma_f32_16x16x32_bf16 v[120:123], v[182:185], v[44:47], v[12:15]
	v_mfma_f32_16x16x32_bf16 v[12:15], v[186:189], v[36:39], v[100:103]
	v_mfma_f32_16x16x32_bf16 v[112:115], v[190:193], v[44:47], v[12:15]
	v_mfma_f32_16x16x32_bf16 v[12:15], v[64:67], v[52:55], v[104:107]
	v_mfma_f32_16x16x32_bf16 v[104:107], v[182:185], v[60:63], v[12:15]
	v_mfma_f32_16x16x32_bf16 v[12:15], v[186:189], v[52:55], v[108:111]
	v_mfma_f32_16x16x32_bf16 v[96:99], v[190:193], v[60:63], v[12:15]
	v_mfma_f32_16x16x32_bf16 v[12:15], v[64:67], v[222:225], v[116:119]
	v_mfma_f32_16x16x32_bf16 v[88:91], v[182:185], v[230:233], v[12:15]
	v_mfma_f32_16x16x32_bf16 v[12:15], v[186:189], v[222:225], v[226:229]
	v_mfma_f32_16x16x32_bf16 v[80:83], v[190:193], v[230:233], v[12:15]
	s_setprio 1
	v_mfma_f32_16x16x32_bf16 v[12:15], v[64:67], v[234:237], v[124:127]
	v_mfma_f32_16x16x32_bf16 v[56:59], v[182:185], v[238:241], v[12:15]
	v_mfma_f32_16x16x32_bf16 v[12:15], v[186:189], v[234:237], v[130:133]
	v_mfma_f32_16x16x32_bf16 v[48:51], v[190:193], v[238:241], v[12:15]
	s_setprio 0
	s_setprio 1
	v_mfma_f32_16x16x32_bf16 v[12:15], v[206:209], v[36:39], v[134:137]
	v_mfma_f32_16x16x32_bf16 v[124:127], v[210:213], v[44:47], v[12:15]
	v_mfma_f32_16x16x32_bf16 v[12:15], v[214:217], v[36:39], v[68:71]
	v_mfma_f32_16x16x32_bf16 v[116:119], v[218:221], v[44:47], v[12:15]
	v_mfma_f32_16x16x32_bf16 v[12:15], v[206:209], v[52:55], v[72:75]
	v_mfma_f32_16x16x32_bf16 v[108:111], v[210:213], v[60:63], v[12:15]
	v_mfma_f32_16x16x32_bf16 v[12:15], v[214:217], v[52:55], v[76:79]
	v_mfma_f32_16x16x32_bf16 v[100:103], v[218:221], v[60:63], v[12:15]
	v_mfma_f32_16x16x32_bf16 v[12:15], v[206:209], v[222:225], v[194:197]
	v_mfma_f32_16x16x32_bf16 v[92:95], v[210:213], v[230:233], v[12:15]
	s_barrier
	v_mfma_f32_16x16x32_bf16 v[12:15], v[214:217], v[222:225], v[84:87]
	v_mfma_f32_16x16x32_bf16 v[84:87], v[218:221], v[230:233], v[12:15]
	v_mfma_f32_16x16x32_bf16 v[12:15], v[206:209], v[234:237], v[198:201]
	v_mfma_f32_16x16x32_bf16 v[60:63], v[210:213], v[238:241], v[12:15]
	v_mfma_f32_16x16x32_bf16 v[12:15], v[214:217], v[234:237], v[202:205]
	v_mfma_f32_16x16x32_bf16 v[52:55], v[218:221], v[238:241], v[12:15]
	s_setprio 0
	s_mov_b32 m0, s87
	ds_read_b128 v[16:19], v242 offset:49152
	ds_read_b128 v[130:133], v242 offset:50176
	ds_read_b128 v[134:137], v242 offset:51200
	ds_read_b128 v[194:197], v242 offset:52224
	ds_read_b128 v[198:201], v242 offset:53248
	ds_read_b128 v[202:205], v242 offset:54272
	ds_read_b128 v[222:225], v242 offset:55296
	ds_read_b128 v[226:229], v242 offset:56320
	global_load_lds_dwordx4 v[4:5], off
	s_mov_b32 m0, s88
	s_nop 0
	global_load_lds_dwordx4 v[6:7], off
	s_mov_b32 m0, s89
	s_nop 0
	global_load_lds_dwordx4 v[8:9], off
	s_mov_b32 m0, s90
	s_nop 0
	global_load_lds_dwordx4 v[10:11], off
	s_mov_b32 m0, s73
	s_nop 0
	global_load_lds_dwordx4 v[0:1], off
	s_mov_b32 m0, s74
	s_nop 0
	global_load_lds_dwordx4 v[2:3], off
	s_waitcnt vmcnt(8)
	s_waitcnt lgkmcnt(0)
	s_barrier
	s_waitcnt lgkmcnt(0)
	v_mfma_f32_16x16x32_bf16 v[0:3], v[64:67], v[16:19], v[20:23]
	v_mfma_f32_16x16x32_bf16 v[76:79], v[182:185], v[130:133], v[0:3]
	v_mfma_f32_16x16x32_bf16 v[0:3], v[186:189], v[16:19], v[24:27]
	v_mfma_f32_16x16x32_bf16 v[68:71], v[190:193], v[130:133], v[0:3]
	v_mfma_f32_16x16x32_bf16 v[0:3], v[64:67], v[134:137], v[28:31]
	v_mfma_f32_16x16x32_bf16 v[44:47], v[182:185], v[194:197], v[0:3]
	v_mfma_f32_16x16x32_bf16 v[0:3], v[186:189], v[134:137], v[32:35]
	v_mfma_f32_16x16x32_bf16 v[36:39], v[190:193], v[194:197], v[0:3]
	v_mfma_f32_16x16x32_bf16 v[0:3], v[64:67], v[198:201], v[166:169]
	v_mfma_f32_16x16x32_bf16 v[28:31], v[182:185], v[202:205], v[0:3]
	v_mfma_f32_16x16x32_bf16 v[0:3], v[186:189], v[198:201], v[170:173]
	v_mfma_f32_16x16x32_bf16 v[20:23], v[190:193], v[202:205], v[0:3]
	s_setprio 1
	v_mfma_f32_16x16x32_bf16 v[0:3], v[64:67], v[222:225], v[40:43]
	v_mfma_f32_16x16x32_bf16 v[12:15], v[182:185], v[226:229], v[0:3]
	v_mfma_f32_16x16x32_bf16 v[0:3], v[186:189], v[222:225], v[142:145]
	v_mfma_f32_16x16x32_bf16 v[4:7], v[190:193], v[226:229], v[0:3]
	s_setprio 0
	s_setprio 1
	v_mfma_f32_16x16x32_bf16 v[0:3], v[206:209], v[16:19], v[146:149]
	v_mfma_f32_16x16x32_bf16 v[72:75], v[210:213], v[130:133], v[0:3]
	v_mfma_f32_16x16x32_bf16 v[0:3], v[214:217], v[16:19], v[150:153]
	v_mfma_f32_16x16x32_bf16 v[64:67], v[218:221], v[130:133], v[0:3]
	v_mfma_f32_16x16x32_bf16 v[0:3], v[206:209], v[134:137], v[154:157]
	v_mfma_f32_16x16x32_bf16 v[40:43], v[210:213], v[194:197], v[0:3]
	v_mfma_f32_16x16x32_bf16 v[0:3], v[214:217], v[134:137], v[174:177]
	v_mfma_f32_16x16x32_bf16 v[32:35], v[218:221], v[194:197], v[0:3]
	v_mfma_f32_16x16x32_bf16 v[0:3], v[206:209], v[198:201], v[178:181]
	v_mfma_f32_16x16x32_bf16 v[24:27], v[210:213], v[202:205], v[0:3]
	s_barrier
	v_mfma_f32_16x16x32_bf16 v[0:3], v[214:217], v[198:201], v[138:141]
	v_mfma_f32_16x16x32_bf16 v[16:19], v[218:221], v[202:205], v[0:3]
	v_mfma_f32_16x16x32_bf16 v[0:3], v[206:209], v[222:225], v[158:161]
	v_mfma_f32_16x16x32_bf16 v[8:11], v[210:213], v[226:229], v[0:3]
	v_mfma_f32_16x16x32_bf16 v[0:3], v[214:217], v[222:225], v[162:165]
	v_mfma_f32_16x16x32_bf16 v[0:3], v[218:221], v[226:229], v[0:3]
	s_setprio 0
	v_cndmask_b32_e64 v130, 0, 1, s[16:17]
	v_cmp_ne_u32_e64 s[4:5], 1, v130
	s_andn2_b64 vcc, exec, s[16:17]
	s_cbranch_vccnz .LBB0_486
	s_barrier

; #define PG8_STAGE(bufoff, gbase, voff) do { _Pragma("unroll") for (int _i = 0; _i < 2; ++_i) \
;         __builtin_amdgcn_global_load_lds((const unsigned*)((const char*)(gbase) + (voff)[_i]), (PG8_LAS unsigned*)(lds + (bufoff) + ldsw + _i * 8192), 16, 0, 0); } while (0)
; #define PG8_LDA(dst, b, h) do { _Pragma("unroll") for (int m = 0; m < 4; ++m) _Pragma("unroll") for (int k = 0; k < 2; ++k) dst[m][k] = *(const PG8_LAS bf16x8*)(lds + PG8_SA(b, h) + aoff + m * 2048 + k * 1024); } while (0)
; #define PG8_LDB(dst, b, h) do { _Pragma("unroll") for (int n = 0; n < 2; ++n) _Pragma("unroll") for (int k = 0; k < 2; ++k) dst[n][k] = *(const PG8_LAS bf16x8*)(lds + PG8_SB(b, h) + boff + n * 2048 + k * 1024); } while (0)
; #define PG8_MMA(ai, bj, At, Bt) do { __builtin_amdgcn_s_setprio(1); _Pragma("unroll") for (int m = 0; m < 4; ++m) _Pragma("unroll") for (int n = 0; n < 2; ++n) _Pragma("unroll") for (int k = 0; k < 2; ++k) \
;         acc[ai][bj][m][n] = __builtin_amdgcn_mfma_f32_16x16x32_bf16(Bt[n][k], At[m][k], acc[ai][bj][m][n], 0, 0, 0); __builtin_amdgcn_s_setprio(0); } while (0)
; #define PG8_WAIT_V(n) asm volatile("s_waitcnt vmcnt(" #n ")" ::: "memory")
; #define PG8_BAR __builtin_amdgcn_s_barrier()
; template <class Epi, class Sched, bool ALIGN_EPI = false, bool SP2 = false>
; __device__ __forceinline__ void gemm_phase(PG8_LAS unsigned char* lds, const Gemm g, const Sched& S, const Epi& E, const int wave_id) {
;     ...
;         for (int t = 0; t < nt; t += 2) {
;             const bool last = (t == nt - 2);
;             const char* a1 = cA + (size_t)(t + 1) * kstep;
;             const char* a2 = last ? nA : cA + (size_t)(t + 2) * kstep; const char* b2 = last ? nB : cB + (size_t)(t + 2) * kstep;
;             const char* a3 = a2 + kstep; const char* b3 = b2 + kstep;
;             if (last && has_next) S.a_ready(nxt);
;             if constexpr (SP2) {
;             PG8_LDB(B0, 0, 0); PG8_LDB(B1, 0, 1); PG8_SCHED; PG8_LDA(At, 0, 0); PG8_STAGE(PG8_SA(1, 1), a1 + hstep, voffA);
;             PG8_WAIT_V(8); PG8_WAIT_L(0); PG8_BAR; PG8_MMA(0, 0, At, B0); PG8_MMA(0, 1, At, B1); PG8_BAR; PG8_SCHED;
;             PG8_LDA(At, 0, 1); PG8_STAGE(PG8_SB(0, 0), b2, voffB); PG8_STAGE(PG8_SB(0, 1), b2 + hstep, voffB); PG8_STAGE(PG8_SA(0, 0), a2, voffA);
;             PG8_WAIT_V(8); PG8_WAIT_L(0); PG8_BAR; PG8_MMA(1, 0, At, B0); PG8_MMA(1, 1, At, B1); PG8_BAR; PG8_SCHED;
.LBB0_522:
	ds_read_b128 v[132:135], v193
	ds_read_b128 v[136:139], v193 offset:1024
	ds_read_b128 v[140:143], v193 offset:2048
	ds_read_b128 v[144:147], v193 offset:3072
	ds_read_b128 v[148:151], v197
	ds_read_b128 v[152:155], v197 offset:1024
	ds_read_b128 v[156:159], v197 offset:2048
	ds_read_b128 v[160:163], v197 offset:3072
	s_add_u32 s50, s46, s48
	s_addc_u32 s51, s47, s49
	s_add_u32 s50, s50, 0x100
	s_addc_u32 s51, s51, 0
	s_add_u32 s92, s13, s48
	s_addc_u32 s93, s67, s49
	s_cmpk_eq_i32 s48, 0xf00
	s_cselect_b32 s55, vcc_lo, s51
	s_cselect_b32 s54, vcc_hi, s50
	s_cselect_b32 s51, s39, s93
	s_cselect_b32 s50, s38, s92
	s_mov_b32 m0, s79
	v_lshl_add_u64 v[186:187], v[128:129], 0, s[48:49]
	ds_read_b128 v[164:167], v201
	ds_read_b128 v[210:213], v201 offset:1024
	ds_read_b128 v[214:217], v201 offset:2048
	ds_read_b128 v[218:221], v201 offset:3072
	ds_read_b128 v[222:225], v201 offset:4096
	ds_read_b128 v[226:229], v201 offset:5120
	ds_read_b128 v[230:233], v201 offset:6144
	ds_read_b128 v[234:237], v201 offset:7168
	global_load_lds_dwordx4 v[186:187], off
	v_lshl_add_u64 v[186:187], v[130:131], 0, s[48:49]
	s_mov_b32 m0, s80
	s_nop 0
	global_load_lds_dwordx4 v[186:187], off
	s_waitcnt vmcnt(8)
	s_waitcnt lgkmcnt(0)
	s_barrier
	s_waitcnt lgkmcnt(0)
	v_mfma_f32_16x16x32_bf16 v[124:127], v[132:135], v[164:167], v[124:127]
	v_mfma_f32_16x16x32_bf16 v[120:123], v[140:143], v[164:167], v[120:123]
	v_mfma_f32_16x16x32_bf16 v[108:111], v[132:135], v[214:217], v[108:111]
	v_mfma_f32_16x16x32_bf16 v[104:107], v[140:143], v[214:217], v[104:107]
	v_mfma_f32_16x16x32_bf16 v[92:95], v[132:135], v[222:225], v[92:95]
	v_mfma_f32_16x16x32_bf16 v[88:91], v[140:143], v[222:225], v[88:91]
	v_mfma_f32_16x16x32_bf16 v[76:79], v[132:135], v[230:233], v[76:79]
	v_mfma_f32_16x16x32_bf16 v[72:75], v[140:143], v[230:233], v[72:75]
	v_mfma_f32_16x16x32_bf16 v[124:127], v[136:139], v[210:213], v[124:127]
	v_mfma_f32_16x16x32_bf16 v[120:123], v[144:147], v[210:213], v[120:123]
	v_mfma_f32_16x16x32_bf16 v[108:111], v[136:139], v[218:221], v[108:111]
	v_mfma_f32_16x16x32_bf16 v[104:107], v[144:147], v[218:221], v[104:107]
	s_setprio 1
	v_mfma_f32_16x16x32_bf16 v[92:95], v[136:139], v[226:229], v[92:95]
	v_mfma_f32_16x16x32_bf16 v[88:91], v[144:147], v[226:229], v[88:91]
	v_mfma_f32_16x16x32_bf16 v[76:79], v[136:139], v[234:237], v[76:79]
	v_mfma_f32_16x16x32_bf16 v[72:75], v[144:147], v[234:237], v[72:75]
	s_setprio 0
	s_setprio 1
	v_mfma_f32_16x16x32_bf16 v[116:119], v[148:151], v[164:167], v[116:119]
	v_mfma_f32_16x16x32_bf16 v[112:115], v[156:159], v[164:167], v[112:115]
	v_mfma_f32_16x16x32_bf16 v[100:103], v[148:151], v[214:217], v[100:103]
	v_mfma_f32_16x16x32_bf16 v[96:99], v[156:159], v[214:217], v[96:99]
	v_mfma_f32_16x16x32_bf16 v[84:87], v[148:151], v[222:225], v[84:87]
	v_mfma_f32_16x16x32_bf16 v[80:83], v[156:159], v[222:225], v[80:83]
	v_mfma_f32_16x16x32_bf16 v[68:71], v[148:151], v[230:233], v[68:71]
	v_mfma_f32_16x16x32_bf16 v[64:67], v[156:159], v[230:233], v[64:67]
	v_mfma_f32_16x16x32_bf16 v[116:119], v[152:155], v[210:213], v[116:119]
	v_mfma_f32_16x16x32_bf16 v[112:115], v[160:163], v[210:213], v[112:115]
	s_barrier
	v_mfma_f32_16x16x32_bf16 v[100:103], v[152:155], v[218:221], v[100:103]
	v_mfma_f32_16x16x32_bf16 v[96:99], v[160:163], v[218:221], v[96:99]
	v_mfma_f32_16x16x32_bf16 v[84:87], v[152:155], v[226:229], v[84:87]
	v_mfma_f32_16x16x32_bf16 v[80:83], v[160:163], v[226:229], v[80:83]
	v_mfma_f32_16x16x32_bf16 v[68:71], v[152:155], v[234:237], v[68:71]
	v_mfma_f32_16x16x32_bf16 v[64:67], v[160:163], v[234:237], v[64:67]
	s_setprio 0
	s_mov_b32 m0, s81
	v_lshl_add_u64 v[186:187], s[50:51], 0, v[168:169]
	s_add_u32 s92, s50, 0x80000
	ds_read_b128 v[164:167], v201 offset:16384
	ds_read_b128 v[210:213], v201 offset:17408
	ds_read_b128 v[214:217], v201 offset:18432
	ds_read_b128 v[218:221], v201 offset:19456
	ds_read_b128 v[222:225], v201 offset:20480
	ds_read_b128 v[226:229], v201 offset:21504
	ds_read_b128 v[230:233], v201 offset:22528
	ds_read_b128 v[234:237], v201 offset:23552
	global_load_lds_dwordx4 v[186:187], off
	v_lshl_add_u64 v[190:191], s[50:51], 0, v[174:175]
	s_mov_b32 m0, s82
	s_addc_u32 s93, s51, 0
	global_load_lds_dwordx4 v[190:191], off
	v_lshl_add_u64 v[194:195], s[92:93], 0, v[168:169]
	s_mov_b32 m0, s83
	v_lshl_add_u64 v[198:199], s[54:55], 0, v[172:173]
	global_load_lds_dwordx4 v[194:195], off
	v_lshl_add_u64 v[194:195], s[92:93], 0, v[174:175]
	s_mov_b32 m0, s84
	s_nop 0
	global_load_lds_dwordx4 v[194:195], off
	v_lshl_add_u64 v[194:195], s[54:55], 0, v[170:171]
	s_mov_b32 m0, s33
	s_nop 0
	global_load_lds_dwordx4 v[194:195], off
	s_mov_b32 m0, s63
	s_nop 0
	global_load_lds_dwordx4 v[198:199], off
	s_waitcnt vmcnt(8)
	s_waitcnt lgkmcnt(0)
	s_barrier
; #define PG8_STAGE(bufoff, gbase, voff) do { _Pragma("unroll") for (int _i = 0; _i < 2; ++_i) \
;         __builtin_amdgcn_global_load_lds((const unsigned*)((const char*)(gbase) + (voff)[_i]), (PG8_LAS unsigned*)(lds + (bufoff) + ldsw + _i * 8192), 16, 0, 0); } while (0)
; #define PG8_LDA(dst, b, h) do { _Pragma("unroll") for (int m = 0; m < 4; ++m) _Pragma("unroll") for (int k = 0; k < 2; ++k) dst[m][k] = *(const PG8_LAS bf16x8*)(lds + PG8_SA(b, h) + aoff + m * 2048 + k * 1024); } while (0)
; #define PG8_LDB(dst, b, h) do { _Pragma("unroll") for (int n = 0; n < 2; ++n) _Pragma("unroll") for (int k = 0; k < 2; ++k) dst[n][k] = *(const PG8_LAS bf16x8*)(lds + PG8_SB(b, h) + boff + n * 2048 + k * 1024); } while (0)
; #define PG8_MMA(ai, bj, At, Bt) do { __builtin_amdgcn_s_setprio(1); _Pragma("unroll") for (int m = 0; m < 4; ++m) _Pragma("unroll") for (int n = 0; n < 2; ++n) _Pragma("unroll") for (int k = 0; k < 2; ++k) \
;         acc[ai][bj][m][n] = __builtin_amdgcn_mfma_f32_16x16x32_bf16(Bt[n][k], At[m][k], acc[ai][bj][m][n], 0, 0, 0); __builtin_amdgcn_s_setprio(0); } while (0)
; #define PG8_WAIT_V(n) asm volatile("s_waitcnt vmcnt(" #n ")" ::: "memory")
; #define PG8_WAIT_L(n) asm volatile("s_waitcnt lgkmcnt(" #n ")" ::: "memory")
; #define PG8_BAR __builtin_amdgcn_s_barrier()
; #define PG8_SCHED __builtin_amdgcn_sched_barrier(0)
; template <class Epi, class Sched, bool ALIGN_EPI = false, bool SP2 = false>
; __device__ __forceinline__ void gemm_phase(PG8_LAS unsigned char* lds, const Gemm g, const Sched& S, const Epi& E, const int wave_id) {
;     ...
;             PG8_WAIT_V(8); PG8_WAIT_L(0); PG8_BAR; PG8_MMA(1, 0, At, B0); PG8_MMA(1, 1, At, B1); PG8_BAR; PG8_SCHED;
;             PG8_LDB(B0, 1, 0); PG8_LDB(B1, 1, 1); PG8_SCHED; PG8_LDA(At, 1, 0); PG8_STAGE(PG8_SA(0, 1), a2 + hstep, voffA);
;             PG8_WAIT_V(8); PG8_WAIT_L(0); PG8_BAR; PG8_MMA(0, 0, At, B0); PG8_MMA(0, 1, At, B1); PG8_BAR; PG8_SCHED;
	s_waitcnt lgkmcnt(0)
	v_mfma_f32_16x16x32_bf16 v[60:63], v[132:135], v[164:167], v[60:63]
	v_mfma_f32_16x16x32_bf16 v[56:59], v[140:143], v[164:167], v[56:59]
	v_mfma_f32_16x16x32_bf16 v[44:47], v[132:135], v[214:217], v[44:47]
	v_mfma_f32_16x16x32_bf16 v[40:43], v[140:143], v[214:217], v[40:43]
	v_mfma_f32_16x16x32_bf16 v[28:31], v[132:135], v[222:225], v[28:31]
	v_mfma_f32_16x16x32_bf16 v[24:27], v[140:143], v[222:225], v[24:27]
	v_mfma_f32_16x16x32_bf16 v[12:15], v[132:135], v[230:233], v[12:15]
	v_mfma_f32_16x16x32_bf16 v[8:11], v[140:143], v[230:233], v[8:11]
	v_mfma_f32_16x16x32_bf16 v[60:63], v[136:139], v[210:213], v[60:63]
	v_mfma_f32_16x16x32_bf16 v[56:59], v[144:147], v[210:213], v[56:59]
	v_mfma_f32_16x16x32_bf16 v[44:47], v[136:139], v[218:221], v[44:47]
	v_mfma_f32_16x16x32_bf16 v[40:43], v[144:147], v[218:221], v[40:43]
	s_setprio 1
	v_mfma_f32_16x16x32_bf16 v[28:31], v[136:139], v[226:229], v[28:31]
	v_mfma_f32_16x16x32_bf16 v[24:27], v[144:147], v[226:229], v[24:27]
	v_mfma_f32_16x16x32_bf16 v[12:15], v[136:139], v[234:237], v[12:15]
	v_mfma_f32_16x16x32_bf16 v[8:11], v[144:147], v[234:237], v[8:11]
	s_setprio 0
	s_setprio 1
	v_mfma_f32_16x16x32_bf16 v[52:55], v[148:151], v[164:167], v[52:55]
	v_mfma_f32_16x16x32_bf16 v[48:51], v[156:159], v[164:167], v[48:51]
	v_mfma_f32_16x16x32_bf16 v[36:39], v[148:151], v[214:217], v[36:39]
	v_mfma_f32_16x16x32_bf16 v[32:35], v[156:159], v[214:217], v[32:35]
	v_mfma_f32_16x16x32_bf16 v[20:23], v[148:151], v[222:225], v[20:23]
	v_mfma_f32_16x16x32_bf16 v[16:19], v[156:159], v[222:225], v[16:19]
	v_mfma_f32_16x16x32_bf16 v[4:7], v[148:151], v[230:233], v[4:7]
	v_mfma_f32_16x16x32_bf16 v[0:3], v[156:159], v[230:233], v[0:3]
	v_mfma_f32_16x16x32_bf16 v[52:55], v[152:155], v[210:213], v[52:55]
	v_mfma_f32_16x16x32_bf16 v[48:51], v[160:163], v[210:213], v[48:51]
	s_barrier
	v_mfma_f32_16x16x32_bf16 v[36:39], v[152:155], v[218:221], v[36:39]
	v_mfma_f32_16x16x32_bf16 v[32:35], v[160:163], v[218:221], v[32:35]
	v_mfma_f32_16x16x32_bf16 v[20:23], v[152:155], v[226:229], v[20:23]
	v_mfma_f32_16x16x32_bf16 v[16:19], v[160:163], v[226:229], v[16:19]
	v_mfma_f32_16x16x32_bf16 v[4:7], v[152:155], v[234:237], v[4:7]
	v_mfma_f32_16x16x32_bf16 v[0:3], v[160:163], v[234:237], v[0:3]
	s_setprio 0
	ds_read_b128 v[132:135], v205
	ds_read_b128 v[136:139], v205 offset:1024
	ds_read_b128 v[140:143], v205 offset:2048
	ds_read_b128 v[144:147], v205 offset:3072
	ds_read_b128 v[148:151], v208
	ds_read_b128 v[152:155], v208 offset:1024
	ds_read_b128 v[156:159], v208 offset:2048
	ds_read_b128 v[160:163], v208 offset:3072
	s_add_u32 s54, s54, 0x80000
	s_addc_u32 s55, s55, 0
	s_mov_b32 m0, s69
	v_lshl_add_u64 v[202:203], s[54:55], 0, v[170:171]
	ds_read_b128 v[164:167], v201 offset:32768
	ds_read_b128 v[210:213], v201 offset:33792
	ds_read_b128 v[214:217], v201 offset:34816
	ds_read_b128 v[218:221], v201 offset:35840
	ds_read_b128 v[222:225], v201 offset:36864
	ds_read_b128 v[226:229], v201 offset:37888
	ds_read_b128 v[230:233], v201 offset:38912
	ds_read_b128 v[234:237], v201 offset:39936
	global_load_lds_dwordx4 v[202:203], off
	v_lshl_add_u64 v[202:203], s[54:55], 0, v[172:173]
	s_mov_b32 m0, s70
	s_nop 0
	global_load_lds_dwordx4 v[202:203], off
	s_waitcnt vmcnt(8)
	s_waitcnt lgkmcnt(0)
	s_barrier
	s_waitcnt lgkmcnt(0)
	v_mfma_f32_16x16x32_bf16 v[124:127], v[132:135], v[164:167], v[124:127]
	v_mfma_f32_16x16x32_bf16 v[120:123], v[140:143], v[164:167], v[120:123]
	v_mfma_f32_16x16x32_bf16 v[108:111], v[132:135], v[214:217], v[108:111]
	v_mfma_f32_16x16x32_bf16 v[104:107], v[140:143], v[214:217], v[104:107]
	v_mfma_f32_16x16x32_bf16 v[92:95], v[132:135], v[222:225], v[92:95]
	v_mfma_f32_16x16x32_bf16 v[88:91], v[140:143], v[222:225], v[88:91]
	v_mfma_f32_16x16x32_bf16 v[76:79], v[132:135], v[230:233], v[76:79]
	v_mfma_f32_16x16x32_bf16 v[72:75], v[140:143], v[230:233], v[72:75]
	v_mfma_f32_16x16x32_bf16 v[124:127], v[136:139], v[210:213], v[124:127]
	v_mfma_f32_16x16x32_bf16 v[120:123], v[144:147], v[210:213], v[120:123]
	v_mfma_f32_16x16x32_bf16 v[108:111], v[136:139], v[218:221], v[108:111]
	v_mfma_f32_16x16x32_bf16 v[104:107], v[144:147], v[218:221], v[104:107]
	s_setprio 1
	v_mfma_f32_16x16x32_bf16 v[92:95], v[136:139], v[226:229], v[92:95]
	v_mfma_f32_16x16x32_bf16 v[88:91], v[144:147], v[226:229], v[88:91]
	v_mfma_f32_16x16x32_bf16 v[76:79], v[136:139], v[234:237], v[76:79]
	v_mfma_f32_16x16x32_bf16 v[72:75], v[144:147], v[234:237], v[72:75]
	s_setprio 0
	s_setprio 1
	v_mfma_f32_16x16x32_bf16 v[116:119], v[148:151], v[164:167], v[116:119]
	v_mfma_f32_16x16x32_bf16 v[112:115], v[156:159], v[164:167], v[112:115]
	v_mfma_f32_16x16x32_bf16 v[100:103], v[148:151], v[214:217], v[100:103]
	v_mfma_f32_16x16x32_bf16 v[96:99], v[156:159], v[214:217], v[96:99]
	v_mfma_f32_16x16x32_bf16 v[84:87], v[148:151], v[222:225], v[84:87]
	v_mfma_f32_16x16x32_bf16 v[80:83], v[156:159], v[222:225], v[80:83]
	v_mfma_f32_16x16x32_bf16 v[68:71], v[148:151], v[230:233], v[68:71]
	v_mfma_f32_16x16x32_bf16 v[64:67], v[156:159], v[230:233], v[64:67]
	v_mfma_f32_16x16x32_bf16 v[116:119], v[152:155], v[210:213], v[116:119]
	v_mfma_f32_16x16x32_bf16 v[112:115], v[160:163], v[210:213], v[112:115]
	s_barrier
; #define PG8_STAGE(bufoff, gbase, voff) do { _Pragma("unroll") for (int _i = 0; _i < 2; ++_i) \
;         __builtin_amdgcn_global_load_lds((const unsigned*)((const char*)(gbase) + (voff)[_i]), (PG8_LAS unsigned*)(lds + (bufoff) + ldsw + _i * 8192), 16, 0, 0); } while (0)
; #define PG8_LDA(dst, b, h) do { _Pragma("unroll") for (int m = 0; m < 4; ++m) _Pragma("unroll") for (int k = 0; k < 2; ++k) dst[m][k] = *(const PG8_LAS bf16x8*)(lds + PG8_SA(b, h) + aoff + m * 2048 + k * 1024); } while (0)
; #define PG8_MMA(ai, bj, At, Bt) do { __builtin_amdgcn_s_setprio(1); _Pragma("unroll") for (int m = 0; m < 4; ++m) _Pragma("unroll") for (int n = 0; n < 2; ++n) _Pragma("unroll") for (int k = 0; k < 2; ++k) \
;         acc[ai][bj][m][n] = __builtin_amdgcn_mfma_f32_16x16x32_bf16(Bt[n][k], At[m][k], acc[ai][bj][m][n], 0, 0, 0); __builtin_amdgcn_s_setprio(0); } while (0)
; #define PG8_WAIT_V(n) asm volatile("s_waitcnt vmcnt(" #n ")" ::: "memory")
; #define PG8_WAIT_L(n) asm volatile("s_waitcnt lgkmcnt(" #n ")" ::: "memory")
; #define PG8_BAR __builtin_amdgcn_s_barrier()
; #define PG8_SCHED __builtin_amdgcn_sched_barrier(0)
; template <class Epi, class Sched, bool ALIGN_EPI = false, bool SP2 = false>
; __device__ __forceinline__ void gemm_phase(PG8_LAS unsigned char* lds, const Gemm g, const Sched& S, const Epi& E, const int wave_id) {
;     ...
;             PG8_WAIT_V(8); PG8_WAIT_L(0); PG8_BAR; PG8_MMA(0, 0, At, B0); PG8_MMA(0, 1, At, B1); PG8_BAR; PG8_SCHED;
;             PG8_LDA(At, 1, 1); PG8_STAGE(PG8_SB(1, 0), b3, voffB); PG8_STAGE(PG8_SB(1, 1), b3 + hstep, voffB); PG8_STAGE(PG8_SA(1, 0), a3, voffA);
;             PG8_WAIT_V(8); PG8_WAIT_L(0); PG8_BAR; PG8_MMA(1, 0, At, B0); PG8_MMA(1, 1, At, B1); PG8_BAR; PG8_SCHED;
;     ...
;         }
;         if constexpr (ALIGN_EPI) { if (wr == 0) PG8_BAR; }
	v_mfma_f32_16x16x32_bf16 v[100:103], v[152:155], v[218:221], v[100:103]
	v_mfma_f32_16x16x32_bf16 v[96:99], v[160:163], v[218:221], v[96:99]
	v_mfma_f32_16x16x32_bf16 v[84:87], v[152:155], v[226:229], v[84:87]
	v_mfma_f32_16x16x32_bf16 v[80:83], v[160:163], v[226:229], v[80:83]
	v_mfma_f32_16x16x32_bf16 v[68:71], v[152:155], v[234:237], v[68:71]
	v_mfma_f32_16x16x32_bf16 v[64:67], v[160:163], v[234:237], v[64:67]
	s_setprio 0
	s_mov_b32 m0, s87
	v_lshl_add_u64 v[186:187], v[186:187], 0, s[44:45]
	s_add_u32 s50, s50, 0x80080
	ds_read_b128 v[164:167], v201 offset:49152
	ds_read_b128 v[210:213], v201 offset:50176
	ds_read_b128 v[214:217], v201 offset:51200
	ds_read_b128 v[218:221], v201 offset:52224
	ds_read_b128 v[222:225], v201 offset:53248
	ds_read_b128 v[226:229], v201 offset:54272
	ds_read_b128 v[230:233], v201 offset:55296
	ds_read_b128 v[234:237], v201 offset:56320
	global_load_lds_dwordx4 v[186:187], off
	v_lshl_add_u64 v[186:187], v[190:191], 0, s[44:45]
	s_mov_b32 m0, s88
	s_addc_u32 s51, s51, 0
	global_load_lds_dwordx4 v[186:187], off
	v_lshl_add_u64 v[186:187], s[50:51], 0, v[168:169]
	s_mov_b32 m0, s89
	s_nop 0
	global_load_lds_dwordx4 v[186:187], off
	v_lshl_add_u64 v[186:187], s[50:51], 0, v[174:175]
	s_mov_b32 m0, s90
	s_nop 0
	global_load_lds_dwordx4 v[186:187], off
	v_lshl_add_u64 v[186:187], v[194:195], 0, s[44:45]
	s_mov_b32 m0, s73
	s_nop 0
	global_load_lds_dwordx4 v[186:187], off
	v_lshl_add_u64 v[186:187], v[198:199], 0, s[44:45]
	s_mov_b32 m0, s74
	s_nop 0
	global_load_lds_dwordx4 v[186:187], off
	s_waitcnt vmcnt(8)
	s_waitcnt lgkmcnt(0)
	s_barrier
	s_waitcnt lgkmcnt(0)
	v_mfma_f32_16x16x32_bf16 v[60:63], v[132:135], v[164:167], v[60:63]
	v_mfma_f32_16x16x32_bf16 v[56:59], v[140:143], v[164:167], v[56:59]
	v_mfma_f32_16x16x32_bf16 v[44:47], v[132:135], v[214:217], v[44:47]
	v_mfma_f32_16x16x32_bf16 v[40:43], v[140:143], v[214:217], v[40:43]
	v_mfma_f32_16x16x32_bf16 v[28:31], v[132:135], v[222:225], v[28:31]
	v_mfma_f32_16x16x32_bf16 v[24:27], v[140:143], v[222:225], v[24:27]
	v_mfma_f32_16x16x32_bf16 v[12:15], v[132:135], v[230:233], v[12:15]
	v_mfma_f32_16x16x32_bf16 v[8:11], v[140:143], v[230:233], v[8:11]
	v_mfma_f32_16x16x32_bf16 v[60:63], v[136:139], v[210:213], v[60:63]
	v_mfma_f32_16x16x32_bf16 v[56:59], v[144:147], v[210:213], v[56:59]
	v_mfma_f32_16x16x32_bf16 v[44:47], v[136:139], v[218:221], v[44:47]
	v_mfma_f32_16x16x32_bf16 v[40:43], v[144:147], v[218:221], v[40:43]
	s_setprio 1
	v_mfma_f32_16x16x32_bf16 v[28:31], v[136:139], v[226:229], v[28:31]
	v_mfma_f32_16x16x32_bf16 v[24:27], v[144:147], v[226:229], v[24:27]
	v_mfma_f32_16x16x32_bf16 v[12:15], v[136:139], v[234:237], v[12:15]
	v_mfma_f32_16x16x32_bf16 v[8:11], v[144:147], v[234:237], v[8:11]
	s_setprio 0
	s_setprio 1
	v_mfma_f32_16x16x32_bf16 v[52:55], v[148:151], v[164:167], v[52:55]
	v_mfma_f32_16x16x32_bf16 v[48:51], v[156:159], v[164:167], v[48:51]
	v_mfma_f32_16x16x32_bf16 v[36:39], v[148:151], v[214:217], v[36:39]
	v_mfma_f32_16x16x32_bf16 v[32:35], v[156:159], v[214:217], v[32:35]
	v_mfma_f32_16x16x32_bf16 v[20:23], v[148:151], v[222:225], v[20:23]
	v_mfma_f32_16x16x32_bf16 v[16:19], v[156:159], v[222:225], v[16:19]
	v_mfma_f32_16x16x32_bf16 v[4:7], v[148:151], v[230:233], v[4:7]
	v_mfma_f32_16x16x32_bf16 v[0:3], v[156:159], v[230:233], v[0:3]
	v_mfma_f32_16x16x32_bf16 v[52:55], v[152:155], v[210:213], v[52:55]
	v_mfma_f32_16x16x32_bf16 v[48:51], v[160:163], v[210:213], v[48:51]
	s_barrier
	v_mfma_f32_16x16x32_bf16 v[36:39], v[152:155], v[218:221], v[36:39]
	v_mfma_f32_16x16x32_bf16 v[32:35], v[160:163], v[218:221], v[32:35]
	v_mfma_f32_16x16x32_bf16 v[20:23], v[152:155], v[226:229], v[20:23]
	v_mfma_f32_16x16x32_bf16 v[16:19], v[160:163], v[226:229], v[16:19]
	v_mfma_f32_16x16x32_bf16 v[4:7], v[152:155], v[234:237], v[4:7]
	v_mfma_f32_16x16x32_bf16 v[0:3], v[160:163], v[234:237], v[0:3]
	s_setprio 0
	s_add_i32 s58, s58, 2
	s_add_u32 s48, s48, 0x100
	s_addc_u32 s49, s49, 0
	s_cmp_gt_u32 s58, 29
	s_cbranch_scc0 .LBB0_522
	s_and_b64 vcc, exec, s[16:17]
	s_cbranch_vccz .LBB0_525
	s_barrier

; #define PG8_STAGE(bufoff, gbase, voff) do { _Pragma("unroll") for (int _i = 0; _i < 2; ++_i) \
;         __builtin_amdgcn_global_load_lds((const unsigned*)((const char*)(gbase) + (voff)[_i]), (PG8_LAS unsigned*)(lds + (bufoff) + ldsw + _i * 8192), 16, 0, 0); } while (0)
; #define PG8_LDA(dst, b, h) do { _Pragma("unroll") for (int m = 0; m < 4; ++m) _Pragma("unroll") for (int k = 0; k < 2; ++k) dst[m][k] = *(const PG8_LAS bf16x8*)(lds + PG8_SA(b, h) + aoff + m * 2048 + k * 1024); } while (0)
; #define PG8_LDB(dst, b, h) do { _Pragma("unroll") for (int n = 0; n < 2; ++n) _Pragma("unroll") for (int k = 0; k < 2; ++k) dst[n][k] = *(const PG8_LAS bf16x8*)(lds + PG8_SB(b, h) + boff + n * 2048 + k * 1024); } while (0)
; #define PG8_MMA(ai, bj, At, Bt) do { __builtin_amdgcn_s_setprio(1); _Pragma("unroll") for (int m = 0; m < 4; ++m) _Pragma("unroll") for (int n = 0; n < 2; ++n) _Pragma("unroll") for (int k = 0; k < 2; ++k) \
;         acc[ai][bj][m][n] = __builtin_amdgcn_mfma_f32_16x16x32_bf16(Bt[n][k], At[m][k], acc[ai][bj][m][n], 0, 0, 0); __builtin_amdgcn_s_setprio(0); } while (0)
; #define PG8_WAIT_V(n) asm volatile("s_waitcnt vmcnt(" #n ")" ::: "memory")
; #define PG8_WAIT_L(n) asm volatile("s_waitcnt lgkmcnt(" #n ")" ::: "memory")
; #define PG8_BAR __builtin_amdgcn_s_barrier()
; #define PG8_SCHED __builtin_amdgcn_sched_barrier(0)
; template <class Epi, class Sched, bool ALIGN_EPI = false, bool SP2 = false>
; __device__ __forceinline__ void gemm_phase(PG8_LAS unsigned char* lds, const Gemm g, const Sched& S, const Epi& E, const int wave_id) {
;     ...
;     const int aoff = lds_byte(wr * 64 + fr, fq * 8), boff = lds_byte(wc * 32 + fr, fq * 8);
;     ...
;         PG8_WAIT_V(2); PG8_BAR;
;         PG8_STAGE(PG8_SB(1, 0), cB + kstep, voffB); PG8_STAGE(PG8_SA(1, 0), cA + kstep, voffA); PG8_STAGE(PG8_SB(1, 1), cB + hstep + kstep, voffB);
;         PG8_WAIT_V(6); PG8_BAR;
;     ...
;             PG8_LDB(B0, 0, 0); PG8_LDB(B1, 0, 1); PG8_SCHED; PG8_LDA(At, 0, 0); PG8_STAGE(PG8_SA(1, 1), a1 + hstep, voffA);
;             PG8_WAIT_V(8); PG8_WAIT_L(0); PG8_BAR; PG8_MMA(0, 0, At, B0); PG8_MMA(0, 1, At, B1); PG8_BAR; PG8_SCHED;
.LBB0_556:
	s_mov_b64 s[0:1], 0x80
	s_mov_b32 m0, s87
	v_lshl_add_u64 v[4:5], v[28:29], 0, s[0:1]
	s_waitcnt vmcnt(2)
	s_barrier
	global_load_lds_dwordx4 v[4:5], off
	v_lshl_add_u64 v[6:7], v[30:31], 0, s[0:1]
	s_mov_b32 m0, s88
	v_lshl_add_u64 v[0:1], v[20:21], 0, s[0:1]
	global_load_lds_dwordx4 v[6:7], off
	s_mov_b32 m0, s73
	v_lshl_add_u64 v[2:3], v[22:23], 0, s[0:1]
	global_load_lds_dwordx4 v[0:1], off
	s_mov_b32 m0, s74
	v_lshl_add_u64 v[8:9], s[22:23], 0, v[32:33]
	global_load_lds_dwordx4 v[2:3], off
	s_mov_b32 m0, s89
	v_lshl_add_u64 v[10:11], s[22:23], 0, v[34:35]
	global_load_lds_dwordx4 v[8:9], off
	s_mov_b32 m0, s90
	v_and_b32_e32 v37, 15, v36
	global_load_lds_dwordx4 v[10:11], off
	v_lshrrev_b32_e32 v38, 1, v36
	v_or_b32_e32 v128, s57, v37
	v_and_b32_e32 v129, 24, v38
	v_lshlrev_b32_e32 v38, 6, v128
	v_lshlrev_b32_e32 v39, 1, v129
	s_movk_i32 s0, 0x3c0
	v_lshlrev_b32_e32 v36, 2, v36
	v_and_or_b32 v68, v38, s0, v39
	v_lshl_or_b32 v37, v37, 6, v39
	v_and_b32_e32 v36, 32, v36
	v_readlane_b32 s0, v254, 9
	v_lshlrev_b32_e32 v38, 2, v128
	v_and_b32_e32 v69, 32, v38
	v_bitop3_b32 v70, v37, s0, v36 bitop3:0xde
	v_add_u32_e32 v233, s78, v70
	s_waitcnt vmcnt(6)
	s_barrier
	v_add_u32_e32 v232, s77, v70
	ds_read_b128 v[36:39], v233 offset:3072
	ds_read_b128 v[40:43], v233 offset:2048
	ds_read_b128 v[44:47], v233 offset:1024
	ds_read_b128 v[48:51], v233
	ds_read_b128 v[52:55], v232 offset:3072
	ds_read_b128 v[56:59], v232 offset:2048
	ds_read_b128 v[60:63], v232 offset:1024
	ds_read_b128 v[64:67], v232
	v_bitop3_b32 v68, v68, s64, v69 bitop3:0xde
	v_add_u32_e32 v242, 0, v68
	v_add_u32_e32 v234, s85, v70
	v_add_u32_e32 v235, s86, v70
	s_add_u32 s0, s10, 0x10080
	s_addc_u32 s1, s11, 0
	s_mov_b32 m0, s79
	v_lshl_add_u64 v[100:101], s[0:1], 0, v[16:17]
	ds_read_b128 v[68:71], v242
	ds_read_b128 v[72:75], v242 offset:1024
	ds_read_b128 v[76:79], v242 offset:2048
	ds_read_b128 v[80:83], v242 offset:3072
	ds_read_b128 v[84:87], v242 offset:4096
	ds_read_b128 v[88:91], v242 offset:5120
	ds_read_b128 v[92:95], v242 offset:6144
	ds_read_b128 v[96:99], v242 offset:7168
	global_load_lds_dwordx4 v[100:101], off
	v_lshl_add_u64 v[100:101], s[0:1], 0, v[26:27]
	s_mov_b32 m0, s80
	s_nop 0
	global_load_lds_dwordx4 v[100:101], off
	s_waitcnt vmcnt(8)
	s_waitcnt lgkmcnt(0)
	s_barrier
	s_waitcnt lgkmcnt(0)
	v_mfma_f32_16x16x32_bf16 v[100:103], v[64:67], v[68:71], 0
	v_mfma_f32_16x16x32_bf16 v[104:107], v[56:59], v[68:71], 0
	v_mfma_f32_16x16x32_bf16 v[108:111], v[64:67], v[76:79], 0
	v_mfma_f32_16x16x32_bf16 v[112:115], v[56:59], v[76:79], 0
	v_mfma_f32_16x16x32_bf16 v[116:119], v[64:67], v[84:87], 0
	v_mfma_f32_16x16x32_bf16 v[120:123], v[56:59], v[84:87], 0
	v_mfma_f32_16x16x32_bf16 v[124:127], v[64:67], v[92:95], 0
	v_mfma_f32_16x16x32_bf16 v[100:103], v[60:63], v[72:75], v[100:103]
	v_mfma_f32_16x16x32_bf16 v[104:107], v[52:55], v[72:75], v[104:107]
	v_mfma_f32_16x16x32_bf16 v[108:111], v[60:63], v[80:83], v[108:111]
	v_mfma_f32_16x16x32_bf16 v[112:115], v[52:55], v[80:83], v[112:115]
	v_mfma_f32_16x16x32_bf16 v[116:119], v[60:63], v[88:91], v[116:119]
	s_setprio 1
	v_mfma_f32_16x16x32_bf16 v[120:123], v[52:55], v[88:91], v[120:123]
	v_mfma_f32_16x16x32_bf16 v[124:127], v[60:63], v[96:99], v[124:127]
	v_mfma_f32_16x16x32_bf16 v[130:133], v[56:59], v[92:95], 0
	v_mfma_f32_16x16x32_bf16 v[130:133], v[52:55], v[96:99], v[130:133]
	s_setprio 0
	s_setprio 1
	v_mfma_f32_16x16x32_bf16 v[134:137], v[48:51], v[68:71], 0
	v_mfma_f32_16x16x32_bf16 v[68:71], v[40:43], v[68:71], 0
	v_mfma_f32_16x16x32_bf16 v[134:137], v[44:47], v[72:75], v[134:137]
	v_mfma_f32_16x16x32_bf16 v[68:71], v[36:39], v[72:75], v[68:71]
	v_mfma_f32_16x16x32_bf16 v[72:75], v[48:51], v[76:79], 0
	v_mfma_f32_16x16x32_bf16 v[76:79], v[40:43], v[76:79], 0
	v_mfma_f32_16x16x32_bf16 v[72:75], v[44:47], v[80:83], v[72:75]
	v_mfma_f32_16x16x32_bf16 v[76:79], v[36:39], v[80:83], v[76:79]
	v_mfma_f32_16x16x32_bf16 v[80:83], v[48:51], v[84:87], 0
	v_mfma_f32_16x16x32_bf16 v[84:87], v[40:43], v[84:87], 0
	s_barrier
	v_mfma_f32_16x16x32_bf16 v[80:83], v[44:47], v[88:91], v[80:83]
	v_mfma_f32_16x16x32_bf16 v[84:87], v[36:39], v[88:91], v[84:87]
	v_mfma_f32_16x16x32_bf16 v[88:91], v[48:51], v[92:95], 0
	v_mfma_f32_16x16x32_bf16 v[92:95], v[40:43], v[92:95], 0
	v_mfma_f32_16x16x32_bf16 v[88:91], v[44:47], v[96:99], v[88:91]
	v_mfma_f32_16x16x32_bf16 v[92:95], v[36:39], v[96:99], v[92:95]
	s_setprio 0
	s_mov_b64 s[0:1], 0x100
	s_mov_b32 m0, s81
	v_lshl_add_u64 v[166:167], v[28:29], 0, s[0:1]
	ds_read_b128 v[96:99], v242 offset:16384
	ds_read_b128 v[138:141], v242 offset:17408
	ds_read_b128 v[142:145], v242 offset:18432
	ds_read_b128 v[146:149], v242 offset:19456
	ds_read_b128 v[150:153], v242 offset:20480
	ds_read_b128 v[154:157], v242 offset:21504
	ds_read_b128 v[158:161], v242 offset:22528
	ds_read_b128 v[162:165], v242 offset:23552
	global_load_lds_dwordx4 v[166:167], off
	v_lshl_add_u64 v[166:167], v[30:31], 0, s[0:1]
	s_mov_b32 m0, s82
	s_nop 0
	global_load_lds_dwordx4 v[166:167], off
	v_lshl_add_u64 v[166:167], s[24:25], 0, v[32:33]
	s_mov_b32 m0, s83
	s_nop 0
	global_load_lds_dwordx4 v[166:167], off
	v_lshl_add_u64 v[166:167], s[24:25], 0, v[34:35]
	s_mov_b32 m0, s84
	s_nop 0
	global_load_lds_dwordx4 v[166:167], off
	v_lshl_add_u64 v[166:167], v[20:21], 0, s[0:1]
	s_mov_b32 m0, s33
	s_nop 0
	global_load_lds_dwordx4 v[166:167], off
	v_lshl_add_u64 v[166:167], v[22:23], 0, s[0:1]
	s_mov_b32 m0, s63
	s_nop 0
	global_load_lds_dwordx4 v[166:167], off
	s_waitcnt vmcnt(8)
	s_waitcnt lgkmcnt(0)
	s_barrier
; #define PG8_STAGE(bufoff, gbase, voff) do { _Pragma("unroll") for (int _i = 0; _i < 2; ++_i) \
;         __builtin_amdgcn_global_load_lds((const unsigned*)((const char*)(gbase) + (voff)[_i]), (PG8_LAS unsigned*)(lds + (bufoff) + ldsw + _i * 8192), 16, 0, 0); } while (0)
; #define PG8_LDA(dst, b, h) do { _Pragma("unroll") for (int m = 0; m < 4; ++m) _Pragma("unroll") for (int k = 0; k < 2; ++k) dst[m][k] = *(const PG8_LAS bf16x8*)(lds + PG8_SA(b, h) + aoff + m * 2048 + k * 1024); } while (0)
; #define PG8_LDB(dst, b, h) do { _Pragma("unroll") for (int n = 0; n < 2; ++n) _Pragma("unroll") for (int k = 0; k < 2; ++k) dst[n][k] = *(const PG8_LAS bf16x8*)(lds + PG8_SB(b, h) + boff + n * 2048 + k * 1024); } while (0)
; #define PG8_MMA(ai, bj, At, Bt) do { __builtin_amdgcn_s_setprio(1); _Pragma("unroll") for (int m = 0; m < 4; ++m) _Pragma("unroll") for (int n = 0; n < 2; ++n) _Pragma("unroll") for (int k = 0; k < 2; ++k) \
;         acc[ai][bj][m][n] = __builtin_amdgcn_mfma_f32_16x16x32_bf16(Bt[n][k], At[m][k], acc[ai][bj][m][n], 0, 0, 0); __builtin_amdgcn_s_setprio(0); } while (0)
; #define PG8_WAIT_V(n) asm volatile("s_waitcnt vmcnt(" #n ")" ::: "memory")
; #define PG8_WAIT_L(n) asm volatile("s_waitcnt lgkmcnt(" #n ")" ::: "memory")
; #define PG8_BAR __builtin_amdgcn_s_barrier()
; #define PG8_SCHED __builtin_amdgcn_sched_barrier(0)
; template <class Epi, class Sched, bool ALIGN_EPI = false, bool SP2 = false>
; __device__ __forceinline__ void gemm_phase(PG8_LAS unsigned char* lds, const Gemm g, const Sched& S, const Epi& E, const int wave_id) {
;     ...
;             PG8_WAIT_V(8); PG8_WAIT_L(0); PG8_BAR; PG8_MMA(1, 0, At, B0); PG8_MMA(1, 1, At, B1); PG8_BAR; PG8_SCHED;
;             PG8_LDB(B0, 1, 0); PG8_LDB(B1, 1, 1); PG8_SCHED; PG8_LDA(At, 1, 0); PG8_STAGE(PG8_SA(0, 1), a2 + hstep, voffA);
;             PG8_WAIT_V(8); PG8_WAIT_L(0); PG8_BAR; PG8_MMA(0, 0, At, B0); PG8_MMA(0, 1, At, B1); PG8_BAR; PG8_SCHED;
	s_waitcnt lgkmcnt(0)
	v_mfma_f32_16x16x32_bf16 v[166:169], v[64:67], v[96:99], 0
	v_mfma_f32_16x16x32_bf16 v[170:173], v[56:59], v[96:99], 0
	v_mfma_f32_16x16x32_bf16 v[174:177], v[64:67], v[142:145], 0
	v_mfma_f32_16x16x32_bf16 v[178:181], v[56:59], v[142:145], 0
	v_mfma_f32_16x16x32_bf16 v[182:185], v[64:67], v[150:153], 0
	v_mfma_f32_16x16x32_bf16 v[186:189], v[56:59], v[150:153], 0
	v_mfma_f32_16x16x32_bf16 v[64:67], v[64:67], v[158:161], 0
	v_mfma_f32_16x16x32_bf16 v[56:59], v[56:59], v[158:161], 0
	v_mfma_f32_16x16x32_bf16 v[166:169], v[60:63], v[138:141], v[166:169]
	v_mfma_f32_16x16x32_bf16 v[170:173], v[52:55], v[138:141], v[170:173]
	v_mfma_f32_16x16x32_bf16 v[174:177], v[60:63], v[146:149], v[174:177]
	v_mfma_f32_16x16x32_bf16 v[178:181], v[52:55], v[146:149], v[178:181]
	s_setprio 1
	v_mfma_f32_16x16x32_bf16 v[182:185], v[60:63], v[154:157], v[182:185]
	v_mfma_f32_16x16x32_bf16 v[186:189], v[52:55], v[154:157], v[186:189]
	v_mfma_f32_16x16x32_bf16 v[60:63], v[60:63], v[162:165], v[64:67]
	v_mfma_f32_16x16x32_bf16 v[52:55], v[52:55], v[162:165], v[56:59]
	s_setprio 0
	s_setprio 1
	v_mfma_f32_16x16x32_bf16 v[56:59], v[48:51], v[96:99], 0
	v_mfma_f32_16x16x32_bf16 v[64:67], v[40:43], v[96:99], 0
	v_mfma_f32_16x16x32_bf16 v[56:59], v[44:47], v[138:141], v[56:59]
	v_mfma_f32_16x16x32_bf16 v[64:67], v[36:39], v[138:141], v[64:67]
	v_mfma_f32_16x16x32_bf16 v[96:99], v[48:51], v[142:145], 0
	v_mfma_f32_16x16x32_bf16 v[138:141], v[40:43], v[142:145], 0
	v_mfma_f32_16x16x32_bf16 v[96:99], v[44:47], v[146:149], v[96:99]
	v_mfma_f32_16x16x32_bf16 v[138:141], v[36:39], v[146:149], v[138:141]
	v_mfma_f32_16x16x32_bf16 v[142:145], v[48:51], v[150:153], 0
	v_mfma_f32_16x16x32_bf16 v[146:149], v[40:43], v[150:153], 0
	s_barrier
	v_mfma_f32_16x16x32_bf16 v[48:51], v[48:51], v[158:161], 0
	v_mfma_f32_16x16x32_bf16 v[40:43], v[40:43], v[158:161], 0
	v_mfma_f32_16x16x32_bf16 v[142:145], v[44:47], v[154:157], v[142:145]
	v_mfma_f32_16x16x32_bf16 v[146:149], v[36:39], v[154:157], v[146:149]
	v_mfma_f32_16x16x32_bf16 v[44:47], v[44:47], v[162:165], v[48:51]
	v_mfma_f32_16x16x32_bf16 v[36:39], v[36:39], v[162:165], v[40:43]
	s_setprio 0
	s_nop 1
	ds_read_b128 v[40:43], v234
	ds_read_b128 v[48:51], v234 offset:1024
	ds_read_b128 v[150:153], v234 offset:2048
	ds_read_b128 v[154:157], v234 offset:3072
	ds_read_b128 v[158:161], v235
	ds_read_b128 v[162:165], v235 offset:1024
	ds_read_b128 v[190:193], v235 offset:2048
	ds_read_b128 v[194:197], v235 offset:3072
	s_add_u32 s0, s10, 0x10100
	s_addc_u32 s1, s11, 0
	s_mov_b32 m0, s69
	v_lshl_add_u64 v[230:231], s[0:1], 0, v[16:17]
	ds_read_b128 v[198:201], v242 offset:32768
	ds_read_b128 v[202:205], v242 offset:33792
	ds_read_b128 v[206:209], v242 offset:34816
	ds_read_b128 v[210:213], v242 offset:35840
	ds_read_b128 v[214:217], v242 offset:36864
	ds_read_b128 v[218:221], v242 offset:37888
	ds_read_b128 v[222:225], v242 offset:38912
	ds_read_b128 v[226:229], v242 offset:39936
	global_load_lds_dwordx4 v[230:231], off
	v_lshl_add_u64 v[230:231], s[0:1], 0, v[26:27]
	s_mov_b32 m0, s70
	s_nop 0
	global_load_lds_dwordx4 v[230:231], off
	s_waitcnt vmcnt(8)
	s_waitcnt lgkmcnt(0)
	s_barrier
	s_waitcnt lgkmcnt(0)
	v_mfma_f32_16x16x32_bf16 v[100:103], v[40:43], v[198:201], v[100:103]
	v_mfma_f32_16x16x32_bf16 v[104:107], v[150:153], v[198:201], v[104:107]
	v_mfma_f32_16x16x32_bf16 v[108:111], v[40:43], v[206:209], v[108:111]
	v_mfma_f32_16x16x32_bf16 v[112:115], v[150:153], v[206:209], v[112:115]
	v_mfma_f32_16x16x32_bf16 v[116:119], v[40:43], v[214:217], v[116:119]
	v_mfma_f32_16x16x32_bf16 v[120:123], v[150:153], v[214:217], v[120:123]
	v_mfma_f32_16x16x32_bf16 v[124:127], v[40:43], v[222:225], v[124:127]
	v_mfma_f32_16x16x32_bf16 v[100:103], v[48:51], v[202:205], v[100:103]
	v_mfma_f32_16x16x32_bf16 v[104:107], v[154:157], v[202:205], v[104:107]
	v_mfma_f32_16x16x32_bf16 v[108:111], v[48:51], v[210:213], v[108:111]
	v_mfma_f32_16x16x32_bf16 v[112:115], v[154:157], v[210:213], v[112:115]
	v_mfma_f32_16x16x32_bf16 v[116:119], v[48:51], v[218:221], v[116:119]
	s_setprio 1
	v_mfma_f32_16x16x32_bf16 v[120:123], v[154:157], v[218:221], v[120:123]
	v_mfma_f32_16x16x32_bf16 v[124:127], v[48:51], v[226:229], v[124:127]
	v_mfma_f32_16x16x32_bf16 v[130:133], v[150:153], v[222:225], v[130:133]
	v_mfma_f32_16x16x32_bf16 v[130:133], v[154:157], v[226:229], v[130:133]
	s_setprio 0
	s_setprio 1
	v_mfma_f32_16x16x32_bf16 v[68:71], v[190:193], v[198:201], v[68:71]
	v_mfma_f32_16x16x32_bf16 v[72:75], v[158:161], v[206:209], v[72:75]
	v_mfma_f32_16x16x32_bf16 v[76:79], v[190:193], v[206:209], v[76:79]
	v_mfma_f32_16x16x32_bf16 v[80:83], v[158:161], v[214:217], v[80:83]
	v_mfma_f32_16x16x32_bf16 v[84:87], v[190:193], v[214:217], v[84:87]
	v_mfma_f32_16x16x32_bf16 v[88:91], v[158:161], v[222:225], v[88:91]
	v_mfma_f32_16x16x32_bf16 v[92:95], v[190:193], v[222:225], v[92:95]
	v_mfma_f32_16x16x32_bf16 v[134:137], v[158:161], v[198:201], v[134:137]
	v_mfma_f32_16x16x32_bf16 v[68:71], v[194:197], v[202:205], v[68:71]
	v_mfma_f32_16x16x32_bf16 v[72:75], v[162:165], v[210:213], v[72:75]
	s_barrier
; #define PG8_STAGE(bufoff, gbase, voff) do { _Pragma("unroll") for (int _i = 0; _i < 2; ++_i) \
;         __builtin_amdgcn_global_load_lds((const unsigned*)((const char*)(gbase) + (voff)[_i]), (PG8_LAS unsigned*)(lds + (bufoff) + ldsw + _i * 8192), 16, 0, 0); } while (0)
; #define PG8_LDA(dst, b, h) do { _Pragma("unroll") for (int m = 0; m < 4; ++m) _Pragma("unroll") for (int k = 0; k < 2; ++k) dst[m][k] = *(const PG8_LAS bf16x8*)(lds + PG8_SA(b, h) + aoff + m * 2048 + k * 1024); } while (0)
; #define PG8_LDB(dst, b, h) do { _Pragma("unroll") for (int n = 0; n < 2; ++n) _Pragma("unroll") for (int k = 0; k < 2; ++k) dst[n][k] = *(const PG8_LAS bf16x8*)(lds + PG8_SB(b, h) + boff + n * 2048 + k * 1024); } while (0)
; #define PG8_MMA(ai, bj, At, Bt) do { __builtin_amdgcn_s_setprio(1); _Pragma("unroll") for (int m = 0; m < 4; ++m) _Pragma("unroll") for (int n = 0; n < 2; ++n) _Pragma("unroll") for (int k = 0; k < 2; ++k) \
;         acc[ai][bj][m][n] = __builtin_amdgcn_mfma_f32_16x16x32_bf16(Bt[n][k], At[m][k], acc[ai][bj][m][n], 0, 0, 0); __builtin_amdgcn_s_setprio(0); } while (0)
; #define PG8_WAIT_V(n) asm volatile("s_waitcnt vmcnt(" #n ")" ::: "memory")
; #define PG8_WAIT_L(n) asm volatile("s_waitcnt lgkmcnt(" #n ")" ::: "memory")
; #define PG8_BAR __builtin_amdgcn_s_barrier()
; #define PG8_SCHED __builtin_amdgcn_sched_barrier(0)
; template <class Epi, class Sched, bool ALIGN_EPI = false, bool SP2 = false>
; __device__ __forceinline__ void gemm_phase(PG8_LAS unsigned char* lds, const Gemm g, const Sched& S, const Epi& E, const int wave_id) {
;     ...
;             PG8_LDB(B0, 0, 0); PG8_LDB(B1, 0, 1); PG8_SCHED; PG8_LDA(At, 0, 0); PG8_STAGE(PG8_SA(1, 1), a1 + hstep, voffA);
;     ...
;             PG8_WAIT_V(8); PG8_WAIT_L(0); PG8_BAR; PG8_MMA(0, 0, At, B0); PG8_MMA(0, 1, At, B1); PG8_BAR; PG8_SCHED;
;             PG8_LDA(At, 1, 1); PG8_STAGE(PG8_SB(1, 0), b3, voffB); PG8_STAGE(PG8_SB(1, 1), b3 + hstep, voffB); PG8_STAGE(PG8_SA(1, 0), a3, voffA);
;             PG8_WAIT_V(8); PG8_WAIT_L(0); PG8_BAR; PG8_MMA(1, 0, At, B0); PG8_MMA(1, 1, At, B1); PG8_BAR; PG8_SCHED;
	v_mfma_f32_16x16x32_bf16 v[76:79], v[194:197], v[210:213], v[76:79]
	v_mfma_f32_16x16x32_bf16 v[80:83], v[162:165], v[218:221], v[80:83]
	v_mfma_f32_16x16x32_bf16 v[84:87], v[194:197], v[218:221], v[84:87]
	v_mfma_f32_16x16x32_bf16 v[88:91], v[162:165], v[226:229], v[88:91]
	v_mfma_f32_16x16x32_bf16 v[92:95], v[194:197], v[226:229], v[92:95]
	v_mfma_f32_16x16x32_bf16 v[134:137], v[162:165], v[202:205], v[134:137]
	s_setprio 0
	s_mov_b64 s[0:1], 0x180
	s_mov_b32 m0, s87
	v_lshl_add_u64 v[230:231], v[28:29], 0, s[0:1]
	ds_read_b128 v[198:201], v242 offset:49152
	ds_read_b128 v[202:205], v242 offset:50176
	ds_read_b128 v[206:209], v242 offset:51200
	ds_read_b128 v[210:213], v242 offset:52224
	ds_read_b128 v[214:217], v242 offset:53248
	ds_read_b128 v[218:221], v242 offset:54272
	ds_read_b128 v[222:225], v242 offset:55296
	ds_read_b128 v[226:229], v242 offset:56320
	global_load_lds_dwordx4 v[230:231], off
	v_lshl_add_u64 v[230:231], v[30:31], 0, s[0:1]
	s_mov_b32 m0, s88
	v_lshl_add_u64 v[32:33], s[26:27], 0, v[32:33]
	global_load_lds_dwordx4 v[230:231], off
	s_mov_b32 m0, s89
	s_nop 0
	global_load_lds_dwordx4 v[32:33], off
	v_lshl_add_u64 v[32:33], s[26:27], 0, v[34:35]
	s_mov_b32 m0, s90
	s_nop 0
	global_load_lds_dwordx4 v[32:33], off
	v_lshl_add_u64 v[32:33], v[20:21], 0, s[0:1]
	s_mov_b32 m0, s73
	s_nop 0
	global_load_lds_dwordx4 v[32:33], off
	v_lshl_add_u64 v[32:33], v[22:23], 0, s[0:1]
	s_mov_b32 m0, s74
	s_nop 0
	global_load_lds_dwordx4 v[32:33], off
	s_waitcnt vmcnt(8)
	s_waitcnt lgkmcnt(0)
	s_barrier
	s_waitcnt lgkmcnt(0)
	v_mfma_f32_16x16x32_bf16 v[32:35], v[40:43], v[198:201], v[166:169]
	v_mfma_f32_16x16x32_bf16 v[166:169], v[150:153], v[198:201], v[170:173]
	v_mfma_f32_16x16x32_bf16 v[170:173], v[40:43], v[206:209], v[174:177]
	v_mfma_f32_16x16x32_bf16 v[174:177], v[150:153], v[206:209], v[178:181]
	v_mfma_f32_16x16x32_bf16 v[178:181], v[40:43], v[214:217], v[182:185]
	v_mfma_f32_16x16x32_bf16 v[40:43], v[40:43], v[222:225], v[60:63]
	v_mfma_f32_16x16x32_bf16 v[32:35], v[48:51], v[202:205], v[32:35]
	v_mfma_f32_16x16x32_bf16 v[170:173], v[48:51], v[210:213], v[170:173]
	v_mfma_f32_16x16x32_bf16 v[178:181], v[48:51], v[218:221], v[178:181]
	v_mfma_f32_16x16x32_bf16 v[40:43], v[48:51], v[226:229], v[40:43]
	v_mfma_f32_16x16x32_bf16 v[48:51], v[150:153], v[222:225], v[52:55]
	v_mfma_f32_16x16x32_bf16 v[182:185], v[150:153], v[214:217], v[186:189]
	s_setprio 1
	v_mfma_f32_16x16x32_bf16 v[48:51], v[154:157], v[226:229], v[48:51]
	v_mfma_f32_16x16x32_bf16 v[166:169], v[154:157], v[202:205], v[166:169]
	v_mfma_f32_16x16x32_bf16 v[174:177], v[154:157], v[210:213], v[174:177]
	v_mfma_f32_16x16x32_bf16 v[182:185], v[154:157], v[218:221], v[182:185]
	s_setprio 0
	s_setprio 1
	v_mfma_f32_16x16x32_bf16 v[52:55], v[158:161], v[198:201], v[56:59]
	v_mfma_f32_16x16x32_bf16 v[56:59], v[190:193], v[198:201], v[64:67]
	v_mfma_f32_16x16x32_bf16 v[60:63], v[158:161], v[206:209], v[96:99]
	v_mfma_f32_16x16x32_bf16 v[64:67], v[190:193], v[206:209], v[138:141]
	v_mfma_f32_16x16x32_bf16 v[96:99], v[158:161], v[214:217], v[142:145]
	v_mfma_f32_16x16x32_bf16 v[44:47], v[158:161], v[222:225], v[44:47]
	v_mfma_f32_16x16x32_bf16 v[36:39], v[190:193], v[222:225], v[36:39]
	v_mfma_f32_16x16x32_bf16 v[52:55], v[162:165], v[202:205], v[52:55]
	v_mfma_f32_16x16x32_bf16 v[56:59], v[194:197], v[202:205], v[56:59]
	v_mfma_f32_16x16x32_bf16 v[60:63], v[162:165], v[210:213], v[60:63]
	s_barrier
	v_mfma_f32_16x16x32_bf16 v[64:67], v[194:197], v[210:213], v[64:67]
	v_mfma_f32_16x16x32_bf16 v[96:99], v[162:165], v[218:221], v[96:99]
	v_mfma_f32_16x16x32_bf16 v[138:141], v[190:193], v[214:217], v[146:149]
	v_mfma_f32_16x16x32_bf16 v[44:47], v[162:165], v[226:229], v[44:47]
	v_mfma_f32_16x16x32_bf16 v[36:39], v[194:197], v[226:229], v[36:39]
	v_mfma_f32_16x16x32_bf16 v[138:141], v[194:197], v[218:221], v[138:141]
	s_setprio 0
	ds_read_b128 v[142:145], v232
	ds_read_b128 v[146:149], v232 offset:1024
	ds_read_b128 v[150:153], v232 offset:2048
	ds_read_b128 v[154:157], v232 offset:3072
	ds_read_b128 v[158:161], v233
	ds_read_b128 v[162:165], v233 offset:1024
	ds_read_b128 v[186:189], v233 offset:2048
	ds_read_b128 v[190:193], v233 offset:3072
	s_add_u32 s0, s10, 0x10180
	s_addc_u32 s1, s11, 0
	s_mov_b32 m0, s79
	v_lshl_add_u64 v[16:17], s[0:1], 0, v[16:17]
	ds_read_b128 v[194:197], v242
	ds_read_b128 v[198:201], v242 offset:1024
	ds_read_b128 v[202:205], v242 offset:2048
	ds_read_b128 v[206:209], v242 offset:3072
	ds_read_b128 v[210:213], v242 offset:4096
	ds_read_b128 v[214:217], v242 offset:5120
	ds_read_b128 v[218:221], v242 offset:6144
	ds_read_b128 v[222:225], v242 offset:7168
	global_load_lds_dwordx4 v[16:17], off
	v_lshl_add_u64 v[16:17], s[0:1], 0, v[26:27]
	s_mov_b32 m0, s80
	s_nop 0
	global_load_lds_dwordx4 v[16:17], off
	s_waitcnt vmcnt(8)
	s_waitcnt lgkmcnt(0)
	s_barrier
; #define PG8_STAGE(bufoff, gbase, voff) do { _Pragma("unroll") for (int _i = 0; _i < 2; ++_i) \
;         __builtin_amdgcn_global_load_lds((const unsigned*)((const char*)(gbase) + (voff)[_i]), (PG8_LAS unsigned*)(lds + (bufoff) + ldsw + _i * 8192), 16, 0, 0); } while (0)
; #define PG8_LDA(dst, b, h) do { _Pragma("unroll") for (int m = 0; m < 4; ++m) _Pragma("unroll") for (int k = 0; k < 2; ++k) dst[m][k] = *(const PG8_LAS bf16x8*)(lds + PG8_SA(b, h) + aoff + m * 2048 + k * 1024); } while (0)
; #define PG8_LDB(dst, b, h) do { _Pragma("unroll") for (int n = 0; n < 2; ++n) _Pragma("unroll") for (int k = 0; k < 2; ++k) dst[n][k] = *(const PG8_LAS bf16x8*)(lds + PG8_SB(b, h) + boff + n * 2048 + k * 1024); } while (0)
; #define PG8_MMA(ai, bj, At, Bt) do { __builtin_amdgcn_s_setprio(1); _Pragma("unroll") for (int m = 0; m < 4; ++m) _Pragma("unroll") for (int n = 0; n < 2; ++n) _Pragma("unroll") for (int k = 0; k < 2; ++k) \
;         acc[ai][bj][m][n] = __builtin_amdgcn_mfma_f32_16x16x32_bf16(Bt[n][k], At[m][k], acc[ai][bj][m][n], 0, 0, 0); __builtin_amdgcn_s_setprio(0); } while (0)
; #define PG8_WAIT_V(n) asm volatile("s_waitcnt vmcnt(" #n ")" ::: "memory")
; #define PG8_WAIT_L(n) asm volatile("s_waitcnt lgkmcnt(" #n ")" ::: "memory")
; #define PG8_BAR __builtin_amdgcn_s_barrier()
; #define PG8_SCHED __builtin_amdgcn_sched_barrier(0)
; template <class Epi, class Sched, bool ALIGN_EPI = false, bool SP2 = false>
; __device__ __forceinline__ void gemm_phase(PG8_LAS unsigned char* lds, const Gemm g, const Sched& S, const Epi& E, const int wave_id) {
;     ...
;             PG8_LDB(B0, 0, 0); PG8_LDB(B1, 0, 1); PG8_SCHED; PG8_LDA(At, 0, 0); PG8_STAGE(PG8_SA(1, 1), a1 + hstep, voffA);
;             PG8_WAIT_V(8); PG8_WAIT_L(0); PG8_BAR; PG8_MMA(0, 0, At, B0); PG8_MMA(0, 1, At, B1); PG8_BAR; PG8_SCHED;
;             PG8_LDA(At, 0, 1); PG8_STAGE(PG8_SB(0, 0), b2, voffB); PG8_STAGE(PG8_SB(0, 1), b2 + hstep, voffB); PG8_STAGE(PG8_SA(0, 0), a2, voffA);
;             PG8_WAIT_V(8); PG8_WAIT_L(0); PG8_BAR; PG8_MMA(1, 0, At, B0); PG8_MMA(1, 1, At, B1); PG8_BAR; PG8_SCHED;
	s_waitcnt lgkmcnt(0)
	v_mfma_f32_16x16x32_bf16 v[112:115], v[150:153], v[202:205], v[112:115]
	v_mfma_f32_16x16x32_bf16 v[226:229], v[154:157], v[206:209], v[112:115]
	v_mfma_f32_16x16x32_bf16 v[112:115], v[142:145], v[210:213], v[116:119]
	v_mfma_f32_16x16x32_bf16 v[116:119], v[146:149], v[214:217], v[112:115]
	v_mfma_f32_16x16x32_bf16 v[112:115], v[150:153], v[210:213], v[120:123]
	v_mfma_f32_16x16x32_bf16 v[100:103], v[142:145], v[194:197], v[100:103]
	v_mfma_f32_16x16x32_bf16 v[104:107], v[150:153], v[194:197], v[104:107]
	v_mfma_f32_16x16x32_bf16 v[108:111], v[142:145], v[202:205], v[108:111]
	v_mfma_f32_16x16x32_bf16 v[230:233], v[154:157], v[214:217], v[112:115]
	v_mfma_f32_16x16x32_bf16 v[112:115], v[142:145], v[218:221], v[124:127]
	v_mfma_f32_16x16x32_bf16 v[100:103], v[146:149], v[198:201], v[100:103]
	v_mfma_f32_16x16x32_bf16 v[104:107], v[154:157], v[198:201], v[104:107]
	s_setprio 1
	v_mfma_f32_16x16x32_bf16 v[108:111], v[146:149], v[206:209], v[108:111]
	v_mfma_f32_16x16x32_bf16 v[124:127], v[146:149], v[222:225], v[112:115]
	v_mfma_f32_16x16x32_bf16 v[112:115], v[150:153], v[218:221], v[130:133]
	v_mfma_f32_16x16x32_bf16 v[130:133], v[154:157], v[222:225], v[112:115]
	s_setprio 0
	s_setprio 1
	v_mfma_f32_16x16x32_bf16 v[80:83], v[158:161], v[210:213], v[80:83]
	v_mfma_f32_16x16x32_bf16 v[112:115], v[158:161], v[194:197], v[134:137]
	v_mfma_f32_16x16x32_bf16 v[68:71], v[186:189], v[194:197], v[68:71]
	v_mfma_f32_16x16x32_bf16 v[194:197], v[162:165], v[214:217], v[80:83]
	v_mfma_f32_16x16x32_bf16 v[80:83], v[186:189], v[210:213], v[84:87]
	v_mfma_f32_16x16x32_bf16 v[72:75], v[158:161], v[202:205], v[72:75]
	v_mfma_f32_16x16x32_bf16 v[76:79], v[186:189], v[202:205], v[76:79]
	v_mfma_f32_16x16x32_bf16 v[84:87], v[190:193], v[214:217], v[80:83]
	v_mfma_f32_16x16x32_bf16 v[80:83], v[158:161], v[218:221], v[88:91]
	v_mfma_f32_16x16x32_bf16 v[134:137], v[162:165], v[198:201], v[112:115]
	s_barrier
	v_mfma_f32_16x16x32_bf16 v[68:71], v[190:193], v[198:201], v[68:71]
	v_mfma_f32_16x16x32_bf16 v[72:75], v[162:165], v[206:209], v[72:75]
	v_mfma_f32_16x16x32_bf16 v[76:79], v[190:193], v[206:209], v[76:79]
	v_mfma_f32_16x16x32_bf16 v[198:201], v[162:165], v[222:225], v[80:83]
	v_mfma_f32_16x16x32_bf16 v[80:83], v[186:189], v[218:221], v[92:95]
	v_mfma_f32_16x16x32_bf16 v[202:205], v[190:193], v[222:225], v[80:83]
	s_setprio 0
	s_mov_b32 m0, s81
	s_nop 3
	ds_read_b128 v[80:83], v242 offset:16384
	ds_read_b128 v[88:91], v242 offset:17408
	ds_read_b128 v[92:95], v242 offset:18432
	ds_read_b128 v[112:115], v242 offset:19456
	ds_read_b128 v[120:123], v242 offset:20480
	ds_read_b128 v[206:209], v242 offset:21504
	ds_read_b128 v[210:213], v242 offset:22528
	ds_read_b128 v[214:217], v242 offset:23552
	global_load_lds_dwordx4 v[28:29], off
	s_mov_b32 m0, s82
	s_nop 0
	global_load_lds_dwordx4 v[30:31], off
	s_mov_b32 m0, s83
	s_nop 0
	global_load_lds_dwordx4 v[24:25], off
	s_mov_b32 m0, s84
	s_nop 0
	global_load_lds_dwordx4 v[18:19], off
	s_mov_b32 m0, s33
	s_nop 0
	global_load_lds_dwordx4 v[20:21], off
	s_mov_b32 m0, s63
	s_nop 0
	global_load_lds_dwordx4 v[22:23], off
	s_waitcnt vmcnt(8)
	s_waitcnt lgkmcnt(0)
	s_barrier
	s_waitcnt lgkmcnt(0)
	v_mfma_f32_16x16x32_bf16 v[16:19], v[142:145], v[80:83], v[32:35]
	v_mfma_f32_16x16x32_bf16 v[20:23], v[150:153], v[80:83], v[166:169]
	v_mfma_f32_16x16x32_bf16 v[24:27], v[142:145], v[92:95], v[170:173]
	v_mfma_f32_16x16x32_bf16 v[28:31], v[150:153], v[92:95], v[174:177]
	v_mfma_f32_16x16x32_bf16 v[32:35], v[142:145], v[120:123], v[178:181]
	v_mfma_f32_16x16x32_bf16 v[40:43], v[142:145], v[210:213], v[40:43]
	v_mfma_f32_16x16x32_bf16 v[16:19], v[146:149], v[88:91], v[16:19]
	v_mfma_f32_16x16x32_bf16 v[20:23], v[154:157], v[88:91], v[20:23]
	v_mfma_f32_16x16x32_bf16 v[24:27], v[146:149], v[112:115], v[24:27]
	v_mfma_f32_16x16x32_bf16 v[28:31], v[154:157], v[112:115], v[28:31]
	v_mfma_f32_16x16x32_bf16 v[32:35], v[146:149], v[206:209], v[32:35]
	v_mfma_f32_16x16x32_bf16 v[166:169], v[150:153], v[120:123], v[182:185]
	s_setprio 1
	v_mfma_f32_16x16x32_bf16 v[40:43], v[146:149], v[214:217], v[40:43]
	v_mfma_f32_16x16x32_bf16 v[48:51], v[150:153], v[210:213], v[48:51]
	v_mfma_f32_16x16x32_bf16 v[166:169], v[154:157], v[206:209], v[166:169]
	v_mfma_f32_16x16x32_bf16 v[142:145], v[154:157], v[214:217], v[48:51]
	s_setprio 0
	s_setprio 1
	v_mfma_f32_16x16x32_bf16 v[48:51], v[158:161], v[80:83], v[52:55]
	v_mfma_f32_16x16x32_bf16 v[146:149], v[162:165], v[88:91], v[48:51]
	v_mfma_f32_16x16x32_bf16 v[48:51], v[186:189], v[80:83], v[56:59]
	v_mfma_f32_16x16x32_bf16 v[150:153], v[190:193], v[88:91], v[48:51]
	v_mfma_f32_16x16x32_bf16 v[48:51], v[158:161], v[92:95], v[60:63]
	v_mfma_f32_16x16x32_bf16 v[154:157], v[162:165], v[112:115], v[48:51]
	v_mfma_f32_16x16x32_bf16 v[48:51], v[186:189], v[92:95], v[64:67]
	v_mfma_f32_16x16x32_bf16 v[170:173], v[190:193], v[112:115], v[48:51]
	v_mfma_f32_16x16x32_bf16 v[48:51], v[158:161], v[120:123], v[96:99]
	v_mfma_f32_16x16x32_bf16 v[174:177], v[162:165], v[206:209], v[48:51]
	s_barrier
; #define PG8_STAGE(bufoff, gbase, voff) do { _Pragma("unroll") for (int _i = 0; _i < 2; ++_i) \
;         __builtin_amdgcn_global_load_lds((const unsigned*)((const char*)(gbase) + (voff)[_i]), (PG8_LAS unsigned*)(lds + (bufoff) + ldsw + _i * 8192), 16, 0, 0); } while (0)
; #define PG8_LDA(dst, b, h) do { _Pragma("unroll") for (int m = 0; m < 4; ++m) _Pragma("unroll") for (int k = 0; k < 2; ++k) dst[m][k] = *(const PG8_LAS bf16x8*)(lds + PG8_SA(b, h) + aoff + m * 2048 + k * 1024); } while (0)
; #define PG8_LDB(dst, b, h) do { _Pragma("unroll") for (int n = 0; n < 2; ++n) _Pragma("unroll") for (int k = 0; k < 2; ++k) dst[n][k] = *(const PG8_LAS bf16x8*)(lds + PG8_SB(b, h) + boff + n * 2048 + k * 1024); } while (0)
; #define PG8_MMA(ai, bj, At, Bt) do { __builtin_amdgcn_s_setprio(1); _Pragma("unroll") for (int m = 0; m < 4; ++m) _Pragma("unroll") for (int n = 0; n < 2; ++n) _Pragma("unroll") for (int k = 0; k < 2; ++k) \
;         acc[ai][bj][m][n] = __builtin_amdgcn_mfma_f32_16x16x32_bf16(Bt[n][k], At[m][k], acc[ai][bj][m][n], 0, 0, 0); __builtin_amdgcn_s_setprio(0); } while (0)
; #define PG8_WAIT_V(n) asm volatile("s_waitcnt vmcnt(" #n ")" ::: "memory")
; #define PG8_WAIT_L(n) asm volatile("s_waitcnt lgkmcnt(" #n ")" ::: "memory")
; #define PG8_BAR __builtin_amdgcn_s_barrier()
; #define PG8_SCHED __builtin_amdgcn_sched_barrier(0)
; template <class Epi, class Sched, bool ALIGN_EPI = false, bool SP2 = false>
; __device__ __forceinline__ void gemm_phase(PG8_LAS unsigned char* lds, const Gemm g, const Sched& S, const Epi& E, const int wave_id) {
;     ...
;             PG8_LDB(B0, 1, 0); PG8_LDB(B1, 1, 1); PG8_SCHED; PG8_LDA(At, 1, 0); PG8_STAGE(PG8_SA(0, 1), a2 + hstep, voffA);
;             PG8_WAIT_V(8); PG8_WAIT_L(0); PG8_BAR; PG8_MMA(0, 0, At, B0); PG8_MMA(0, 1, At, B1); PG8_BAR; PG8_SCHED;
;             PG8_LDA(At, 1, 1); PG8_STAGE(PG8_SB(1, 0), b3, voffB); PG8_STAGE(PG8_SB(1, 1), b3 + hstep, voffB); PG8_STAGE(PG8_SA(1, 0), a3, voffA);
;             PG8_WAIT_V(8); PG8_WAIT_L(0); PG8_BAR; PG8_MMA(1, 0, At, B0); PG8_MMA(1, 1, At, B1); PG8_BAR; PG8_SCHED;
;     ...
;         if constexpr (ALIGN_EPI) { if (wr == 0) PG8_BAR; }
	v_mfma_f32_16x16x32_bf16 v[48:51], v[186:189], v[120:123], v[138:141]
	v_mfma_f32_16x16x32_bf16 v[44:47], v[158:161], v[210:213], v[44:47]
	v_mfma_f32_16x16x32_bf16 v[36:39], v[186:189], v[210:213], v[36:39]
	v_mfma_f32_16x16x32_bf16 v[138:141], v[190:193], v[206:209], v[48:51]
	v_mfma_f32_16x16x32_bf16 v[158:161], v[162:165], v[214:217], v[44:47]
	v_mfma_f32_16x16x32_bf16 v[162:165], v[190:193], v[214:217], v[36:39]
	s_setprio 0
	ds_read_b128 v[64:67], v234
	ds_read_b128 v[178:181], v234 offset:1024
	ds_read_b128 v[182:185], v234 offset:2048
	ds_read_b128 v[186:189], v234 offset:3072
	ds_read_b128 v[190:193], v235
	ds_read_b128 v[206:209], v235 offset:1024
	ds_read_b128 v[210:213], v235 offset:2048
	ds_read_b128 v[214:217], v235 offset:3072
	s_mov_b32 m0, s69
	ds_read_b128 v[36:39], v242 offset:32768
	ds_read_b128 v[44:47], v242 offset:33792
	ds_read_b128 v[52:55], v242 offset:34816
	ds_read_b128 v[60:63], v242 offset:35840
	ds_read_b128 v[218:221], v242 offset:36864
	ds_read_b128 v[222:225], v242 offset:37888
	ds_read_b128 v[234:237], v242 offset:38912
	ds_read_b128 v[238:241], v242 offset:39936
	global_load_lds_dwordx4 v[12:13], off
	s_mov_b32 m0, s70
	s_nop 0
	global_load_lds_dwordx4 v[14:15], off
	s_waitcnt vmcnt(8)
	s_waitcnt lgkmcnt(0)
	s_barrier
	s_waitcnt lgkmcnt(0)
	v_mfma_f32_16x16x32_bf16 v[12:15], v[64:67], v[36:39], v[100:103]
	v_mfma_f32_16x16x32_bf16 v[120:123], v[178:181], v[44:47], v[12:15]
	v_mfma_f32_16x16x32_bf16 v[12:15], v[182:185], v[36:39], v[104:107]
	v_mfma_f32_16x16x32_bf16 v[112:115], v[186:189], v[44:47], v[12:15]
	v_mfma_f32_16x16x32_bf16 v[12:15], v[64:67], v[52:55], v[108:111]
	v_mfma_f32_16x16x32_bf16 v[104:107], v[178:181], v[60:63], v[12:15]
	v_mfma_f32_16x16x32_bf16 v[12:15], v[182:185], v[52:55], v[226:229]
	v_mfma_f32_16x16x32_bf16 v[96:99], v[186:189], v[60:63], v[12:15]
	v_mfma_f32_16x16x32_bf16 v[12:15], v[64:67], v[218:221], v[116:119]
	v_mfma_f32_16x16x32_bf16 v[88:91], v[178:181], v[222:225], v[12:15]
	v_mfma_f32_16x16x32_bf16 v[12:15], v[182:185], v[218:221], v[230:233]
	v_mfma_f32_16x16x32_bf16 v[80:83], v[186:189], v[222:225], v[12:15]
	s_setprio 1
	v_mfma_f32_16x16x32_bf16 v[12:15], v[64:67], v[234:237], v[124:127]
	v_mfma_f32_16x16x32_bf16 v[56:59], v[178:181], v[238:241], v[12:15]
	v_mfma_f32_16x16x32_bf16 v[12:15], v[182:185], v[234:237], v[130:133]
	v_mfma_f32_16x16x32_bf16 v[48:51], v[186:189], v[238:241], v[12:15]
	s_setprio 0
	s_setprio 1
	v_mfma_f32_16x16x32_bf16 v[12:15], v[190:193], v[36:39], v[134:137]
	v_mfma_f32_16x16x32_bf16 v[124:127], v[206:209], v[44:47], v[12:15]
	v_mfma_f32_16x16x32_bf16 v[12:15], v[210:213], v[36:39], v[68:71]
	v_mfma_f32_16x16x32_bf16 v[116:119], v[214:217], v[44:47], v[12:15]
	v_mfma_f32_16x16x32_bf16 v[12:15], v[190:193], v[52:55], v[72:75]
	v_mfma_f32_16x16x32_bf16 v[108:111], v[206:209], v[60:63], v[12:15]
	v_mfma_f32_16x16x32_bf16 v[12:15], v[210:213], v[52:55], v[76:79]
	v_mfma_f32_16x16x32_bf16 v[100:103], v[214:217], v[60:63], v[12:15]
	v_mfma_f32_16x16x32_bf16 v[12:15], v[190:193], v[218:221], v[194:197]
	v_mfma_f32_16x16x32_bf16 v[92:95], v[206:209], v[222:225], v[12:15]
	s_barrier
	v_mfma_f32_16x16x32_bf16 v[12:15], v[210:213], v[218:221], v[84:87]
	v_mfma_f32_16x16x32_bf16 v[84:87], v[214:217], v[222:225], v[12:15]
	v_mfma_f32_16x16x32_bf16 v[12:15], v[190:193], v[234:237], v[198:201]
	v_mfma_f32_16x16x32_bf16 v[60:63], v[206:209], v[238:241], v[12:15]
	v_mfma_f32_16x16x32_bf16 v[12:15], v[210:213], v[234:237], v[202:205]
	v_mfma_f32_16x16x32_bf16 v[52:55], v[214:217], v[238:241], v[12:15]
	s_setprio 0
	s_mov_b32 m0, s87
	ds_read_b128 v[130:133], v242 offset:49152
	ds_read_b128 v[134:137], v242 offset:50176
	ds_read_b128 v[194:197], v242 offset:51200
	ds_read_b128 v[198:201], v242 offset:52224
	ds_read_b128 v[202:205], v242 offset:53248
	ds_read_b128 v[218:221], v242 offset:54272
	ds_read_b128 v[222:225], v242 offset:55296
	ds_read_b128 v[226:229], v242 offset:56320
	global_load_lds_dwordx4 v[4:5], off
	s_mov_b32 m0, s88
	s_nop 0
	global_load_lds_dwordx4 v[6:7], off
	s_mov_b32 m0, s89
	s_nop 0
	global_load_lds_dwordx4 v[8:9], off
	s_mov_b32 m0, s90
	s_nop 0
	global_load_lds_dwordx4 v[10:11], off
	s_mov_b32 m0, s73
	s_nop 0
	global_load_lds_dwordx4 v[0:1], off
	s_mov_b32 m0, s74
	s_nop 0
	global_load_lds_dwordx4 v[2:3], off
	s_waitcnt vmcnt(8)
	s_waitcnt lgkmcnt(0)
	s_barrier
	s_waitcnt lgkmcnt(0)
	v_mfma_f32_16x16x32_bf16 v[0:3], v[64:67], v[130:133], v[16:19]
	v_mfma_f32_16x16x32_bf16 v[76:79], v[178:181], v[134:137], v[0:3]
	v_mfma_f32_16x16x32_bf16 v[0:3], v[182:185], v[130:133], v[20:23]
	v_mfma_f32_16x16x32_bf16 v[72:75], v[186:189], v[134:137], v[0:3]
	v_mfma_f32_16x16x32_bf16 v[0:3], v[64:67], v[194:197], v[24:27]
	v_mfma_f32_16x16x32_bf16 v[44:47], v[178:181], v[198:201], v[0:3]
	v_mfma_f32_16x16x32_bf16 v[0:3], v[182:185], v[194:197], v[28:31]
	v_mfma_f32_16x16x32_bf16 v[36:39], v[186:189], v[198:201], v[0:3]
	v_mfma_f32_16x16x32_bf16 v[0:3], v[64:67], v[202:205], v[32:35]
	v_mfma_f32_16x16x32_bf16 v[28:31], v[178:181], v[218:221], v[0:3]
	v_mfma_f32_16x16x32_bf16 v[0:3], v[182:185], v[202:205], v[166:169]
	v_mfma_f32_16x16x32_bf16 v[20:23], v[186:189], v[218:221], v[0:3]
	s_setprio 1
	v_mfma_f32_16x16x32_bf16 v[0:3], v[64:67], v[222:225], v[40:43]
	v_mfma_f32_16x16x32_bf16 v[12:15], v[178:181], v[226:229], v[0:3]
	v_mfma_f32_16x16x32_bf16 v[0:3], v[182:185], v[222:225], v[142:145]
	v_mfma_f32_16x16x32_bf16 v[4:7], v[186:189], v[226:229], v[0:3]
	s_setprio 0
	s_setprio 1
	v_mfma_f32_16x16x32_bf16 v[0:3], v[190:193], v[130:133], v[146:149]
	v_mfma_f32_16x16x32_bf16 v[68:71], v[206:209], v[134:137], v[0:3]
	v_mfma_f32_16x16x32_bf16 v[0:3], v[210:213], v[130:133], v[150:153]
	v_mfma_f32_16x16x32_bf16 v[64:67], v[214:217], v[134:137], v[0:3]
	v_mfma_f32_16x16x32_bf16 v[0:3], v[190:193], v[194:197], v[154:157]
	v_mfma_f32_16x16x32_bf16 v[40:43], v[206:209], v[198:201], v[0:3]
	v_mfma_f32_16x16x32_bf16 v[0:3], v[210:213], v[194:197], v[170:173]
	v_mfma_f32_16x16x32_bf16 v[32:35], v[214:217], v[198:201], v[0:3]
	v_mfma_f32_16x16x32_bf16 v[0:3], v[190:193], v[202:205], v[174:177]
	v_mfma_f32_16x16x32_bf16 v[24:27], v[206:209], v[218:221], v[0:3]
	s_barrier
	v_mfma_f32_16x16x32_bf16 v[0:3], v[210:213], v[202:205], v[138:141]
	v_mfma_f32_16x16x32_bf16 v[16:19], v[214:217], v[218:221], v[0:3]
	v_mfma_f32_16x16x32_bf16 v[0:3], v[190:193], v[222:225], v[158:161]
	v_mfma_f32_16x16x32_bf16 v[8:11], v[206:209], v[226:229], v[0:3]
	v_mfma_f32_16x16x32_bf16 v[0:3], v[210:213], v[222:225], v[162:165]
	v_mfma_f32_16x16x32_bf16 v[0:3], v[214:217], v[226:229], v[0:3]
	s_setprio 0
	s_and_b64 vcc, exec, s[4:5]
	s_cbranch_vccnz .LBB0_558
	s_barrier

; #define PG8_STAGE(bufoff, gbase, voff) do { _Pragma("unroll") for (int _i = 0; _i < 2; ++_i) \
;         __builtin_amdgcn_global_load_lds((const unsigned*)((const char*)(gbase) + (voff)[_i]), (PG8_LAS unsigned*)(lds + (bufoff) + ldsw + _i * 8192), 16, 0, 0); } while (0)
; #define PG8_LDA(dst, b, h) do { _Pragma("unroll") for (int m = 0; m < 4; ++m) _Pragma("unroll") for (int k = 0; k < 2; ++k) dst[m][k] = *(const PG8_LAS bf16x8*)(lds + PG8_SA(b, h) + aoff + m * 2048 + k * 1024); } while (0)
; #define PG8_LDB(dst, b, h) do { _Pragma("unroll") for (int n = 0; n < 2; ++n) _Pragma("unroll") for (int k = 0; k < 2; ++k) dst[n][k] = *(const PG8_LAS bf16x8*)(lds + PG8_SB(b, h) + boff + n * 2048 + k * 1024); } while (0)
; #define PG8_MMA(ai, bj, At, Bt) do { __builtin_amdgcn_s_setprio(1); _Pragma("unroll") for (int m = 0; m < 4; ++m) _Pragma("unroll") for (int n = 0; n < 2; ++n) _Pragma("unroll") for (int k = 0; k < 2; ++k) \
;         acc[ai][bj][m][n] = __builtin_amdgcn_mfma_f32_16x16x32_bf16(Bt[n][k], At[m][k], acc[ai][bj][m][n], 0, 0, 0); __builtin_amdgcn_s_setprio(0); } while (0)
; #define PG8_WAIT_V(n) asm volatile("s_waitcnt vmcnt(" #n ")" ::: "memory")
; #define PG8_BAR __builtin_amdgcn_s_barrier()
; template <class Epi, class Sched, bool ALIGN_EPI = false, bool SP2 = false>
; __device__ __forceinline__ void gemm_phase(PG8_LAS unsigned char* lds, const Gemm g, const Sched& S, const Epi& E, const int wave_id) {
;     ...
;         for (int t = 0; t < nt; t += 2) {
;             const bool last = (t == nt - 2);
;             const char* a1 = cA + (size_t)(t + 1) * kstep;
;             const char* a2 = last ? nA : cA + (size_t)(t + 2) * kstep; const char* b2 = last ? nB : cB + (size_t)(t + 2) * kstep;
;             const char* a3 = a2 + kstep; const char* b3 = b2 + kstep;
;             if (last && has_next) S.a_ready(nxt);
;             if constexpr (SP2) {
;             PG8_LDB(B0, 0, 0); PG8_LDB(B1, 0, 1); PG8_SCHED; PG8_LDA(At, 0, 0); PG8_STAGE(PG8_SA(1, 1), a1 + hstep, voffA);
;             PG8_WAIT_V(8); PG8_WAIT_L(0); PG8_BAR; PG8_MMA(0, 0, At, B0); PG8_MMA(0, 1, At, B1); PG8_BAR; PG8_SCHED;
;             PG8_LDA(At, 0, 1); PG8_STAGE(PG8_SB(0, 0), b2, voffB); PG8_STAGE(PG8_SB(0, 1), b2 + hstep, voffB); PG8_STAGE(PG8_SA(0, 0), a2, voffA);
;             PG8_WAIT_V(8); PG8_WAIT_L(0); PG8_BAR; PG8_MMA(1, 0, At, B0); PG8_MMA(1, 1, At, B1); PG8_BAR; PG8_SCHED;
.LBB0_581:
	v_add_u32_e32 v152, s77, v138
	v_add_u32_e32 v168, s78, v138
	ds_read_b128 v[140:143], v152
	ds_read_b128 v[144:147], v152 offset:1024
	ds_read_b128 v[148:151], v152 offset:2048
	ds_read_b128 v[152:155], v152 offset:3072
	ds_read_b128 v[156:159], v168
	ds_read_b128 v[160:163], v168 offset:1024
	ds_read_b128 v[164:167], v168 offset:2048
	ds_read_b128 v[168:171], v168 offset:3072
	s_add_u32 s44, s34, s43
	s_addc_u32 s45, s35, s48
	s_add_u32 s93, s34, s6
	s_addc_u32 s94, s35, s7
	s_cmp_eq_u32 s49, 28
	s_cselect_b32 s47, s1, s45
	s_cselect_b32 s46, s0, s44
	s_cselect_b32 s45, s17, s94
	s_cselect_b32 s44, s16, s93
	s_mov_b32 m0, s79
	v_lshl_add_u64 v[204:205], s[34:35], 0, v[134:135]
	ds_read_b128 v[172:175], v139
	ds_read_b128 v[176:179], v139 offset:1024
	ds_read_b128 v[180:183], v139 offset:2048
	ds_read_b128 v[184:187], v139 offset:3072
	ds_read_b128 v[188:191], v139 offset:4096
	ds_read_b128 v[192:195], v139 offset:5120
	ds_read_b128 v[196:199], v139 offset:6144
	ds_read_b128 v[200:203], v139 offset:7168
	global_load_lds_dwordx4 v[204:205], off
	v_lshl_add_u64 v[204:205], s[34:35], 0, v[136:137]
	s_mov_b32 m0, s80
	s_nop 0
	global_load_lds_dwordx4 v[204:205], off
	s_waitcnt vmcnt(8)
	s_waitcnt lgkmcnt(0)
	s_barrier
	s_waitcnt lgkmcnt(0)
	v_mfma_f32_16x16x32_bf16 v[116:119], v[140:143], v[172:175], v[116:119]
	v_mfma_f32_16x16x32_bf16 v[112:115], v[148:151], v[172:175], v[112:115]
	v_mfma_f32_16x16x32_bf16 v[84:87], v[140:143], v[180:183], v[84:87]
	v_mfma_f32_16x16x32_bf16 v[80:83], v[148:151], v[180:183], v[80:83]
	v_mfma_f32_16x16x32_bf16 v[60:63], v[140:143], v[188:191], v[60:63]
	v_mfma_f32_16x16x32_bf16 v[56:59], v[148:151], v[188:191], v[56:59]
	v_mfma_f32_16x16x32_bf16 v[36:39], v[140:143], v[196:199], v[36:39]
	v_mfma_f32_16x16x32_bf16 v[32:35], v[148:151], v[196:199], v[32:35]
	v_mfma_f32_16x16x32_bf16 v[116:119], v[144:147], v[176:179], v[116:119]
	v_mfma_f32_16x16x32_bf16 v[112:115], v[152:155], v[176:179], v[112:115]
	v_mfma_f32_16x16x32_bf16 v[84:87], v[144:147], v[184:187], v[84:87]
	v_mfma_f32_16x16x32_bf16 v[80:83], v[152:155], v[184:187], v[80:83]
	s_setprio 1
	v_mfma_f32_16x16x32_bf16 v[60:63], v[144:147], v[192:195], v[60:63]
	v_mfma_f32_16x16x32_bf16 v[56:59], v[152:155], v[192:195], v[56:59]
	v_mfma_f32_16x16x32_bf16 v[36:39], v[144:147], v[200:203], v[36:39]
	v_mfma_f32_16x16x32_bf16 v[32:35], v[152:155], v[200:203], v[32:35]
	s_setprio 0
	s_setprio 1
	v_mfma_f32_16x16x32_bf16 v[100:103], v[156:159], v[172:175], v[100:103]
	v_mfma_f32_16x16x32_bf16 v[96:99], v[164:167], v[172:175], v[96:99]
	v_mfma_f32_16x16x32_bf16 v[76:79], v[156:159], v[180:183], v[76:79]
	v_mfma_f32_16x16x32_bf16 v[72:75], v[164:167], v[180:183], v[72:75]
	v_mfma_f32_16x16x32_bf16 v[48:51], v[156:159], v[188:191], v[48:51]
	v_mfma_f32_16x16x32_bf16 v[40:43], v[164:167], v[188:191], v[40:43]
	v_mfma_f32_16x16x32_bf16 v[28:31], v[156:159], v[196:199], v[28:31]
	v_mfma_f32_16x16x32_bf16 v[24:27], v[164:167], v[196:199], v[24:27]
	v_mfma_f32_16x16x32_bf16 v[100:103], v[160:163], v[176:179], v[100:103]
	v_mfma_f32_16x16x32_bf16 v[96:99], v[168:171], v[176:179], v[96:99]
	s_barrier
	v_mfma_f32_16x16x32_bf16 v[76:79], v[160:163], v[184:187], v[76:79]
	v_mfma_f32_16x16x32_bf16 v[72:75], v[168:171], v[184:187], v[72:75]
	v_mfma_f32_16x16x32_bf16 v[48:51], v[160:163], v[192:195], v[48:51]
	v_mfma_f32_16x16x32_bf16 v[40:43], v[168:171], v[192:195], v[40:43]
	v_mfma_f32_16x16x32_bf16 v[28:31], v[160:163], v[200:203], v[28:31]
	v_mfma_f32_16x16x32_bf16 v[24:27], v[168:171], v[200:203], v[24:27]
	s_setprio 0
	s_mov_b32 m0, s81
	v_lshl_add_u64 v[204:205], s[44:45], 0, v[224:225]
	s_add_u32 s94, s44, 0x80000
	ds_read_b128 v[172:175], v139 offset:16384
	ds_read_b128 v[176:179], v139 offset:17408
	ds_read_b128 v[180:183], v139 offset:18432
	ds_read_b128 v[184:187], v139 offset:19456
	ds_read_b128 v[188:191], v139 offset:20480
	ds_read_b128 v[192:195], v139 offset:21504
	ds_read_b128 v[196:199], v139 offset:22528
	ds_read_b128 v[200:203], v139 offset:23552
	global_load_lds_dwordx4 v[204:205], off
	v_lshl_add_u64 v[206:207], s[44:45], 0, v[132:133]
	s_mov_b32 m0, s82
	s_addc_u32 s95, s45, 0
	global_load_lds_dwordx4 v[206:207], off
	v_lshl_add_u64 v[208:209], s[94:95], 0, v[224:225]
	s_mov_b32 m0, s83
	v_lshl_add_u64 v[210:211], s[46:47], 0, v[130:131]
	global_load_lds_dwordx4 v[208:209], off
	v_lshl_add_u64 v[208:209], s[94:95], 0, v[132:133]
	s_mov_b32 m0, s84
	s_nop 0
	global_load_lds_dwordx4 v[208:209], off
	v_lshl_add_u64 v[208:209], s[46:47], 0, v[128:129]
	s_mov_b32 m0, s33
	s_nop 0
	global_load_lds_dwordx4 v[208:209], off
	s_mov_b32 m0, s63
	s_nop 0
	global_load_lds_dwordx4 v[210:211], off
	s_waitcnt vmcnt(8)
	s_waitcnt lgkmcnt(0)
	s_barrier
; #define PG8_STAGE(bufoff, gbase, voff) do { _Pragma("unroll") for (int _i = 0; _i < 2; ++_i) \
;         __builtin_amdgcn_global_load_lds((const unsigned*)((const char*)(gbase) + (voff)[_i]), (PG8_LAS unsigned*)(lds + (bufoff) + ldsw + _i * 8192), 16, 0, 0); } while (0)
; #define PG8_LDA(dst, b, h) do { _Pragma("unroll") for (int m = 0; m < 4; ++m) _Pragma("unroll") for (int k = 0; k < 2; ++k) dst[m][k] = *(const PG8_LAS bf16x8*)(lds + PG8_SA(b, h) + aoff + m * 2048 + k * 1024); } while (0)
; #define PG8_LDB(dst, b, h) do { _Pragma("unroll") for (int n = 0; n < 2; ++n) _Pragma("unroll") for (int k = 0; k < 2; ++k) dst[n][k] = *(const PG8_LAS bf16x8*)(lds + PG8_SB(b, h) + boff + n * 2048 + k * 1024); } while (0)
; #define PG8_MMA(ai, bj, At, Bt) do { __builtin_amdgcn_s_setprio(1); _Pragma("unroll") for (int m = 0; m < 4; ++m) _Pragma("unroll") for (int n = 0; n < 2; ++n) _Pragma("unroll") for (int k = 0; k < 2; ++k) \
;         acc[ai][bj][m][n] = __builtin_amdgcn_mfma_f32_16x16x32_bf16(Bt[n][k], At[m][k], acc[ai][bj][m][n], 0, 0, 0); __builtin_amdgcn_s_setprio(0); } while (0)
; #define PG8_WAIT_V(n) asm volatile("s_waitcnt vmcnt(" #n ")" ::: "memory")
; #define PG8_WAIT_L(n) asm volatile("s_waitcnt lgkmcnt(" #n ")" ::: "memory")
; #define PG8_BAR __builtin_amdgcn_s_barrier()
; #define PG8_SCHED __builtin_amdgcn_sched_barrier(0)
; template <class Epi, class Sched, bool ALIGN_EPI = false, bool SP2 = false>
; __device__ __forceinline__ void gemm_phase(PG8_LAS unsigned char* lds, const Gemm g, const Sched& S, const Epi& E, const int wave_id) {
;     ...
;             PG8_WAIT_V(8); PG8_WAIT_L(0); PG8_BAR; PG8_MMA(1, 0, At, B0); PG8_MMA(1, 1, At, B1); PG8_BAR; PG8_SCHED;
;             PG8_LDB(B0, 1, 0); PG8_LDB(B1, 1, 1); PG8_SCHED; PG8_LDA(At, 1, 0); PG8_STAGE(PG8_SA(0, 1), a2 + hstep, voffA);
;             PG8_WAIT_V(8); PG8_WAIT_L(0); PG8_BAR; PG8_MMA(0, 0, At, B0); PG8_MMA(0, 1, At, B1); PG8_BAR; PG8_SCHED;
	s_waitcnt lgkmcnt(0)
	v_mfma_f32_16x16x32_bf16 v[124:127], v[140:143], v[172:175], v[124:127]
	v_mfma_f32_16x16x32_bf16 v[120:123], v[148:151], v[172:175], v[120:123]
	v_mfma_f32_16x16x32_bf16 v[92:95], v[140:143], v[180:183], v[92:95]
	v_mfma_f32_16x16x32_bf16 v[88:91], v[148:151], v[180:183], v[88:91]
	v_mfma_f32_16x16x32_bf16 v[52:55], v[140:143], v[188:191], v[52:55]
	v_mfma_f32_16x16x32_bf16 v[44:47], v[148:151], v[188:191], v[44:47]
	v_mfma_f32_16x16x32_bf16 v[12:15], v[140:143], v[196:199], v[12:15]
	v_mfma_f32_16x16x32_bf16 v[8:11], v[148:151], v[196:199], v[8:11]
	v_mfma_f32_16x16x32_bf16 v[124:127], v[144:147], v[176:179], v[124:127]
	v_mfma_f32_16x16x32_bf16 v[120:123], v[152:155], v[176:179], v[120:123]
	v_mfma_f32_16x16x32_bf16 v[92:95], v[144:147], v[184:187], v[92:95]
	v_mfma_f32_16x16x32_bf16 v[88:91], v[152:155], v[184:187], v[88:91]
	s_setprio 1
	v_mfma_f32_16x16x32_bf16 v[52:55], v[144:147], v[192:195], v[52:55]
	v_mfma_f32_16x16x32_bf16 v[44:47], v[152:155], v[192:195], v[44:47]
	v_mfma_f32_16x16x32_bf16 v[12:15], v[144:147], v[200:203], v[12:15]
	v_mfma_f32_16x16x32_bf16 v[8:11], v[152:155], v[200:203], v[8:11]
	s_setprio 0
	s_setprio 1
	v_mfma_f32_16x16x32_bf16 v[108:111], v[156:159], v[172:175], v[108:111]
	v_mfma_f32_16x16x32_bf16 v[104:107], v[164:167], v[172:175], v[104:107]
	v_mfma_f32_16x16x32_bf16 v[68:71], v[156:159], v[180:183], v[68:71]
	v_mfma_f32_16x16x32_bf16 v[64:67], v[164:167], v[180:183], v[64:67]
	v_mfma_f32_16x16x32_bf16 v[20:23], v[156:159], v[188:191], v[20:23]
	v_mfma_f32_16x16x32_bf16 v[16:19], v[164:167], v[188:191], v[16:19]
	v_mfma_f32_16x16x32_bf16 v[4:7], v[156:159], v[196:199], v[4:7]
	v_mfma_f32_16x16x32_bf16 v[0:3], v[164:167], v[196:199], v[0:3]
	v_mfma_f32_16x16x32_bf16 v[108:111], v[160:163], v[176:179], v[108:111]
	v_mfma_f32_16x16x32_bf16 v[104:107], v[168:171], v[176:179], v[104:107]
	s_barrier
	v_mfma_f32_16x16x32_bf16 v[68:71], v[160:163], v[184:187], v[68:71]
	v_mfma_f32_16x16x32_bf16 v[64:67], v[168:171], v[184:187], v[64:67]
	v_mfma_f32_16x16x32_bf16 v[20:23], v[160:163], v[192:195], v[20:23]
	v_mfma_f32_16x16x32_bf16 v[16:19], v[168:171], v[192:195], v[16:19]
	v_mfma_f32_16x16x32_bf16 v[4:7], v[160:163], v[200:203], v[4:7]
	v_mfma_f32_16x16x32_bf16 v[0:3], v[168:171], v[200:203], v[0:3]
	s_setprio 0
	v_add_u32_e32 v152, s85, v138
	v_add_u32_e32 v168, s86, v138
	ds_read_b128 v[140:143], v152
	ds_read_b128 v[144:147], v152 offset:1024
	ds_read_b128 v[148:151], v152 offset:2048
	ds_read_b128 v[152:155], v152 offset:3072
	ds_read_b128 v[156:159], v168
	ds_read_b128 v[160:163], v168 offset:1024
	ds_read_b128 v[164:167], v168 offset:2048
	ds_read_b128 v[168:171], v168 offset:3072
	s_add_u32 s46, s46, 0x80000
	s_addc_u32 s47, s47, 0
	s_mov_b32 m0, s69
	v_lshl_add_u64 v[212:213], s[46:47], 0, v[128:129]
	ds_read_b128 v[172:175], v139 offset:32768
	ds_read_b128 v[176:179], v139 offset:33792
	ds_read_b128 v[180:183], v139 offset:34816
	ds_read_b128 v[184:187], v139 offset:35840
	ds_read_b128 v[188:191], v139 offset:36864
	ds_read_b128 v[192:195], v139 offset:37888
	ds_read_b128 v[196:199], v139 offset:38912
	ds_read_b128 v[200:203], v139 offset:39936
	global_load_lds_dwordx4 v[212:213], off
	v_lshl_add_u64 v[212:213], s[46:47], 0, v[130:131]
	s_mov_b32 m0, s70
	s_nop 0
	global_load_lds_dwordx4 v[212:213], off
	s_waitcnt vmcnt(8)
	s_waitcnt lgkmcnt(0)
	s_barrier
	s_waitcnt lgkmcnt(0)
	v_mfma_f32_16x16x32_bf16 v[116:119], v[140:143], v[172:175], v[116:119]
	v_mfma_f32_16x16x32_bf16 v[112:115], v[148:151], v[172:175], v[112:115]
	v_mfma_f32_16x16x32_bf16 v[84:87], v[140:143], v[180:183], v[84:87]
	v_mfma_f32_16x16x32_bf16 v[80:83], v[148:151], v[180:183], v[80:83]
	v_mfma_f32_16x16x32_bf16 v[60:63], v[140:143], v[188:191], v[60:63]
	v_mfma_f32_16x16x32_bf16 v[56:59], v[148:151], v[188:191], v[56:59]
	v_mfma_f32_16x16x32_bf16 v[36:39], v[140:143], v[196:199], v[36:39]
	v_mfma_f32_16x16x32_bf16 v[32:35], v[148:151], v[196:199], v[32:35]
	v_mfma_f32_16x16x32_bf16 v[116:119], v[144:147], v[176:179], v[116:119]
	v_mfma_f32_16x16x32_bf16 v[112:115], v[152:155], v[176:179], v[112:115]
	v_mfma_f32_16x16x32_bf16 v[84:87], v[144:147], v[184:187], v[84:87]
	v_mfma_f32_16x16x32_bf16 v[80:83], v[152:155], v[184:187], v[80:83]
	s_setprio 1
	v_mfma_f32_16x16x32_bf16 v[60:63], v[144:147], v[192:195], v[60:63]
	v_mfma_f32_16x16x32_bf16 v[56:59], v[152:155], v[192:195], v[56:59]
	v_mfma_f32_16x16x32_bf16 v[36:39], v[144:147], v[200:203], v[36:39]
	v_mfma_f32_16x16x32_bf16 v[32:35], v[152:155], v[200:203], v[32:35]
	s_setprio 0
	s_setprio 1
	v_mfma_f32_16x16x32_bf16 v[100:103], v[156:159], v[172:175], v[100:103]
	v_mfma_f32_16x16x32_bf16 v[96:99], v[164:167], v[172:175], v[96:99]
	v_mfma_f32_16x16x32_bf16 v[76:79], v[156:159], v[180:183], v[76:79]
	v_mfma_f32_16x16x32_bf16 v[72:75], v[164:167], v[180:183], v[72:75]
	v_mfma_f32_16x16x32_bf16 v[48:51], v[156:159], v[188:191], v[48:51]
	v_mfma_f32_16x16x32_bf16 v[40:43], v[164:167], v[188:191], v[40:43]
	v_mfma_f32_16x16x32_bf16 v[28:31], v[156:159], v[196:199], v[28:31]
	v_mfma_f32_16x16x32_bf16 v[24:27], v[164:167], v[196:199], v[24:27]
	v_mfma_f32_16x16x32_bf16 v[100:103], v[160:163], v[176:179], v[100:103]
	v_mfma_f32_16x16x32_bf16 v[96:99], v[168:171], v[176:179], v[96:99]
	s_barrier
; #define PG8_STAGE(bufoff, gbase, voff) do { _Pragma("unroll") for (int _i = 0; _i < 2; ++_i) \
;         __builtin_amdgcn_global_load_lds((const unsigned*)((const char*)(gbase) + (voff)[_i]), (PG8_LAS unsigned*)(lds + (bufoff) + ldsw + _i * 8192), 16, 0, 0); } while (0)
; #define PG8_LDA(dst, b, h) do { _Pragma("unroll") for (int m = 0; m < 4; ++m) _Pragma("unroll") for (int k = 0; k < 2; ++k) dst[m][k] = *(const PG8_LAS bf16x8*)(lds + PG8_SA(b, h) + aoff + m * 2048 + k * 1024); } while (0)
; #define PG8_MMA(ai, bj, At, Bt) do { __builtin_amdgcn_s_setprio(1); _Pragma("unroll") for (int m = 0; m < 4; ++m) _Pragma("unroll") for (int n = 0; n < 2; ++n) _Pragma("unroll") for (int k = 0; k < 2; ++k) \
;         acc[ai][bj][m][n] = __builtin_amdgcn_mfma_f32_16x16x32_bf16(Bt[n][k], At[m][k], acc[ai][bj][m][n], 0, 0, 0); __builtin_amdgcn_s_setprio(0); } while (0)
; #define PG8_WAIT_V(n) asm volatile("s_waitcnt vmcnt(" #n ")" ::: "memory")
; #define PG8_WAIT_L(n) asm volatile("s_waitcnt lgkmcnt(" #n ")" ::: "memory")
; #define PG8_BAR __builtin_amdgcn_s_barrier()
; #define PG8_SCHED __builtin_amdgcn_sched_barrier(0)
; template <class Epi, class Sched, bool ALIGN_EPI = false, bool SP2 = false>
; __device__ __forceinline__ void gemm_phase(PG8_LAS unsigned char* lds, const Gemm g, const Sched& S, const Epi& E, const int wave_id) {
;     ...
;             PG8_WAIT_V(8); PG8_WAIT_L(0); PG8_BAR; PG8_MMA(0, 0, At, B0); PG8_MMA(0, 1, At, B1); PG8_BAR; PG8_SCHED;
;             PG8_LDA(At, 1, 1); PG8_STAGE(PG8_SB(1, 0), b3, voffB); PG8_STAGE(PG8_SB(1, 1), b3 + hstep, voffB); PG8_STAGE(PG8_SA(1, 0), a3, voffA);
;             PG8_WAIT_V(8); PG8_WAIT_L(0); PG8_BAR; PG8_MMA(1, 0, At, B0); PG8_MMA(1, 1, At, B1); PG8_BAR; PG8_SCHED;
;     ...
;     PG8_WAIT_V(0);
;     if constexpr (!ALIGN_EPI) { if (wr == 0) PG8_BAR; }
	v_mfma_f32_16x16x32_bf16 v[76:79], v[160:163], v[184:187], v[76:79]
	v_mfma_f32_16x16x32_bf16 v[72:75], v[168:171], v[184:187], v[72:75]
	v_mfma_f32_16x16x32_bf16 v[48:51], v[160:163], v[192:195], v[48:51]
	v_mfma_f32_16x16x32_bf16 v[40:43], v[168:171], v[192:195], v[40:43]
	v_mfma_f32_16x16x32_bf16 v[28:31], v[160:163], v[200:203], v[28:31]
	v_mfma_f32_16x16x32_bf16 v[24:27], v[168:171], v[200:203], v[24:27]
	s_setprio 0
	s_mov_b32 m0, s87
	v_lshl_add_u64 v[204:205], v[204:205], 0, s[36:37]
	s_add_u32 s44, s44, 0x80080
	ds_read_b128 v[172:175], v139 offset:49152
	ds_read_b128 v[176:179], v139 offset:50176
	ds_read_b128 v[180:183], v139 offset:51200
	ds_read_b128 v[184:187], v139 offset:52224
	ds_read_b128 v[188:191], v139 offset:53248
	ds_read_b128 v[192:195], v139 offset:54272
	ds_read_b128 v[196:199], v139 offset:55296
	ds_read_b128 v[200:203], v139 offset:56320
	global_load_lds_dwordx4 v[204:205], off
	v_lshl_add_u64 v[204:205], v[206:207], 0, s[36:37]
	s_mov_b32 m0, s88
	s_addc_u32 s45, s45, 0
	global_load_lds_dwordx4 v[204:205], off
	v_lshl_add_u64 v[204:205], s[44:45], 0, v[224:225]
	s_mov_b32 m0, s89
	s_nop 0
	global_load_lds_dwordx4 v[204:205], off
	v_lshl_add_u64 v[204:205], s[44:45], 0, v[132:133]
	s_mov_b32 m0, s90
	s_nop 0
	global_load_lds_dwordx4 v[204:205], off
	v_lshl_add_u64 v[204:205], v[208:209], 0, s[36:37]
	s_mov_b32 m0, s73
	s_nop 0
	global_load_lds_dwordx4 v[204:205], off
	v_lshl_add_u64 v[204:205], v[210:211], 0, s[36:37]
	s_mov_b32 m0, s74
	s_nop 0
	global_load_lds_dwordx4 v[204:205], off
	s_waitcnt vmcnt(8)
	s_waitcnt lgkmcnt(0)
	s_barrier
	s_waitcnt lgkmcnt(0)
	v_mfma_f32_16x16x32_bf16 v[124:127], v[140:143], v[172:175], v[124:127]
	v_mfma_f32_16x16x32_bf16 v[120:123], v[148:151], v[172:175], v[120:123]
	v_mfma_f32_16x16x32_bf16 v[92:95], v[140:143], v[180:183], v[92:95]
	v_mfma_f32_16x16x32_bf16 v[88:91], v[148:151], v[180:183], v[88:91]
	v_mfma_f32_16x16x32_bf16 v[52:55], v[140:143], v[188:191], v[52:55]
	v_mfma_f32_16x16x32_bf16 v[44:47], v[148:151], v[188:191], v[44:47]
	v_mfma_f32_16x16x32_bf16 v[12:15], v[140:143], v[196:199], v[12:15]
	v_mfma_f32_16x16x32_bf16 v[8:11], v[148:151], v[196:199], v[8:11]
	v_mfma_f32_16x16x32_bf16 v[124:127], v[144:147], v[176:179], v[124:127]
	v_mfma_f32_16x16x32_bf16 v[120:123], v[152:155], v[176:179], v[120:123]
	v_mfma_f32_16x16x32_bf16 v[92:95], v[144:147], v[184:187], v[92:95]
	v_mfma_f32_16x16x32_bf16 v[88:91], v[152:155], v[184:187], v[88:91]
	s_setprio 1
	v_mfma_f32_16x16x32_bf16 v[52:55], v[144:147], v[192:195], v[52:55]
	v_mfma_f32_16x16x32_bf16 v[44:47], v[152:155], v[192:195], v[44:47]
	v_mfma_f32_16x16x32_bf16 v[12:15], v[144:147], v[200:203], v[12:15]
	v_mfma_f32_16x16x32_bf16 v[8:11], v[152:155], v[200:203], v[8:11]
	s_setprio 0
	s_setprio 1
	v_mfma_f32_16x16x32_bf16 v[108:111], v[156:159], v[172:175], v[108:111]
	v_mfma_f32_16x16x32_bf16 v[104:107], v[164:167], v[172:175], v[104:107]
	v_mfma_f32_16x16x32_bf16 v[68:71], v[156:159], v[180:183], v[68:71]
	v_mfma_f32_16x16x32_bf16 v[64:67], v[164:167], v[180:183], v[64:67]
	v_mfma_f32_16x16x32_bf16 v[20:23], v[156:159], v[188:191], v[20:23]
	v_mfma_f32_16x16x32_bf16 v[16:19], v[164:167], v[188:191], v[16:19]
	v_mfma_f32_16x16x32_bf16 v[4:7], v[156:159], v[196:199], v[4:7]
	v_mfma_f32_16x16x32_bf16 v[0:3], v[164:167], v[196:199], v[0:3]
	v_mfma_f32_16x16x32_bf16 v[108:111], v[160:163], v[176:179], v[108:111]
	v_mfma_f32_16x16x32_bf16 v[104:107], v[168:171], v[176:179], v[104:107]
	s_barrier
	v_mfma_f32_16x16x32_bf16 v[68:71], v[160:163], v[184:187], v[68:71]
	v_mfma_f32_16x16x32_bf16 v[64:67], v[168:171], v[184:187], v[64:67]
	v_mfma_f32_16x16x32_bf16 v[20:23], v[160:163], v[192:195], v[20:23]
	v_mfma_f32_16x16x32_bf16 v[16:19], v[168:171], v[192:195], v[16:19]
	v_mfma_f32_16x16x32_bf16 v[4:7], v[160:163], v[200:203], v[4:7]
	v_mfma_f32_16x16x32_bf16 v[0:3], v[168:171], v[200:203], v[0:3]
	s_setprio 0
	s_add_i32 s49, s49, 2
	s_add_u32 s43, s43, 0x100
	s_addc_u32 s48, s48, 0
	s_add_u32 s6, s6, 0x100
	s_addc_u32 s7, s7, 0
	v_lshl_add_u64 v[134:135], v[134:135], 0, s[38:39]
	s_cmp_lt_u32 s49, 30
	v_lshl_add_u64 v[136:137], v[136:137], 0, s[38:39]
	s_cbranch_scc1 .LBB0_581
	s_waitcnt vmcnt(0)
	s_and_b64 vcc, exec, s[4:5]
	s_cbranch_vccnz .LBB0_584
	s_barrier
